# nt (streaming) hint on the stores of the FFN-in phases' epilogue regions (SwiGLU outputs, layer-0 background prep outputs)
# speedup vs baseline: 1.0056x; 1.0056x over previous
.LBB0_292:
	v_mul_f32_e32 v164, 0xbfb8aa3b, v124
	v_exp_f32_e32 v170, v164
	v_mul_f32_e32 v164, 0xbfb8aa3b, v125
	v_exp_f32_e32 v171, v164
	v_mul_f32_e32 v172, 0xbfb8aa3b, v126
	v_mul_f32_e32 v173, 0xbfb8aa3b, v127
	v_exp_f32_e32 v172, v172
	v_exp_f32_e32 v173, v173
	v_add_f32_e32 v170, 1.0, v170
	v_add_f32_e32 v171, 1.0, v171
	v_rcp_f32_e32 v170, v170
	v_rcp_f32_e32 v171, v171
	v_add_f32_e32 v172, 1.0, v172
	v_add_f32_e32 v173, 1.0, v173
	v_rcp_f32_e32 v172, v172
	v_rcp_f32_e32 v173, v173
	v_pk_mul_f32 v[124:125], v[124:125], v[170:171]
	s_lshl_b32 s13, s22, 7
	v_pk_mul_f32 v[120:121], v[124:125], v[120:121]
	v_pk_mul_f32 v[124:125], v[126:127], v[172:173]
	v_cvt_pk_bf16_f32 v120, v120, v121
	v_mul_f32_e32 v121, 0xbfb8aa3b, v116
	v_pk_mul_f32 v[122:123], v[124:125], v[122:123]
	v_exp_f32_e32 v124, v121
	v_mul_f32_e32 v121, 0xbfb8aa3b, v117
	v_exp_f32_e32 v125, v121
	v_cvt_pk_bf16_f32 v121, v122, v123
	v_add_f32_e32 v122, 1.0, v124
	v_mul_f32_e32 v124, 0xbfb8aa3b, v118
	v_add_f32_e32 v123, 1.0, v125
	v_mul_f32_e32 v125, 0xbfb8aa3b, v119
	v_exp_f32_e32 v124, v124
	v_exp_f32_e32 v125, v125
	v_rcp_f32_e32 v122, v122
	v_rcp_f32_e32 v123, v123
	v_add_f32_e32 v124, 1.0, v124
	v_add_f32_e32 v125, 1.0, v125
	v_rcp_f32_e32 v124, v124
	v_rcp_f32_e32 v125, v125
	v_pk_mul_f32 v[116:117], v[116:117], v[122:123]
	s_or_b32 s13, s13, s44
	v_pk_mul_f32 v[112:113], v[116:117], v[112:113]
	s_mul_i32 s15, s20, 44
	s_ashr_i32 s13, s13, 6
	v_cvt_pk_bf16_f32 v122, v112, v113
	v_pk_mul_f32 v[112:113], v[118:119], v[124:125]
	s_add_i32 s24, s13, s15
	v_pk_mul_f32 v[112:113], v[112:113], v[114:115]
	v_mul_f32_e32 v114, 0xbfb8aa3b, v108
	v_mul_f32_e32 v115, 0xbfb8aa3b, v109
	s_ashr_i32 s25, s24, 31
	v_exp_f32_e32 v114, v114
	v_exp_f32_e32 v115, v115
	s_lshl_b64 s[24:25], s[24:25], 15
	v_lshl_add_u64 v[164:165], v[138:139], 0, s[24:25]
	v_cvt_pk_bf16_f32 v123, v112, v113
	v_lshl_add_u64 v[112:113], v[164:165], 0, v[140:141]
	global_store_dwordx4 v[112:113], v[120:123], off nt
	v_add_f32_e32 v112, 1.0, v114
	v_add_f32_e32 v113, 1.0, v115
	v_mul_f32_e32 v114, 0xbfb8aa3b, v110
	v_mul_f32_e32 v115, 0xbfb8aa3b, v111
	v_exp_f32_e32 v114, v114
	v_exp_f32_e32 v115, v115
	v_rcp_f32_e32 v112, v112
	v_rcp_f32_e32 v113, v113
	v_add_f32_e32 v114, 1.0, v114
	v_add_f32_e32 v115, 1.0, v115
	v_rcp_f32_e32 v114, v114
	v_rcp_f32_e32 v115, v115
	v_pk_mul_f32 v[108:109], v[108:109], v[112:113]
	s_andn2_b64 vcc, exec, s[0:1]
	v_pk_mul_f32 v[104:105], v[108:109], v[104:105]
	v_pk_mul_f32 v[108:109], v[110:111], v[114:115]
	v_cvt_pk_bf16_f32 v104, v104, v105
	v_mul_f32_e32 v105, 0xbfb8aa3b, v100
	v_pk_mul_f32 v[106:107], v[108:109], v[106:107]
	v_exp_f32_e32 v108, v105
	v_mul_f32_e32 v105, 0xbfb8aa3b, v101
	v_exp_f32_e32 v109, v105
	v_cvt_pk_bf16_f32 v105, v106, v107
	v_add_f32_e32 v106, 1.0, v108
	v_mul_f32_e32 v108, 0xbfb8aa3b, v102
	v_add_f32_e32 v107, 1.0, v109
	v_mul_f32_e32 v109, 0xbfb8aa3b, v103
	v_exp_f32_e32 v108, v108
	v_exp_f32_e32 v109, v109
	v_rcp_f32_e32 v106, v106
	v_rcp_f32_e32 v107, v107
	v_add_f32_e32 v108, 1.0, v108
	v_add_f32_e32 v109, 1.0, v109
	v_rcp_f32_e32 v108, v108
	v_rcp_f32_e32 v109, v109
	v_pk_mul_f32 v[100:101], v[100:101], v[106:107]
	s_mov_b64 s[0:1], -1
	v_pk_mul_f32 v[96:97], v[100:101], v[96:97]
	s_nop 0
	v_cvt_pk_bf16_f32 v106, v96, v97
	v_pk_mul_f32 v[96:97], v[102:103], v[108:109]
	s_nop 0
	v_pk_mul_f32 v[96:97], v[96:97], v[98:99]
	v_mul_f32_e32 v98, 0xbfb8aa3b, v92
	v_mul_f32_e32 v99, 0xbfb8aa3b, v93
	v_exp_f32_e32 v98, v98
	v_exp_f32_e32 v99, v99
	v_cvt_pk_bf16_f32 v107, v96, v97
	v_lshl_add_u64 v[96:97], v[164:165], 0, v[142:143]
	global_store_dwordx4 v[96:97], v[104:107], off nt
	v_add_f32_e32 v96, 1.0, v98
	v_add_f32_e32 v97, 1.0, v99
	v_mul_f32_e32 v98, 0xbfb8aa3b, v94
	v_mul_f32_e32 v99, 0xbfb8aa3b, v95
	v_exp_f32_e32 v98, v98
	v_exp_f32_e32 v99, v99
	v_rcp_f32_e32 v96, v96
	v_rcp_f32_e32 v97, v97
	v_add_f32_e32 v98, 1.0, v98
	v_add_f32_e32 v99, 1.0, v99
	v_rcp_f32_e32 v98, v98
	v_rcp_f32_e32 v99, v99
	v_pk_mul_f32 v[92:93], v[92:93], v[96:97]
	s_nop 0
	v_pk_mul_f32 v[88:89], v[92:93], v[88:89]
	v_pk_mul_f32 v[92:93], v[94:95], v[98:99]
	v_cvt_pk_bf16_f32 v88, v88, v89
	v_mul_f32_e32 v89, 0xbfb8aa3b, v84
	v_pk_mul_f32 v[90:91], v[92:93], v[90:91]
	v_exp_f32_e32 v92, v89
	v_mul_f32_e32 v89, 0xbfb8aa3b, v85
	v_exp_f32_e32 v93, v89
	v_cvt_pk_bf16_f32 v89, v90, v91
	v_add_f32_e32 v90, 1.0, v92
	v_mul_f32_e32 v92, 0xbfb8aa3b, v86
	v_add_f32_e32 v91, 1.0, v93
	v_mul_f32_e32 v93, 0xbfb8aa3b, v87
	v_exp_f32_e32 v92, v92
	v_exp_f32_e32 v93, v93
	v_rcp_f32_e32 v90, v90
	v_rcp_f32_e32 v91, v91
	v_add_f32_e32 v92, 1.0, v92
	v_add_f32_e32 v93, 1.0, v93
	v_rcp_f32_e32 v92, v92
	v_rcp_f32_e32 v93, v93
	v_pk_mul_f32 v[84:85], v[84:85], v[90:91]
	s_nop 0
	v_pk_mul_f32 v[80:81], v[84:85], v[80:81]
	s_nop 0
	v_cvt_pk_bf16_f32 v90, v80, v81
	v_pk_mul_f32 v[80:81], v[86:87], v[92:93]
	s_nop 0
	v_pk_mul_f32 v[80:81], v[80:81], v[82:83]
	v_mul_f32_e32 v82, 0xbfb8aa3b, v76
	v_mul_f32_e32 v83, 0xbfb8aa3b, v77
	v_exp_f32_e32 v82, v82
	v_exp_f32_e32 v83, v83
	v_cvt_pk_bf16_f32 v91, v80, v81
	v_lshl_add_u64 v[80:81], v[164:165], 0, v[144:145]
	global_store_dwordx4 v[80:81], v[88:91], off nt
	v_add_f32_e32 v80, 1.0, v82
	v_add_f32_e32 v81, 1.0, v83
	v_mul_f32_e32 v82, 0xbfb8aa3b, v78
	v_mul_f32_e32 v83, 0xbfb8aa3b, v79
	v_exp_f32_e32 v82, v82
	v_exp_f32_e32 v83, v83
	v_rcp_f32_e32 v80, v80
	v_rcp_f32_e32 v81, v81
	v_add_f32_e32 v82, 1.0, v82
	v_add_f32_e32 v83, 1.0, v83
	v_rcp_f32_e32 v82, v82
	v_rcp_f32_e32 v83, v83
	v_pk_mul_f32 v[76:77], v[76:77], v[80:81]
	s_nop 0
	v_pk_mul_f32 v[72:73], v[76:77], v[72:73]
	v_pk_mul_f32 v[76:77], v[78:79], v[82:83]
	v_cvt_pk_bf16_f32 v72, v72, v73
	v_mul_f32_e32 v73, 0xbfb8aa3b, v68
	v_pk_mul_f32 v[74:75], v[76:77], v[74:75]
	v_exp_f32_e32 v76, v73
	v_mul_f32_e32 v73, 0xbfb8aa3b, v69
	v_exp_f32_e32 v77, v73
	v_cvt_pk_bf16_f32 v73, v74, v75
	v_add_f32_e32 v74, 1.0, v76
	v_mul_f32_e32 v76, 0xbfb8aa3b, v70
	v_add_f32_e32 v75, 1.0, v77
	v_mul_f32_e32 v77, 0xbfb8aa3b, v71
	v_exp_f32_e32 v76, v76
	v_exp_f32_e32 v77, v77
	v_rcp_f32_e32 v74, v74
	v_rcp_f32_e32 v75, v75
	v_add_f32_e32 v76, 1.0, v76
	v_add_f32_e32 v77, 1.0, v77
	v_rcp_f32_e32 v76, v76
	v_rcp_f32_e32 v77, v77
	v_pk_mul_f32 v[68:69], v[68:69], v[74:75]
	s_nop 0
	v_pk_mul_f32 v[64:65], v[68:69], v[64:65]
	s_nop 0
	v_cvt_pk_bf16_f32 v74, v64, v65
	v_pk_mul_f32 v[64:65], v[70:71], v[76:77]
	s_nop 0
	v_pk_mul_f32 v[64:65], v[64:65], v[66:67]
	v_mul_f32_e32 v66, 0xbfb8aa3b, v60
	v_mul_f32_e32 v67, 0xbfb8aa3b, v61
	v_exp_f32_e32 v66, v66
	v_exp_f32_e32 v67, v67
	v_cvt_pk_bf16_f32 v75, v64, v65
	v_lshl_add_u64 v[64:65], v[164:165], 0, v[146:147]
	global_store_dwordx4 v[64:65], v[72:75], off nt
	v_add_f32_e32 v64, 1.0, v66
	v_add_f32_e32 v65, 1.0, v67
	v_mul_f32_e32 v66, 0xbfb8aa3b, v62
	v_mul_f32_e32 v67, 0xbfb8aa3b, v63
	v_exp_f32_e32 v66, v66
	v_exp_f32_e32 v67, v67
	v_rcp_f32_e32 v64, v64
	v_rcp_f32_e32 v65, v65
	v_add_f32_e32 v66, 1.0, v66
	v_add_f32_e32 v67, 1.0, v67
	v_rcp_f32_e32 v66, v66
	v_rcp_f32_e32 v67, v67
	v_pk_mul_f32 v[60:61], v[60:61], v[64:65]
	s_nop 0
	v_pk_mul_f32 v[56:57], v[60:61], v[56:57]
	v_pk_mul_f32 v[60:61], v[62:63], v[66:67]
	v_cvt_pk_bf16_f32 v56, v56, v57
	v_mul_f32_e32 v57, 0xbfb8aa3b, v52
	v_pk_mul_f32 v[58:59], v[60:61], v[58:59]
	v_exp_f32_e32 v60, v57
	v_mul_f32_e32 v57, 0xbfb8aa3b, v53
	v_exp_f32_e32 v61, v57
	v_cvt_pk_bf16_f32 v57, v58, v59
	v_add_f32_e32 v58, 1.0, v60
	v_mul_f32_e32 v60, 0xbfb8aa3b, v54
	v_add_f32_e32 v59, 1.0, v61
	v_mul_f32_e32 v61, 0xbfb8aa3b, v55
	v_exp_f32_e32 v60, v60
	v_exp_f32_e32 v61, v61
	v_rcp_f32_e32 v58, v58
	v_rcp_f32_e32 v59, v59
	v_add_f32_e32 v60, 1.0, v60
	v_add_f32_e32 v61, 1.0, v61
	v_rcp_f32_e32 v60, v60
	v_rcp_f32_e32 v61, v61
	v_pk_mul_f32 v[52:53], v[52:53], v[58:59]
	s_nop 0
	v_pk_mul_f32 v[48:49], v[52:53], v[48:49]
	s_nop 0
	v_cvt_pk_bf16_f32 v58, v48, v49
	v_pk_mul_f32 v[48:49], v[54:55], v[60:61]
	s_nop 0
	v_pk_mul_f32 v[48:49], v[48:49], v[50:51]
	v_mul_f32_e32 v50, 0xbfb8aa3b, v44
	v_mul_f32_e32 v51, 0xbfb8aa3b, v45
	v_exp_f32_e32 v50, v50
	v_exp_f32_e32 v51, v51
	v_cvt_pk_bf16_f32 v59, v48, v49
	v_lshl_add_u64 v[48:49], v[164:165], 0, v[148:149]
	global_store_dwordx4 v[48:49], v[56:59], off nt
	v_add_f32_e32 v48, 1.0, v50
	v_add_f32_e32 v49, 1.0, v51
	v_mul_f32_e32 v50, 0xbfb8aa3b, v46
	v_mul_f32_e32 v51, 0xbfb8aa3b, v47
	v_exp_f32_e32 v50, v50
	v_exp_f32_e32 v51, v51
	v_rcp_f32_e32 v48, v48
	v_rcp_f32_e32 v49, v49
	v_add_f32_e32 v50, 1.0, v50
	v_add_f32_e32 v51, 1.0, v51
	v_rcp_f32_e32 v50, v50
	v_rcp_f32_e32 v51, v51
	v_pk_mul_f32 v[44:45], v[44:45], v[48:49]
	s_nop 0
	v_pk_mul_f32 v[40:41], v[44:45], v[40:41]
	v_pk_mul_f32 v[44:45], v[46:47], v[50:51]
	v_cvt_pk_bf16_f32 v40, v40, v41
	v_mul_f32_e32 v41, 0xbfb8aa3b, v36
	v_pk_mul_f32 v[42:43], v[44:45], v[42:43]
	v_exp_f32_e32 v44, v41
	v_mul_f32_e32 v41, 0xbfb8aa3b, v37
	v_exp_f32_e32 v45, v41
	v_cvt_pk_bf16_f32 v41, v42, v43
	v_add_f32_e32 v42, 1.0, v44
	v_mul_f32_e32 v44, 0xbfb8aa3b, v38
	v_add_f32_e32 v43, 1.0, v45
	v_mul_f32_e32 v45, 0xbfb8aa3b, v39
	v_exp_f32_e32 v44, v44
	v_exp_f32_e32 v45, v45
	v_rcp_f32_e32 v42, v42
	v_rcp_f32_e32 v43, v43
	v_add_f32_e32 v44, 1.0, v44
	v_add_f32_e32 v45, 1.0, v45
	v_rcp_f32_e32 v44, v44
	v_rcp_f32_e32 v45, v45
	v_pk_mul_f32 v[36:37], v[36:37], v[42:43]
	s_nop 0
	v_pk_mul_f32 v[32:33], v[36:37], v[32:33]
	s_nop 0
	v_cvt_pk_bf16_f32 v42, v32, v33
	v_pk_mul_f32 v[32:33], v[38:39], v[44:45]
	s_nop 0
	v_pk_mul_f32 v[32:33], v[32:33], v[34:35]
	v_mul_f32_e32 v34, 0xbfb8aa3b, v28
	v_mul_f32_e32 v35, 0xbfb8aa3b, v29
	v_exp_f32_e32 v34, v34
	v_exp_f32_e32 v35, v35
	v_cvt_pk_bf16_f32 v43, v32, v33
	v_lshl_add_u64 v[32:33], v[164:165], 0, v[150:151]
	global_store_dwordx4 v[32:33], v[40:43], off nt
	v_add_f32_e32 v32, 1.0, v34
	v_add_f32_e32 v33, 1.0, v35
	v_mul_f32_e32 v34, 0xbfb8aa3b, v30
	v_mul_f32_e32 v35, 0xbfb8aa3b, v31
	v_exp_f32_e32 v34, v34
	v_exp_f32_e32 v35, v35
	v_rcp_f32_e32 v32, v32
	v_rcp_f32_e32 v33, v33
	v_add_f32_e32 v34, 1.0, v34
	v_add_f32_e32 v35, 1.0, v35
	v_rcp_f32_e32 v34, v34
	v_rcp_f32_e32 v35, v35
	v_pk_mul_f32 v[28:29], v[28:29], v[32:33]
	s_nop 0
	v_pk_mul_f32 v[24:25], v[28:29], v[24:25]
	v_pk_mul_f32 v[28:29], v[30:31], v[34:35]
	v_cvt_pk_bf16_f32 v24, v24, v25
	v_mul_f32_e32 v25, 0xbfb8aa3b, v20
	v_pk_mul_f32 v[26:27], v[28:29], v[26:27]
	v_exp_f32_e32 v28, v25
	v_mul_f32_e32 v25, 0xbfb8aa3b, v21
	v_exp_f32_e32 v29, v25
	v_cvt_pk_bf16_f32 v25, v26, v27
	v_add_f32_e32 v26, 1.0, v28
	v_mul_f32_e32 v28, 0xbfb8aa3b, v22
	v_add_f32_e32 v27, 1.0, v29
	v_mul_f32_e32 v29, 0xbfb8aa3b, v23
	v_exp_f32_e32 v28, v28
	v_exp_f32_e32 v29, v29
	v_rcp_f32_e32 v26, v26
	v_rcp_f32_e32 v27, v27
	v_add_f32_e32 v28, 1.0, v28
	v_add_f32_e32 v29, 1.0, v29
	v_rcp_f32_e32 v28, v28
	v_rcp_f32_e32 v29, v29
	v_pk_mul_f32 v[20:21], v[20:21], v[26:27]
	s_nop 0
	v_pk_mul_f32 v[16:17], v[20:21], v[16:17]
	s_nop 0
	v_cvt_pk_bf16_f32 v26, v16, v17
	v_pk_mul_f32 v[16:17], v[22:23], v[28:29]
	s_nop 0
	v_pk_mul_f32 v[16:17], v[16:17], v[18:19]
	v_mul_f32_e32 v18, 0xbfb8aa3b, v12
	v_mul_f32_e32 v19, 0xbfb8aa3b, v13
	v_exp_f32_e32 v18, v18
	v_exp_f32_e32 v19, v19
	v_cvt_pk_bf16_f32 v27, v16, v17
	v_lshl_add_u64 v[16:17], v[164:165], 0, v[152:153]
	global_store_dwordx4 v[16:17], v[24:27], off nt
	v_add_f32_e32 v16, 1.0, v18
	v_add_f32_e32 v17, 1.0, v19
	v_mul_f32_e32 v18, 0xbfb8aa3b, v14
	v_mul_f32_e32 v19, 0xbfb8aa3b, v15
	v_exp_f32_e32 v18, v18
	v_exp_f32_e32 v19, v19
	v_rcp_f32_e32 v16, v16
	v_rcp_f32_e32 v17, v17
	v_add_f32_e32 v18, 1.0, v18
	v_add_f32_e32 v19, 1.0, v19
	v_rcp_f32_e32 v18, v18
	v_rcp_f32_e32 v19, v19
	v_pk_mul_f32 v[12:13], v[12:13], v[16:17]
	s_nop 0
	v_pk_mul_f32 v[8:9], v[12:13], v[8:9]
	v_pk_mul_f32 v[12:13], v[14:15], v[18:19]
	v_cvt_pk_bf16_f32 v8, v8, v9
	v_mul_f32_e32 v9, 0xbfb8aa3b, v4
	v_pk_mul_f32 v[10:11], v[12:13], v[10:11]
	v_exp_f32_e32 v12, v9
	v_mul_f32_e32 v9, 0xbfb8aa3b, v5
	v_exp_f32_e32 v13, v9
	v_cvt_pk_bf16_f32 v9, v10, v11
	v_add_f32_e32 v10, 1.0, v12
	v_mul_f32_e32 v12, 0xbfb8aa3b, v6
	v_add_f32_e32 v11, 1.0, v13
	v_mul_f32_e32 v13, 0xbfb8aa3b, v7
	v_exp_f32_e32 v12, v12
	v_exp_f32_e32 v13, v13
	v_rcp_f32_e32 v10, v10
	v_rcp_f32_e32 v11, v11
	v_add_f32_e32 v12, 1.0, v12
	v_add_f32_e32 v13, 1.0, v13
	v_rcp_f32_e32 v12, v12
	v_rcp_f32_e32 v13, v13
	v_pk_mul_f32 v[4:5], v[4:5], v[10:11]
	s_nop 0
	v_pk_mul_f32 v[0:1], v[4:5], v[0:1]
	s_nop 0
	v_cvt_pk_bf16_f32 v10, v0, v1
	v_pk_mul_f32 v[0:1], v[6:7], v[12:13]
	s_nop 0
	v_pk_mul_f32 v[0:1], v[0:1], v[2:3]
	s_nop 0
	v_cvt_pk_bf16_f32 v11, v0, v1
	v_lshl_add_u64 v[0:1], v[164:165], 0, v[154:155]
	global_store_dwordx4 v[0:1], v[8:11], off nt
	s_cbranch_vccnz .LBB0_285
	s_andn2_b64 vcc, exec, s[6:7]
	s_cbranch_vccnz .LBB0_284
	s_barrier
	s_branch .LBB0_284

.LBB0_303:
	s_cmpk_gt_i32 s10, 0x47f
	s_mov_b64 s[4:5], -1
	s_cbranch_scc0 .LBB0_329
	s_add_i32 s55, s10, 0xfffffb80
	s_cmpk_gt_u32 s55, 0xaff
	s_load_dwordx2 s[4:5], s[2:3], 0x28
	s_cselect_b64 s[6:7], -1, 0
	v_cndmask_b32_e64 v0, 0, 1, s[6:7]
	s_nop 0
	v_readfirstlane_b32 s6, v0
	s_or_b32 s6, s6, 2
	s_mul_i32 s7, s6, 0x1600000
	s_waitcnt lgkmcnt(0)
	s_add_u32 s8, s4, s7
	s_addc_u32 s9, s5, 0
	s_mul_i32 s6, s6, 0xb00000
	s_add_u32 s4, s30, s6
	s_addc_u32 s5, s31, 0
	s_add_i32 s6, s10, 0xf080
	s_cmpk_lt_u32 s55, 0xb00
	s_cselect_b32 s6, s55, s6
	s_and_b32 s7, s6, 0xffff
	s_mul_i32 s7, s7, 0xba2f
	s_lshr_b32 s55, s7, 23
	s_mul_i32 s7, s55, 0xb0
	s_sub_i32 s6, s6, s7
	s_lshl_b32 s6, s6, 5
	s_and_b32 s6, s6, 0xffe0
	v_or_b32_e32 v2, s6, v36
	v_lshl_add_u32 v3, s55, 6, v37
	v_mov_b64_e32 v[0:1], s[8:9]
	v_mad_i64_i32 v[0:1], s[8:9], v3, s17, v[0:1]
	v_lshlrev_b32_e32 v20, 2, v2
	v_lshl_add_u64 v[0:1], v[0:1], 0, v[20:21]
	v_add_co_u32_e32 v2, vcc, s18, v0
	s_nop 1
	v_addc_co_u32_e32 v3, vcc, 0, v1, vcc
	v_add_co_u32_e32 v4, vcc, s19, v0
	s_nop 1
	v_addc_co_u32_e32 v5, vcc, 0, v1, vcc
	v_add_co_u32_e32 v6, vcc, s20, v0
	s_nop 1
	v_addc_co_u32_e32 v7, vcc, 0, v1, vcc
	v_add_co_u32_e32 v8, vcc, s21, v0
	s_nop 1
	v_addc_co_u32_e32 v9, vcc, 0, v1, vcc
	v_add_co_u32_e32 v10, vcc, s22, v0
	s_nop 1
	v_addc_co_u32_e32 v11, vcc, 0, v1, vcc
	v_add_co_u32_e32 v12, vcc, s23, v0
	s_nop 1
	v_addc_co_u32_e32 v13, vcc, 0, v1, vcc
	v_add_co_u32_e32 v14, vcc, s24, v0
	s_nop 1
	v_addc_co_u32_e32 v15, vcc, 0, v1, vcc
	global_load_dword v18, v[0:1], off
	global_load_dword v19, v[2:3], off
	global_load_dword v20, v[4:5], off
	global_load_dword v23, v[6:7], off
	global_load_dword v24, v[8:9], off
	global_load_dword v25, v[10:11], off
	global_load_dword v26, v[12:13], off
	global_load_dword v27, v[14:15], off
	v_add_co_u32_e32 v2, vcc, s25, v0
	s_nop 1
	v_addc_co_u32_e32 v3, vcc, 0, v1, vcc
	v_add_co_u32_e32 v4, vcc, s26, v0
	s_nop 1
	v_addc_co_u32_e32 v5, vcc, 0, v1, vcc
	v_add_co_u32_e32 v6, vcc, s27, v0
	s_nop 1
	v_addc_co_u32_e32 v7, vcc, 0, v1, vcc
	v_add_co_u32_e32 v8, vcc, s28, v0
	s_nop 1
	v_addc_co_u32_e32 v9, vcc, 0, v1, vcc
	v_add_co_u32_e32 v10, vcc, s29, v0
	s_nop 1
	v_addc_co_u32_e32 v11, vcc, 0, v1, vcc
	v_add_co_u32_e32 v12, vcc, s33, v0
	s_nop 1
	v_addc_co_u32_e32 v13, vcc, 0, v1, vcc
	v_add_co_u32_e32 v14, vcc, s34, v0
	s_nop 1
	v_addc_co_u32_e32 v15, vcc, 0, v1, vcc
	v_add_co_u32_e32 v16, vcc, s35, v0
	s_nop 1
	v_addc_co_u32_e32 v17, vcc, 0, v1, vcc
	global_load_dword v28, v[2:3], off
	global_load_dword v29, v[4:5], off
	global_load_dword v30, v[6:7], off
	global_load_dword v31, v[8:9], off
	global_load_dword v32, v[10:11], off
	global_load_dword v33, v[12:13], off
	global_load_dword v34, v[14:15], off
	global_load_dword v35, v[16:17], off
	v_add_co_u32_e32 v2, vcc, s36, v0
	s_nop 1
	v_addc_co_u32_e32 v3, vcc, 0, v1, vcc
	v_add_co_u32_e32 v4, vcc, s37, v0
	s_nop 1
	v_addc_co_u32_e32 v5, vcc, 0, v1, vcc
	v_add_co_u32_e32 v6, vcc, s38, v0
	s_nop 1
	v_addc_co_u32_e32 v7, vcc, 0, v1, vcc
	v_add_co_u32_e32 v8, vcc, s39, v0
	s_nop 1
	v_addc_co_u32_e32 v9, vcc, 0, v1, vcc
	v_add_co_u32_e32 v10, vcc, s40, v0
	s_nop 1
	v_addc_co_u32_e32 v11, vcc, 0, v1, vcc
	v_add_co_u32_e32 v12, vcc, s41, v0
	s_nop 1
	v_addc_co_u32_e32 v13, vcc, 0, v1, vcc
	v_add_co_u32_e32 v14, vcc, s42, v0
	s_nop 1
	v_addc_co_u32_e32 v15, vcc, 0, v1, vcc
	v_add_co_u32_e32 v16, vcc, s43, v0
	s_nop 1
	v_addc_co_u32_e32 v17, vcc, 0, v1, vcc
	global_load_dword v48, v[2:3], off
	global_load_dword v49, v[4:5], off
	global_load_dword v50, v[6:7], off
	global_load_dword v51, v[8:9], off
	global_load_dword v52, v[10:11], off
	global_load_dword v53, v[12:13], off
	global_load_dword v54, v[14:15], off
	s_nop 0
	global_load_dword v16, v[16:17], off
	v_add_co_u32_e32 v2, vcc, s44, v0
	s_nop 1
	v_addc_co_u32_e32 v3, vcc, 0, v1, vcc
	v_add_co_u32_e32 v4, vcc, s45, v0
	s_nop 1
	v_addc_co_u32_e32 v5, vcc, 0, v1, vcc
	v_add_co_u32_e32 v6, vcc, s46, v0
	s_nop 1
	v_addc_co_u32_e32 v7, vcc, 0, v1, vcc
	v_add_co_u32_e32 v8, vcc, s47, v0
	s_nop 1
	v_addc_co_u32_e32 v9, vcc, 0, v1, vcc
	v_add_co_u32_e32 v10, vcc, s48, v0
	s_nop 1
	v_addc_co_u32_e32 v11, vcc, 0, v1, vcc
	v_add_co_u32_e32 v12, vcc, s49, v0
	s_nop 1
	v_addc_co_u32_e32 v13, vcc, 0, v1, vcc
	v_add_co_u32_e32 v14, vcc, s50, v0
	s_nop 1
	v_addc_co_u32_e32 v15, vcc, 0, v1, vcc
	v_add_co_u32_e32 v0, vcc, s51, v0
	s_nop 1
	v_addc_co_u32_e32 v1, vcc, 0, v1, vcc
	global_load_dword v2, v[2:3], off
	s_nop 0
	global_load_dword v3, v[4:5], off
	s_nop 0
	global_load_dword v4, v[6:7], off
	global_load_dword v5, v[8:9], off
	s_nop 0
	global_load_dword v6, v[10:11], off
	global_load_dword v7, v[12:13], off
	global_load_dword v8, v[14:15], off
	s_nop 0
	global_load_dword v0, v[0:1], off
	s_waitcnt vmcnt(30)
	ds_write2_b32 v39, v18, v19 offset1:66
	s_waitcnt vmcnt(28)
	ds_write2_b32 v39, v20, v23 offset0:132 offset1:198
	s_waitcnt vmcnt(26)
	ds_write2_b32 v40, v24, v25 offset0:8 offset1:74
	s_waitcnt vmcnt(24)
	ds_write2_b32 v40, v26, v27 offset0:140 offset1:206
	s_waitcnt vmcnt(22)
	ds_write2_b32 v41, v28, v29 offset0:16 offset1:82
	s_waitcnt vmcnt(20)
	ds_write2_b32 v41, v30, v31 offset0:148 offset1:214
	s_waitcnt vmcnt(18)
	ds_write2_b32 v42, v32, v33 offset0:24 offset1:90
	s_waitcnt vmcnt(16)
	ds_write2_b32 v42, v34, v35 offset0:156 offset1:222
	s_waitcnt vmcnt(14)
	ds_write2_b32 v43, v48, v49 offset0:32 offset1:98
	s_waitcnt vmcnt(12)
	ds_write2_b32 v43, v50, v51 offset0:164 offset1:230
	s_waitcnt vmcnt(10)
	ds_write2_b32 v44, v52, v53 offset0:40 offset1:106
	s_waitcnt vmcnt(8)
	ds_write2_b32 v44, v54, v16 offset0:172 offset1:238
	s_waitcnt vmcnt(6)
	ds_write2_b32 v45, v2, v3 offset0:48 offset1:114
	s_waitcnt vmcnt(4)
	ds_write2_b32 v45, v4, v5 offset0:180 offset1:246
	s_waitcnt vmcnt(2)
	ds_write2_b32 v46, v6, v7 offset0:56 offset1:122
	s_waitcnt vmcnt(0)
	ds_write2_b32 v46, v8, v0 offset0:188 offset1:254
	s_waitcnt lgkmcnt(0)
	v_add_u32_e32 v8, s6, v38
	v_cmp_gt_i32_e32 vcc, s52, v8
	s_and_saveexec_b64 s[6:7], vcc
	s_cbranch_execz .LBB0_310
	ds_read2_b32 v[0:1], v47 offset1:33
	ds_read2_b32 v[2:3], v47 offset0:66 offset1:99
	ds_read2_b32 v[4:5], v47 offset0:132 offset1:165
	ds_read2_b32 v[6:7], v47 offset0:198 offset1:231
	v_cmp_lt_i32_e32 vcc, s16, v8
	v_lshlrev_b32_e32 v10, 1, v8
	v_and_b32_e32 v11, 0x7f, v8
	s_and_saveexec_b64 s[8:9], vcc
	s_xor_b64 s[8:9], exec, s[8:9]
	v_add_u32_e32 v9, 0x7fffea00, v10
	v_and_b32_e32 v9, 0x7fffff00, v9
	v_or3_b32 v9, v11, v9, s53
	s_andn2_saveexec_b64 s[8:9], s[8:9]
	v_and_or_b32 v9, v10, s54, v11
	s_or_b64 exec, exec, s[8:9]
	s_waitcnt lgkmcnt(3)
	v_cvt_pk_bf16_f32 v0, v0, v1
	s_waitcnt lgkmcnt(2)
	v_cvt_pk_bf16_f32 v1, v2, v3
	s_waitcnt lgkmcnt(1)
	v_cvt_pk_bf16_f32 v2, v4, v5
	v_ashrrev_i32_e32 v4, 4, v9
	v_and_b32_e32 v4, -16, v4
	v_add_u32_e32 v4, s55, v4
	v_ashrrev_i32_e32 v5, 31, v4
	s_waitcnt lgkmcnt(0)
	v_cvt_pk_bf16_f32 v3, v6, v7
	v_lshlrev_b64 v[4:5], 15, v[4:5]
	v_lshlrev_b32_e32 v6, 7, v9
	v_lshl_add_u64 v[4:5], s[4:5], 0, v[4:5]
	v_and_b32_e32 v20, 0x7f80, v6
	v_lshl_add_u64 v[4:5], v[4:5], 0, v[20:21]
	v_mov_b32_e32 v23, v21
	v_lshl_add_u64 v[4:5], v[4:5], 0, v[22:23]
	global_store_dwordx4 v[4:5], v[0:3], off nt
.LBB0_310:
	s_or_b64 exec, exec, s[6:7]
	v_add_u32_e32 v9, 8, v8
	v_cmp_gt_i32_e32 vcc, s52, v9
	s_and_saveexec_b64 s[6:7], vcc
	s_cbranch_execz .LBB0_316
	ds_read2_b32 v[0:1], v47 offset0:8 offset1:41
	ds_read2_b32 v[2:3], v47 offset0:74 offset1:107
	ds_read2_b32 v[4:5], v47 offset0:140 offset1:173
	ds_read2_b32 v[6:7], v47 offset0:206 offset1:239
	v_cmp_lt_i32_e32 vcc, s16, v9
	v_lshlrev_b32_e32 v10, 1, v9
	v_and_b32_e32 v11, 0x7f, v9
	s_and_saveexec_b64 s[8:9], vcc
	s_xor_b64 s[8:9], exec, s[8:9]
	v_add_u32_e32 v9, 0x7fffea00, v10
	v_and_b32_e32 v9, 0x7fffff00, v9
	v_or3_b32 v9, v11, v9, s53
	s_andn2_saveexec_b64 s[8:9], s[8:9]
	v_and_or_b32 v9, v10, s54, v11
	s_or_b64 exec, exec, s[8:9]
	s_waitcnt lgkmcnt(3)
	v_cvt_pk_bf16_f32 v0, v0, v1
	s_waitcnt lgkmcnt(2)
	v_cvt_pk_bf16_f32 v1, v2, v3
	s_waitcnt lgkmcnt(1)
	v_cvt_pk_bf16_f32 v2, v4, v5
	v_ashrrev_i32_e32 v4, 4, v9
	v_and_b32_e32 v4, -16, v4
	v_add_u32_e32 v4, s55, v4
	v_ashrrev_i32_e32 v5, 31, v4
	s_waitcnt lgkmcnt(0)
	v_cvt_pk_bf16_f32 v3, v6, v7
	v_lshlrev_b64 v[4:5], 15, v[4:5]
	v_lshlrev_b32_e32 v6, 7, v9
	v_lshl_add_u64 v[4:5], s[4:5], 0, v[4:5]
	v_and_b32_e32 v20, 0x7f80, v6
	v_lshl_add_u64 v[4:5], v[4:5], 0, v[20:21]
	v_mov_b32_e32 v23, v21
	v_lshl_add_u64 v[4:5], v[4:5], 0, v[22:23]
	global_store_dwordx4 v[4:5], v[0:3], off nt
.LBB0_316:
	s_or_b64 exec, exec, s[6:7]
	v_add_u32_e32 v9, 16, v8
	v_cmp_gt_i32_e32 vcc, s52, v9
	s_and_saveexec_b64 s[6:7], vcc
	s_cbranch_execz .LBB0_322
	ds_read2_b32 v[0:1], v47 offset0:16 offset1:49
	ds_read2_b32 v[2:3], v47 offset0:82 offset1:115
	ds_read2_b32 v[4:5], v47 offset0:148 offset1:181
	ds_read2_b32 v[6:7], v47 offset0:214 offset1:247
	v_cmp_lt_i32_e32 vcc, s16, v9
	v_lshlrev_b32_e32 v10, 1, v9
	v_and_b32_e32 v11, 0x7f, v9
	s_and_saveexec_b64 s[8:9], vcc
	s_xor_b64 s[8:9], exec, s[8:9]
	v_add_u32_e32 v9, 0x7fffea00, v10
	v_and_b32_e32 v9, 0x7fffff00, v9
	v_or3_b32 v9, v11, v9, s53
	s_andn2_saveexec_b64 s[8:9], s[8:9]
	v_and_or_b32 v9, v10, s54, v11
	s_or_b64 exec, exec, s[8:9]
	s_waitcnt lgkmcnt(3)
	v_cvt_pk_bf16_f32 v0, v0, v1
	s_waitcnt lgkmcnt(2)
	v_cvt_pk_bf16_f32 v1, v2, v3
	s_waitcnt lgkmcnt(1)
	v_cvt_pk_bf16_f32 v2, v4, v5
	v_ashrrev_i32_e32 v4, 4, v9
	v_and_b32_e32 v4, -16, v4
	v_add_u32_e32 v4, s55, v4
	v_ashrrev_i32_e32 v5, 31, v4
	s_waitcnt lgkmcnt(0)
	v_cvt_pk_bf16_f32 v3, v6, v7
	v_lshlrev_b64 v[4:5], 15, v[4:5]
	v_lshlrev_b32_e32 v6, 7, v9
	v_lshl_add_u64 v[4:5], s[4:5], 0, v[4:5]
	v_and_b32_e32 v20, 0x7f80, v6
	v_lshl_add_u64 v[4:5], v[4:5], 0, v[20:21]
	v_mov_b32_e32 v23, v21
	v_lshl_add_u64 v[4:5], v[4:5], 0, v[22:23]
	global_store_dwordx4 v[4:5], v[0:3], off nt
.LBB0_322:
	s_or_b64 exec, exec, s[6:7]
	v_add_u32_e32 v8, 24, v8
	v_cmp_gt_i32_e32 vcc, s52, v8
	s_and_saveexec_b64 s[6:7], vcc
	s_cbranch_execz .LBB0_328
	ds_read2_b32 v[0:1], v47 offset0:24 offset1:57
	ds_read2_b32 v[2:3], v47 offset0:90 offset1:123
	ds_read2_b32 v[4:5], v47 offset0:156 offset1:189
	ds_read2_b32 v[6:7], v47 offset0:222 offset1:255
	v_cmp_lt_i32_e32 vcc, s16, v8
	v_lshlrev_b32_e32 v9, 1, v8
	v_and_b32_e32 v10, 0x7f, v8
	s_and_saveexec_b64 s[8:9], vcc
	s_xor_b64 s[8:9], exec, s[8:9]
	v_add_u32_e32 v8, 0x7fffea00, v9
	v_and_b32_e32 v8, 0x7fffff00, v8
	v_or3_b32 v8, v10, v8, s53
	s_andn2_saveexec_b64 s[8:9], s[8:9]
	v_and_or_b32 v8, v9, s54, v10
	s_or_b64 exec, exec, s[8:9]
	s_waitcnt lgkmcnt(3)
	v_cvt_pk_bf16_f32 v0, v0, v1
	s_waitcnt lgkmcnt(2)
	v_cvt_pk_bf16_f32 v1, v2, v3
	s_waitcnt lgkmcnt(1)
	v_cvt_pk_bf16_f32 v2, v4, v5
	v_ashrrev_i32_e32 v4, 4, v8
	v_and_b32_e32 v4, -16, v4
	v_add_u32_e32 v4, s55, v4
	v_ashrrev_i32_e32 v5, 31, v4
	s_waitcnt lgkmcnt(0)
	v_cvt_pk_bf16_f32 v3, v6, v7
	v_lshlrev_b64 v[4:5], 15, v[4:5]
	v_lshlrev_b32_e32 v6, 7, v8
	v_lshl_add_u64 v[4:5], s[4:5], 0, v[4:5]
	v_and_b32_e32 v20, 0x7f80, v6
	v_lshl_add_u64 v[4:5], v[4:5], 0, v[20:21]
	v_mov_b32_e32 v23, v21
	v_lshl_add_u64 v[4:5], v[4:5], 0, v[22:23]
	global_store_dwordx4 v[4:5], v[0:3], off nt

.LBB0_331:
	v_lshl_add_u64 v[34:35], v[26:27], 0, s[4:5]
	v_add_co_u32_e32 v156, vcc, 0x2400000, v34
	v_mov_b32_e32 v8, s6
	s_nop 0
	v_addc_co_u32_e32 v157, vcc, 0, v35, vcc
	v_add_co_u32_e32 v158, vcc, 0x2409000, v34
	ds_read_b128 v[48:51], v8
	ds_read_b128 v[52:55], v8 offset:16
	ds_read_b128 v[56:59], v8 offset:32
	ds_read_b128 v[60:63], v8 offset:48
	ds_read_b128 v[64:67], v8 offset:4096
	ds_read_b128 v[68:71], v8 offset:4112
	ds_read_b128 v[72:75], v8 offset:8192
	ds_read_b128 v[76:79], v8 offset:8208
	ds_read_b128 v[80:83], v8 offset:12288
	ds_read_b128 v[84:87], v8 offset:12304
	ds_read_b128 v[88:91], v8 offset:16384
	ds_read_b128 v[92:95], v8 offset:16400
	ds_read_b128 v[96:99], v8 offset:20480
	ds_read_b128 v[100:103], v8 offset:20496
	ds_read_b128 v[104:107], v8 offset:24576
	ds_read_b128 v[108:111], v8 offset:24592
	ds_read_b128 v[112:115], v8 offset:28672
	ds_read_b128 v[116:119], v8 offset:28688
	ds_read_b128 v[120:123], v8 offset:4128
	ds_read_b128 v[0:3], v8 offset:4144
	ds_read_b128 v[124:127], v8 offset:8224
	ds_read_b128 v[128:131], v8 offset:8240
	ds_read_b128 v[132:135], v8 offset:12320
	ds_read_b128 v[4:7], v8 offset:12336
	ds_read_b128 v[136:139], v8 offset:16416
	ds_read_b128 v[140:143], v8 offset:16432
	ds_read_b128 v[144:147], v8 offset:20512
	ds_read_b128 v[12:15], v8 offset:20528
	ds_read_b128 v[148:151], v8 offset:24608
	ds_read_b128 v[16:19], v8 offset:24624
	ds_read_b128 v[152:155], v8 offset:28704
	ds_read_b128 v[8:11], v8 offset:28720
	v_addc_co_u32_e32 v159, vcc, 0, v35, vcc
	v_add_co_u32_e32 v160, vcc, 0x2412000, v34
	global_load_dword v156, v[156:157], off
	s_nop 0
	global_load_dword v157, v[158:159], off
	v_addc_co_u32_e32 v161, vcc, 0, v35, vcc
	v_add_co_u32_e32 v158, vcc, 0x241b000, v34
	s_waitcnt lgkmcnt(14)
	v_mov_b32_e32 v164, v112
	v_addc_co_u32_e32 v159, vcc, 0, v35, vcc
	v_add_co_u32_e32 v162, vcc, 0x2424000, v34
	global_load_dword v160, v[160:161], off
	s_nop 0
	global_load_dword v161, v[158:159], off
	v_addc_co_u32_e32 v163, vcc, 0, v35, vcc
	v_add_co_u32_e32 v158, vcc, 0x242d000, v34
	v_mov_b32_e32 v165, v116
	s_nop 0
	v_addc_co_u32_e32 v159, vcc, 0, v35, vcc
	v_mov_b32_e32 v116, v113
	v_mov_b32_e32 v112, v114
	v_mov_b32_e32 v113, v118
	v_mov_b32_e32 v118, v115
	v_mov_b32_e32 v114, v48
	v_mov_b32_e32 v115, v64
	v_mov_b32_e32 v64, v49
	v_mov_b32_e32 v48, v50
	v_mov_b32_e32 v49, v66
	v_mov_b32_e32 v66, v51
	v_mov_b32_e32 v50, v52
	v_mov_b32_e32 v51, v68
	v_mov_b32_e32 v68, v53
	v_mov_b32_e32 v52, v54
	v_mov_b32_e32 v53, v70
	v_mov_b32_e32 v70, v55
	v_mov_b32_e32 v54, v56
	s_waitcnt lgkmcnt(13)
	v_mov_b32_e32 v55, v120
	v_mov_b32_e32 v120, v57
	v_mov_b32_e32 v56, v58
	v_mov_b32_e32 v57, v122
	v_mov_b32_e32 v122, v59
	v_mov_b32_e32 v58, v60
	s_waitcnt lgkmcnt(12)
	v_mov_b32_e32 v59, v0
	v_mov_b32_e32 v0, v61
	v_mov_b32_e32 v60, v62
	v_mov_b32_e32 v61, v2
	v_mov_b32_e32 v2, v63
	v_mov_b32_e32 v62, v72
	v_mov_b32_e32 v63, v80
	v_mov_b32_e32 v80, v73
	v_mov_b32_e32 v72, v74
	v_mov_b32_e32 v73, v82
	v_mov_b32_e32 v82, v75
	v_mov_b32_e32 v74, v76
	v_mov_b32_e32 v75, v84
	v_mov_b32_e32 v84, v77
	v_mov_b32_e32 v76, v78
	v_mov_b32_e32 v77, v86
	v_mov_b32_e32 v86, v79
	s_waitcnt lgkmcnt(11)
	v_mov_b32_e32 v78, v124
	s_waitcnt lgkmcnt(9)
	v_mov_b32_e32 v79, v132
	v_mov_b32_e32 v132, v125
	v_mov_b32_e32 v124, v126
	v_mov_b32_e32 v125, v134
	v_mov_b32_e32 v134, v127
	v_mov_b32_e32 v126, v128
	s_waitcnt lgkmcnt(8)
	v_mov_b32_e32 v127, v4
	v_mov_b32_e32 v4, v129
	v_mov_b32_e32 v128, v130
	v_mov_b32_e32 v129, v6
	v_mov_b32_e32 v6, v131
	v_mov_b32_e32 v130, v88
	v_mov_b32_e32 v131, v96
	v_mov_b32_e32 v96, v89
	v_mov_b32_e32 v88, v90
	v_mov_b32_e32 v89, v98
	v_mov_b32_e32 v98, v91
	v_mov_b32_e32 v90, v92
	v_mov_b32_e32 v91, v100
	v_mov_b32_e32 v100, v93
	v_mov_b32_e32 v92, v94
	v_mov_b32_e32 v93, v102
	v_mov_b32_e32 v102, v95
	s_waitcnt lgkmcnt(7)
	v_mov_b32_e32 v94, v136
	s_waitcnt lgkmcnt(5)
	v_mov_b32_e32 v95, v144
	v_mov_b32_e32 v144, v137
	v_mov_b32_e32 v136, v138
	v_mov_b32_e32 v137, v146
	v_mov_b32_e32 v146, v139
	v_mov_b32_e32 v138, v140
	s_waitcnt lgkmcnt(4)
	v_mov_b32_e32 v139, v12
	v_mov_b32_e32 v12, v141
	v_mov_b32_e32 v140, v142
	v_mov_b32_e32 v141, v14
	v_mov_b32_e32 v14, v143
	s_waitcnt lgkmcnt(1)
	v_mov_b32_e32 v142, v152
	s_waitcnt lgkmcnt(0)
	v_mov_b32_e32 v143, v8
	v_mov_b32_e32 v8, v153
	v_mov_b32_e32 v152, v154
	v_mov_b32_e32 v153, v10
	v_mov_b32_e32 v10, v155
	global_load_dword v154, v[162:163], off
	global_load_dword v155, v[158:159], off
	v_add_co_u32_e32 v162, vcc, 0x2436000, v34
	s_waitcnt vmcnt(4)
	v_mov_b32_e32 v180, v157
	v_addc_co_u32_e32 v163, vcc, 0, v35, vcc
	v_add_co_u32_e32 v158, vcc, 0x243f000, v34
	global_load_dword v162, v[162:163], off
	s_nop 0
	v_addc_co_u32_e32 v159, vcc, 0, v35, vcc
	v_add_co_u32_e32 v168, vcc, 0x2448000, v34
	global_load_dword v163, v[158:159], off
	s_nop 0
	v_addc_co_u32_e32 v169, vcc, 0, v35, vcc
	v_add_co_u32_e32 v158, vcc, 0x2451000, v34
	v_pk_mul_f32 v[64:65], v[180:181], v[64:65] op_sel_hi:[0,1]
	s_nop 0
	v_addc_co_u32_e32 v159, vcc, 0, v35, vcc
	v_add_co_u32_e32 v170, vcc, 0x245a000, v34
	global_load_dword v168, v[168:169], off
	s_nop 0
	global_load_dword v169, v[158:159], off
	v_addc_co_u32_e32 v171, vcc, 0, v35, vcc
	v_add_co_u32_e32 v158, vcc, 0x2463000, v34
	v_pk_mul_f32 v[80:81], v[180:181], v[80:81] op_sel_hi:[0,1]
	s_nop 0
	v_addc_co_u32_e32 v159, vcc, 0, v35, vcc
	v_add_co_u32_e32 v172, vcc, 0x246c000, v34
	global_load_dword v170, v[170:171], off
	s_nop 0
	global_load_dword v171, v[158:159], off
	v_addc_co_u32_e32 v173, vcc, 0, v35, vcc
	v_add_co_u32_e32 v158, vcc, 0x2475000, v34
	v_pk_mul_f32 v[96:97], v[180:181], v[96:97] op_sel_hi:[0,1]
	s_nop 0
	v_addc_co_u32_e32 v159, vcc, 0, v35, vcc
	v_add_co_u32_e32 v174, vcc, 0x247e000, v34
	global_load_dword v172, v[172:173], off
	s_nop 0
	global_load_dword v20, v[158:159], off
	v_addc_co_u32_e32 v175, vcc, 0, v35, vcc
	v_add_co_u32_e32 v34, vcc, 0x2487000, v34
	v_pk_fma_f32 v[64:65], v[156:157], v[114:115], v[64:65] op_sel_hi:[0,1,1]
	s_nop 0
	v_addc_co_u32_e32 v35, vcc, 0, v35, vcc
	global_load_dword v158, v[174:175], off
	s_nop 0
	global_load_dword v34, v[34:35], off
	v_pk_fma_f32 v[62:63], v[156:157], v[62:63], v[80:81] op_sel_hi:[0,1,1]
	v_pk_fma_f32 v[80:81], v[156:157], v[130:131], v[96:97] op_sel_hi:[0,1,1]
	s_waitcnt vmcnt(12)
	v_mov_b32_e32 v114, v161
	v_pk_fma_f32 v[48:49], v[160:161], v[48:49], v[64:65] op_sel_hi:[0,1,1]
	v_pk_fma_f32 v[62:63], v[160:161], v[72:73], v[62:63] op_sel_hi:[0,1,1]
	v_pk_fma_f32 v[64:65], v[160:161], v[88:89], v[80:81] op_sel_hi:[0,1,1]
	v_pk_fma_f32 v[48:49], v[114:115], v[66:67], v[48:49] op_sel_hi:[0,1,1]
	v_pk_fma_f32 v[62:63], v[114:115], v[82:83], v[62:63] op_sel_hi:[0,1,1]
	v_pk_fma_f32 v[64:65], v[114:115], v[98:99], v[64:65] op_sel_hi:[0,1,1]
	v_pk_add_f32 v[32:33], v[32:33], v[48:49]
	v_pk_add_f32 v[30:31], v[30:31], v[62:63]
	v_pk_add_f32 v[28:29], v[28:29], v[64:65]
	v_mov_b32_e32 v178, v157
	v_mov_b32_e32 v174, v156
	v_mul_f32_e32 v176, v157, v105
	v_pk_fma_f32 v[104:105], v[156:157], v[104:105], v[176:177] op_sel_hi:[1,1,0]
	v_mov_b32_e32 v176, v160
	v_pk_fma_f32 v[104:105], v[160:161], v[106:107], v[104:105]
	v_mul_f32_e32 v106, v161, v107
	v_mov_b32_e32 v180, v161
	v_pk_add_f32 v[96:97], v[106:107], v[104:105] op_sel_hi:[0,1]
	s_add_u32 s4, s4, 0x90000
	s_addc_u32 s5, s5, 0
	s_add_i32 s6, s6, 64
	s_cmp_eq_u32 s4, 0x480000
	s_waitcnt vmcnt(11)
	v_mov_b32_e32 v175, v154
	s_waitcnt vmcnt(10)
	v_mov_b32_e32 v66, v155
	v_pk_mul_f32 v[48:49], v[66:67], v[68:69] op_sel_hi:[0,1]
	v_pk_mul_f32 v[62:63], v[66:67], v[84:85] op_sel_hi:[0,1]
	v_pk_mul_f32 v[64:65], v[66:67], v[100:101] op_sel_hi:[0,1]
	v_pk_fma_f32 v[48:49], v[154:155], v[50:51], v[48:49] op_sel_hi:[0,1,1]
	v_pk_fma_f32 v[62:63], v[154:155], v[74:75], v[62:63] op_sel_hi:[0,1,1]
	v_pk_fma_f32 v[64:65], v[154:155], v[90:91], v[64:65] op_sel_hi:[0,1,1]
	v_mul_f32_e32 v72, v155, v109
	v_mov_b32_e32 v179, v155
	v_pk_fma_f32 v[72:73], v[154:155], v[108:109], v[72:73] op_sel_hi:[1,1,0]
	v_pk_mul_f32 v[80:81], v[178:179], v[116:117]
	s_waitcnt vmcnt(9)
	v_mov_b32_e32 v177, v162
	s_waitcnt vmcnt(8)
	v_mov_b32_e32 v50, v163
	v_pk_fma_f32 v[48:49], v[162:163], v[52:53], v[48:49] op_sel_hi:[0,1,1]
	v_pk_fma_f32 v[52:53], v[162:163], v[76:77], v[62:63] op_sel_hi:[0,1,1]
	v_pk_fma_f32 v[62:63], v[162:163], v[92:93], v[64:65] op_sel_hi:[0,1,1]
	v_pk_fma_f32 v[48:49], v[50:51], v[70:71], v[48:49] op_sel_hi:[0,1,1]
	v_pk_fma_f32 v[52:53], v[50:51], v[86:87], v[52:53] op_sel_hi:[0,1,1]
	v_pk_fma_f32 v[50:51], v[50:51], v[102:103], v[62:63] op_sel_hi:[0,1,1]
	v_pk_add_f32 v[32:33], v[32:33], v[48:49]
	v_pk_add_f32 v[30:31], v[30:31], v[52:53]
	v_pk_add_f32 v[28:29], v[28:29], v[50:51]
	s_waitcnt vmcnt(6)
	v_mov_b32_e32 v70, v169
	v_pk_mul_f32 v[48:49], v[70:71], v[120:121] op_sel_hi:[0,1]
	v_pk_mul_f32 v[52:53], v[70:71], v[132:133] op_sel_hi:[0,1]
	v_pk_mul_f32 v[50:51], v[70:71], v[144:145] op_sel_hi:[0,1]
	v_pk_fma_f32 v[66:67], v[162:163], v[110:111], v[72:73]
	v_mul_f32_e32 v68, v163, v111
	v_pk_fma_f32 v[72:73], v[174:175], v[164:165], v[80:81]
	v_mov_b32_e32 v62, v169
	v_pk_fma_f32 v[48:49], v[168:169], v[54:55], v[48:49] op_sel_hi:[0,1,1]
	v_pk_fma_f32 v[52:53], v[168:169], v[78:79], v[52:53] op_sel_hi:[0,1,1]
	v_pk_fma_f32 v[50:51], v[168:169], v[94:95], v[50:51] op_sel_hi:[0,1,1]
	v_mov_b32_e32 v181, v163
	v_pk_add_f32 v[66:67], v[68:69], v[66:67] op_sel_hi:[0,1]
	v_pk_fma_f32 v[68:69], v[176:177], v[112:113], v[72:73]
	v_mov_b32_e32 v64, v168
	v_mul_f32_e32 v72, v169, v149
	s_waitcnt vmcnt(4)
	v_mov_b32_e32 v54, v171
	v_pk_fma_f32 v[48:49], v[170:171], v[56:57], v[48:49] op_sel_hi:[0,1,1]
	v_pk_fma_f32 v[52:53], v[170:171], v[124:125], v[52:53] op_sel_hi:[0,1,1]
	v_pk_fma_f32 v[50:51], v[170:171], v[136:137], v[50:51] op_sel_hi:[0,1,1]
	s_waitcnt vmcnt(2)
	v_pk_mul_f32 v[0:1], v[20:21], v[0:1] op_sel_hi:[0,1]
	v_pk_mul_f32 v[4:5], v[20:21], v[4:5] op_sel_hi:[0,1]
	v_mov_b32_e32 v63, v20
	v_mov_b32_e32 v65, v172
	v_pk_mul_f32 v[12:13], v[20:21], v[12:13] op_sel_hi:[0,1]
	v_pk_fma_f32 v[0:1], v[172:173], v[58:59], v[0:1] op_sel_hi:[0,1,1]
	v_pk_fma_f32 v[4:5], v[172:173], v[126:127], v[4:5] op_sel_hi:[0,1,1]
	v_pk_mul_f32 v[8:9], v[62:63], v[8:9]
	v_pk_fma_f32 v[68:69], v[180:181], v[118:119], v[68:69]
	v_pk_fma_f32 v[72:73], v[168:169], v[148:149], v[72:73] op_sel_hi:[1,1,0]
	v_mov_b32_e32 v70, v170
	v_pk_fma_f32 v[48:49], v[54:55], v[122:123], v[48:49] op_sel_hi:[0,1,1]
	v_pk_fma_f32 v[52:53], v[54:55], v[134:135], v[52:53] op_sel_hi:[0,1,1]
	v_pk_fma_f32 v[50:51], v[54:55], v[146:147], v[50:51] op_sel_hi:[0,1,1]
	v_mul_f32_e32 v54, v20, v17
	v_pk_fma_f32 v[12:13], v[172:173], v[138:139], v[12:13] op_sel_hi:[0,1,1]
	v_mov_b32_e32 v173, v20
	s_waitcnt vmcnt(1)
	v_mov_b32_e32 v71, v158
	v_pk_fma_f32 v[0:1], v[158:159], v[60:61], v[0:1] op_sel_hi:[0,1,1]
	v_pk_fma_f32 v[4:5], v[158:159], v[128:129], v[4:5] op_sel_hi:[0,1,1]
	v_pk_fma_f32 v[8:9], v[64:65], v[142:143], v[8:9]
	v_mov_b32_e32 v97, v68
	v_mov_b32_e32 v67, v69
	v_pk_fma_f32 v[68:69], v[170:171], v[150:151], v[72:73]
	v_mul_f32_e32 v72, v171, v151
	v_mov_b32_e32 v74, v171
	v_pk_add_f32 v[30:31], v[30:31], v[52:53]
	v_pk_fma_f32 v[12:13], v[158:159], v[140:141], v[12:13] op_sel_hi:[0,1,1]
	v_pk_fma_f32 v[16:17], v[172:173], v[16:17], v[54:55] op_sel_hi:[1,1,0]
	s_waitcnt vmcnt(0)
	v_mov_b32_e32 v159, v34
	v_mov_b32_e32 v75, v34
	v_pk_fma_f32 v[0:1], v[34:35], v[2:3], v[0:1] op_sel_hi:[0,1,1]
	v_pk_fma_f32 v[2:3], v[34:35], v[6:7], v[4:5] op_sel_hi:[0,1,1]
	v_pk_fma_f32 v[8:9], v[70:71], v[152:153], v[8:9]
	v_pk_add_f32 v[24:25], v[24:25], v[96:97]
	v_pk_add_f32 v[68:69], v[72:73], v[68:69] op_sel_hi:[0,1]
	v_pk_add_f32 v[32:33], v[32:33], v[48:49]
	v_mul_f32_e32 v20, v34, v19
	v_pk_fma_f32 v[6:7], v[158:159], v[18:19], v[16:17]
	v_pk_add_f32 v[30:31], v[30:31], v[2:3]
	v_pk_fma_f32 v[2:3], v[74:75], v[10:11], v[8:9]
	v_pk_add_f32 v[24:25], v[24:25], v[66:67]
	v_pk_add_f32 v[32:33], v[32:33], v[0:1]
	v_pk_add_f32 v[0:1], v[20:21], v[6:7] op_sel_hi:[0,1]
	v_mov_b32_e32 v69, v2
	v_pk_add_f32 v[28:29], v[28:29], v[50:51]
	v_pk_fma_f32 v[4:5], v[34:35], v[14:15], v[12:13] op_sel_hi:[0,1,1]
	v_mov_b32_e32 v1, v3
	v_pk_add_f32 v[2:3], v[24:25], v[68:69]
	v_pk_add_f32 v[28:29], v[28:29], v[4:5]
	v_pk_add_f32 v[24:25], v[2:3], v[0:1]
	s_cbranch_scc0 .LBB0_331
	s_lshl_b32 s4, s10, 3
	s_andn2_b32 s4, s4, 63
	v_add_u32_e32 v0, s4, v166
	v_ashrrev_i32_e32 v1, 31, v0
	v_lshl_add_u64 v[0:1], v[0:1], 2, s[0:1]
	v_add_co_u32_e32 v2, vcc, 0x240000, v0
	s_nop 1
	v_addc_co_u32_e32 v3, vcc, 0, v1, vcc
	global_store_dword v[2:3], v32, off nt
	v_add_co_u32_e32 v2, vcc, 0x249000, v0
	s_nop 1
	v_addc_co_u32_e32 v3, vcc, 0, v1, vcc
	global_store_dword v[2:3], v33, off nt
	v_add_co_u32_e32 v2, vcc, 0x252000, v0
	s_nop 1
	v_addc_co_u32_e32 v3, vcc, 0, v1, vcc
	global_store_dword v[2:3], v30, off nt
	v_add_co_u32_e32 v2, vcc, 0x25b000, v0
	s_nop 1
	v_addc_co_u32_e32 v3, vcc, 0, v1, vcc
	global_store_dword v[2:3], v31, off nt
	v_add_co_u32_e32 v2, vcc, 0x264000, v0
	s_nop 1
	v_addc_co_u32_e32 v3, vcc, 0, v1, vcc
	global_store_dword v[2:3], v28, off nt
	v_add_co_u32_e32 v2, vcc, 0x26d000, v0
	s_nop 1
	v_addc_co_u32_e32 v3, vcc, 0, v1, vcc
	global_store_dword v[2:3], v29, off nt
	v_add_co_u32_e32 v2, vcc, 0x276000, v0
	s_nop 1
	v_addc_co_u32_e32 v3, vcc, 0, v1, vcc
	v_add_co_u32_e32 v0, vcc, 0x27f000, v0
	global_store_dword v[2:3], v24, off nt
	s_nop 0
	v_addc_co_u32_e32 v1, vcc, 0, v1, vcc
	global_store_dword v[0:1], v25, off nt
	s_branch .LBB0_302

.LBB0_1256:
	v_mul_f32_e32 v164, 0xbfb8aa3b, v124
	v_exp_f32_e32 v170, v164
	v_mul_f32_e32 v164, 0xbfb8aa3b, v125
	v_exp_f32_e32 v171, v164
	v_mul_f32_e32 v172, 0xbfb8aa3b, v126
	v_mul_f32_e32 v173, 0xbfb8aa3b, v127
	v_exp_f32_e32 v172, v172
	v_exp_f32_e32 v173, v173
	v_add_f32_e32 v170, 1.0, v170
	v_add_f32_e32 v171, 1.0, v171
	v_rcp_f32_e32 v170, v170
	v_rcp_f32_e32 v171, v171
	v_add_f32_e32 v172, 1.0, v172
	v_add_f32_e32 v173, 1.0, v173
	v_rcp_f32_e32 v172, v172
	v_rcp_f32_e32 v173, v173
	v_pk_mul_f32 v[124:125], v[124:125], v[170:171]
	s_lshl_b32 s11, s22, 7
	v_pk_mul_f32 v[120:121], v[124:125], v[120:121]
	v_pk_mul_f32 v[124:125], v[126:127], v[172:173]
	v_cvt_pk_bf16_f32 v120, v120, v121
	v_mul_f32_e32 v121, 0xbfb8aa3b, v116
	v_pk_mul_f32 v[122:123], v[124:125], v[122:123]
	v_exp_f32_e32 v124, v121
	v_mul_f32_e32 v121, 0xbfb8aa3b, v117
	v_exp_f32_e32 v125, v121
	v_cvt_pk_bf16_f32 v121, v122, v123
	v_add_f32_e32 v122, 1.0, v124
	v_mul_f32_e32 v124, 0xbfb8aa3b, v118
	v_add_f32_e32 v123, 1.0, v125
	v_mul_f32_e32 v125, 0xbfb8aa3b, v119
	v_exp_f32_e32 v124, v124
	v_exp_f32_e32 v125, v125
	v_rcp_f32_e32 v122, v122
	v_rcp_f32_e32 v123, v123
	v_add_f32_e32 v124, 1.0, v124
	v_add_f32_e32 v125, 1.0, v125
	v_rcp_f32_e32 v124, v124
	v_rcp_f32_e32 v125, v125
	v_pk_mul_f32 v[116:117], v[116:117], v[122:123]
	s_or_b32 s11, s11, s44
	v_pk_mul_f32 v[112:113], v[116:117], v[112:113]
	s_mul_i32 s13, s20, 44
	s_ashr_i32 s11, s11, 6
	v_cvt_pk_bf16_f32 v122, v112, v113
	v_pk_mul_f32 v[112:113], v[118:119], v[124:125]
	s_add_i32 s24, s11, s13
	v_pk_mul_f32 v[112:113], v[112:113], v[114:115]
	v_mul_f32_e32 v114, 0xbfb8aa3b, v108
	v_mul_f32_e32 v115, 0xbfb8aa3b, v109
	s_ashr_i32 s25, s24, 31
	v_exp_f32_e32 v114, v114
	v_exp_f32_e32 v115, v115
	s_lshl_b64 s[24:25], s[24:25], 15
	v_lshl_add_u64 v[164:165], v[138:139], 0, s[24:25]
	v_cvt_pk_bf16_f32 v123, v112, v113
	v_lshl_add_u64 v[112:113], v[164:165], 0, v[140:141]
	global_store_dwordx4 v[112:113], v[120:123], off nt
	v_add_f32_e32 v112, 1.0, v114
	v_add_f32_e32 v113, 1.0, v115
	v_mul_f32_e32 v114, 0xbfb8aa3b, v110
	v_mul_f32_e32 v115, 0xbfb8aa3b, v111
	v_exp_f32_e32 v114, v114
	v_exp_f32_e32 v115, v115
	v_rcp_f32_e32 v112, v112
	v_rcp_f32_e32 v113, v113
	v_add_f32_e32 v114, 1.0, v114
	v_add_f32_e32 v115, 1.0, v115
	v_rcp_f32_e32 v114, v114
	v_rcp_f32_e32 v115, v115
	v_pk_mul_f32 v[108:109], v[108:109], v[112:113]
	s_andn2_b64 vcc, exec, s[0:1]
	v_pk_mul_f32 v[104:105], v[108:109], v[104:105]
	v_pk_mul_f32 v[108:109], v[110:111], v[114:115]
	v_cvt_pk_bf16_f32 v104, v104, v105
	v_mul_f32_e32 v105, 0xbfb8aa3b, v100
	v_pk_mul_f32 v[106:107], v[108:109], v[106:107]
	v_exp_f32_e32 v108, v105
	v_mul_f32_e32 v105, 0xbfb8aa3b, v101
	v_exp_f32_e32 v109, v105
	v_cvt_pk_bf16_f32 v105, v106, v107
	v_add_f32_e32 v106, 1.0, v108
	v_mul_f32_e32 v108, 0xbfb8aa3b, v102
	v_add_f32_e32 v107, 1.0, v109
	v_mul_f32_e32 v109, 0xbfb8aa3b, v103
	v_exp_f32_e32 v108, v108
	v_exp_f32_e32 v109, v109
	v_rcp_f32_e32 v106, v106
	v_rcp_f32_e32 v107, v107
	v_add_f32_e32 v108, 1.0, v108
	v_add_f32_e32 v109, 1.0, v109
	v_rcp_f32_e32 v108, v108
	v_rcp_f32_e32 v109, v109
	v_pk_mul_f32 v[100:101], v[100:101], v[106:107]
	s_mov_b64 s[0:1], -1
	v_pk_mul_f32 v[96:97], v[100:101], v[96:97]
	s_nop 0
	v_cvt_pk_bf16_f32 v106, v96, v97
	v_pk_mul_f32 v[96:97], v[102:103], v[108:109]
	s_nop 0
	v_pk_mul_f32 v[96:97], v[96:97], v[98:99]
	v_mul_f32_e32 v98, 0xbfb8aa3b, v92
	v_mul_f32_e32 v99, 0xbfb8aa3b, v93
	v_exp_f32_e32 v98, v98
	v_exp_f32_e32 v99, v99
	v_cvt_pk_bf16_f32 v107, v96, v97
	v_lshl_add_u64 v[96:97], v[164:165], 0, v[142:143]
	global_store_dwordx4 v[96:97], v[104:107], off nt
	v_add_f32_e32 v96, 1.0, v98
	v_add_f32_e32 v97, 1.0, v99
	v_mul_f32_e32 v98, 0xbfb8aa3b, v94
	v_mul_f32_e32 v99, 0xbfb8aa3b, v95
	v_exp_f32_e32 v98, v98
	v_exp_f32_e32 v99, v99
	v_rcp_f32_e32 v96, v96
	v_rcp_f32_e32 v97, v97
	v_add_f32_e32 v98, 1.0, v98
	v_add_f32_e32 v99, 1.0, v99
	v_rcp_f32_e32 v98, v98
	v_rcp_f32_e32 v99, v99
	v_pk_mul_f32 v[92:93], v[92:93], v[96:97]
	s_nop 0
	v_pk_mul_f32 v[88:89], v[92:93], v[88:89]
	v_pk_mul_f32 v[92:93], v[94:95], v[98:99]
	v_cvt_pk_bf16_f32 v88, v88, v89
	v_mul_f32_e32 v89, 0xbfb8aa3b, v84
	v_pk_mul_f32 v[90:91], v[92:93], v[90:91]
	v_exp_f32_e32 v92, v89
	v_mul_f32_e32 v89, 0xbfb8aa3b, v85
	v_exp_f32_e32 v93, v89
	v_cvt_pk_bf16_f32 v89, v90, v91
	v_add_f32_e32 v90, 1.0, v92
	v_mul_f32_e32 v92, 0xbfb8aa3b, v86
	v_add_f32_e32 v91, 1.0, v93
	v_mul_f32_e32 v93, 0xbfb8aa3b, v87
	v_exp_f32_e32 v92, v92
	v_exp_f32_e32 v93, v93
	v_rcp_f32_e32 v90, v90
	v_rcp_f32_e32 v91, v91
	v_add_f32_e32 v92, 1.0, v92
	v_add_f32_e32 v93, 1.0, v93
	v_rcp_f32_e32 v92, v92
	v_rcp_f32_e32 v93, v93
	v_pk_mul_f32 v[84:85], v[84:85], v[90:91]
	s_nop 0
	v_pk_mul_f32 v[80:81], v[84:85], v[80:81]
	s_nop 0
	v_cvt_pk_bf16_f32 v90, v80, v81
	v_pk_mul_f32 v[80:81], v[86:87], v[92:93]
	s_nop 0
	v_pk_mul_f32 v[80:81], v[80:81], v[82:83]
	v_mul_f32_e32 v82, 0xbfb8aa3b, v76
	v_mul_f32_e32 v83, 0xbfb8aa3b, v77
	v_exp_f32_e32 v82, v82
	v_exp_f32_e32 v83, v83
	v_cvt_pk_bf16_f32 v91, v80, v81
	v_lshl_add_u64 v[80:81], v[164:165], 0, v[144:145]
	global_store_dwordx4 v[80:81], v[88:91], off nt
	v_add_f32_e32 v80, 1.0, v82
	v_add_f32_e32 v81, 1.0, v83
	v_mul_f32_e32 v82, 0xbfb8aa3b, v78
	v_mul_f32_e32 v83, 0xbfb8aa3b, v79
	v_exp_f32_e32 v82, v82
	v_exp_f32_e32 v83, v83
	v_rcp_f32_e32 v80, v80
	v_rcp_f32_e32 v81, v81
	v_add_f32_e32 v82, 1.0, v82
	v_add_f32_e32 v83, 1.0, v83
	v_rcp_f32_e32 v82, v82
	v_rcp_f32_e32 v83, v83
	v_pk_mul_f32 v[76:77], v[76:77], v[80:81]
	s_nop 0
	v_pk_mul_f32 v[72:73], v[76:77], v[72:73]
	v_pk_mul_f32 v[76:77], v[78:79], v[82:83]
	v_cvt_pk_bf16_f32 v72, v72, v73
	v_mul_f32_e32 v73, 0xbfb8aa3b, v68
	v_pk_mul_f32 v[74:75], v[76:77], v[74:75]
	v_exp_f32_e32 v76, v73
	v_mul_f32_e32 v73, 0xbfb8aa3b, v69
	v_exp_f32_e32 v77, v73
	v_cvt_pk_bf16_f32 v73, v74, v75
	v_add_f32_e32 v74, 1.0, v76
	v_mul_f32_e32 v76, 0xbfb8aa3b, v70
	v_add_f32_e32 v75, 1.0, v77
	v_mul_f32_e32 v77, 0xbfb8aa3b, v71
	v_exp_f32_e32 v76, v76
	v_exp_f32_e32 v77, v77
	v_rcp_f32_e32 v74, v74
	v_rcp_f32_e32 v75, v75
	v_add_f32_e32 v76, 1.0, v76
	v_add_f32_e32 v77, 1.0, v77
	v_rcp_f32_e32 v76, v76
	v_rcp_f32_e32 v77, v77
	v_pk_mul_f32 v[68:69], v[68:69], v[74:75]
	s_nop 0
	v_pk_mul_f32 v[64:65], v[68:69], v[64:65]
	s_nop 0
	v_cvt_pk_bf16_f32 v74, v64, v65
	v_pk_mul_f32 v[64:65], v[70:71], v[76:77]
	s_nop 0
	v_pk_mul_f32 v[64:65], v[64:65], v[66:67]
	v_mul_f32_e32 v66, 0xbfb8aa3b, v60
	v_mul_f32_e32 v67, 0xbfb8aa3b, v61
	v_exp_f32_e32 v66, v66
	v_exp_f32_e32 v67, v67
	v_cvt_pk_bf16_f32 v75, v64, v65
	v_lshl_add_u64 v[64:65], v[164:165], 0, v[146:147]
	global_store_dwordx4 v[64:65], v[72:75], off nt
	v_add_f32_e32 v64, 1.0, v66
	v_add_f32_e32 v65, 1.0, v67
	v_mul_f32_e32 v66, 0xbfb8aa3b, v62
	v_mul_f32_e32 v67, 0xbfb8aa3b, v63
	v_exp_f32_e32 v66, v66
	v_exp_f32_e32 v67, v67
	v_rcp_f32_e32 v64, v64
	v_rcp_f32_e32 v65, v65
	v_add_f32_e32 v66, 1.0, v66
	v_add_f32_e32 v67, 1.0, v67
	v_rcp_f32_e32 v66, v66
	v_rcp_f32_e32 v67, v67
	v_pk_mul_f32 v[60:61], v[60:61], v[64:65]
	s_nop 0
	v_pk_mul_f32 v[56:57], v[60:61], v[56:57]
	v_pk_mul_f32 v[60:61], v[62:63], v[66:67]
	v_cvt_pk_bf16_f32 v56, v56, v57
	v_mul_f32_e32 v57, 0xbfb8aa3b, v52
	v_pk_mul_f32 v[58:59], v[60:61], v[58:59]
	v_exp_f32_e32 v60, v57
	v_mul_f32_e32 v57, 0xbfb8aa3b, v53
	v_exp_f32_e32 v61, v57
	v_cvt_pk_bf16_f32 v57, v58, v59
	v_add_f32_e32 v58, 1.0, v60
	v_mul_f32_e32 v60, 0xbfb8aa3b, v54
	v_add_f32_e32 v59, 1.0, v61
	v_mul_f32_e32 v61, 0xbfb8aa3b, v55
	v_exp_f32_e32 v60, v60
	v_exp_f32_e32 v61, v61
	v_rcp_f32_e32 v58, v58
	v_rcp_f32_e32 v59, v59
	v_add_f32_e32 v60, 1.0, v60
	v_add_f32_e32 v61, 1.0, v61
	v_rcp_f32_e32 v60, v60
	v_rcp_f32_e32 v61, v61
	v_pk_mul_f32 v[52:53], v[52:53], v[58:59]
	s_nop 0
	v_pk_mul_f32 v[48:49], v[52:53], v[48:49]
	s_nop 0
	v_cvt_pk_bf16_f32 v58, v48, v49
	v_pk_mul_f32 v[48:49], v[54:55], v[60:61]
	s_nop 0
	v_pk_mul_f32 v[48:49], v[48:49], v[50:51]
	v_mul_f32_e32 v50, 0xbfb8aa3b, v44
	v_mul_f32_e32 v51, 0xbfb8aa3b, v45
	v_exp_f32_e32 v50, v50
	v_exp_f32_e32 v51, v51
	v_cvt_pk_bf16_f32 v59, v48, v49
	v_lshl_add_u64 v[48:49], v[164:165], 0, v[148:149]
	global_store_dwordx4 v[48:49], v[56:59], off nt
	v_add_f32_e32 v48, 1.0, v50
	v_add_f32_e32 v49, 1.0, v51
	v_mul_f32_e32 v50, 0xbfb8aa3b, v46
	v_mul_f32_e32 v51, 0xbfb8aa3b, v47
	v_exp_f32_e32 v50, v50
	v_exp_f32_e32 v51, v51
	v_rcp_f32_e32 v48, v48
	v_rcp_f32_e32 v49, v49
	v_add_f32_e32 v50, 1.0, v50
	v_add_f32_e32 v51, 1.0, v51
	v_rcp_f32_e32 v50, v50
	v_rcp_f32_e32 v51, v51
	v_pk_mul_f32 v[44:45], v[44:45], v[48:49]
	s_nop 0
	v_pk_mul_f32 v[40:41], v[44:45], v[40:41]
	v_pk_mul_f32 v[44:45], v[46:47], v[50:51]
	v_cvt_pk_bf16_f32 v40, v40, v41
	v_mul_f32_e32 v41, 0xbfb8aa3b, v36
	v_pk_mul_f32 v[42:43], v[44:45], v[42:43]
	v_exp_f32_e32 v44, v41
	v_mul_f32_e32 v41, 0xbfb8aa3b, v37
	v_exp_f32_e32 v45, v41
	v_cvt_pk_bf16_f32 v41, v42, v43
	v_add_f32_e32 v42, 1.0, v44
	v_mul_f32_e32 v44, 0xbfb8aa3b, v38
	v_add_f32_e32 v43, 1.0, v45
	v_mul_f32_e32 v45, 0xbfb8aa3b, v39
	v_exp_f32_e32 v44, v44
	v_exp_f32_e32 v45, v45
	v_rcp_f32_e32 v42, v42
	v_rcp_f32_e32 v43, v43
	v_add_f32_e32 v44, 1.0, v44
	v_add_f32_e32 v45, 1.0, v45
	v_rcp_f32_e32 v44, v44
	v_rcp_f32_e32 v45, v45
	v_pk_mul_f32 v[36:37], v[36:37], v[42:43]
	s_nop 0
	v_pk_mul_f32 v[32:33], v[36:37], v[32:33]
	s_nop 0
	v_cvt_pk_bf16_f32 v42, v32, v33
	v_pk_mul_f32 v[32:33], v[38:39], v[44:45]
	s_nop 0
	v_pk_mul_f32 v[32:33], v[32:33], v[34:35]
	v_mul_f32_e32 v34, 0xbfb8aa3b, v28
	v_mul_f32_e32 v35, 0xbfb8aa3b, v29
	v_exp_f32_e32 v34, v34
	v_exp_f32_e32 v35, v35
	v_cvt_pk_bf16_f32 v43, v32, v33
	v_lshl_add_u64 v[32:33], v[164:165], 0, v[150:151]
	global_store_dwordx4 v[32:33], v[40:43], off nt
	v_add_f32_e32 v32, 1.0, v34
	v_add_f32_e32 v33, 1.0, v35
	v_mul_f32_e32 v34, 0xbfb8aa3b, v30
	v_mul_f32_e32 v35, 0xbfb8aa3b, v31
	v_exp_f32_e32 v34, v34
	v_exp_f32_e32 v35, v35
	v_rcp_f32_e32 v32, v32
	v_rcp_f32_e32 v33, v33
	v_add_f32_e32 v34, 1.0, v34
	v_add_f32_e32 v35, 1.0, v35
	v_rcp_f32_e32 v34, v34
	v_rcp_f32_e32 v35, v35
	v_pk_mul_f32 v[28:29], v[28:29], v[32:33]
	s_nop 0
	v_pk_mul_f32 v[24:25], v[28:29], v[24:25]
	v_pk_mul_f32 v[28:29], v[30:31], v[34:35]
	v_cvt_pk_bf16_f32 v24, v24, v25
	v_mul_f32_e32 v25, 0xbfb8aa3b, v20
	v_pk_mul_f32 v[26:27], v[28:29], v[26:27]
	v_exp_f32_e32 v28, v25
	v_mul_f32_e32 v25, 0xbfb8aa3b, v21
	v_exp_f32_e32 v29, v25
	v_cvt_pk_bf16_f32 v25, v26, v27
	v_add_f32_e32 v26, 1.0, v28
	v_mul_f32_e32 v28, 0xbfb8aa3b, v22
	v_add_f32_e32 v27, 1.0, v29
	v_mul_f32_e32 v29, 0xbfb8aa3b, v23
	v_exp_f32_e32 v28, v28
	v_exp_f32_e32 v29, v29
	v_rcp_f32_e32 v26, v26
	v_rcp_f32_e32 v27, v27
	v_add_f32_e32 v28, 1.0, v28
	v_add_f32_e32 v29, 1.0, v29
	v_rcp_f32_e32 v28, v28
	v_rcp_f32_e32 v29, v29
	v_pk_mul_f32 v[20:21], v[20:21], v[26:27]
	s_nop 0
	v_pk_mul_f32 v[16:17], v[20:21], v[16:17]
	s_nop 0
	v_cvt_pk_bf16_f32 v26, v16, v17
	v_pk_mul_f32 v[16:17], v[22:23], v[28:29]
	s_nop 0
	v_pk_mul_f32 v[16:17], v[16:17], v[18:19]
	v_mul_f32_e32 v18, 0xbfb8aa3b, v12
	v_mul_f32_e32 v19, 0xbfb8aa3b, v13
	v_exp_f32_e32 v18, v18
	v_exp_f32_e32 v19, v19
	v_cvt_pk_bf16_f32 v27, v16, v17
	v_lshl_add_u64 v[16:17], v[164:165], 0, v[152:153]
	global_store_dwordx4 v[16:17], v[24:27], off nt
	v_add_f32_e32 v16, 1.0, v18
	v_add_f32_e32 v17, 1.0, v19
	v_mul_f32_e32 v18, 0xbfb8aa3b, v14
	v_mul_f32_e32 v19, 0xbfb8aa3b, v15
	v_exp_f32_e32 v18, v18
	v_exp_f32_e32 v19, v19
	v_rcp_f32_e32 v16, v16
	v_rcp_f32_e32 v17, v17
	v_add_f32_e32 v18, 1.0, v18
	v_add_f32_e32 v19, 1.0, v19
	v_rcp_f32_e32 v18, v18
	v_rcp_f32_e32 v19, v19
	v_pk_mul_f32 v[12:13], v[12:13], v[16:17]
	s_nop 0
	v_pk_mul_f32 v[8:9], v[12:13], v[8:9]
	v_pk_mul_f32 v[12:13], v[14:15], v[18:19]
	v_cvt_pk_bf16_f32 v8, v8, v9
	v_mul_f32_e32 v9, 0xbfb8aa3b, v4
	v_pk_mul_f32 v[10:11], v[12:13], v[10:11]
	v_exp_f32_e32 v12, v9
	v_mul_f32_e32 v9, 0xbfb8aa3b, v5
	v_exp_f32_e32 v13, v9
	v_cvt_pk_bf16_f32 v9, v10, v11
	v_add_f32_e32 v10, 1.0, v12
	v_mul_f32_e32 v12, 0xbfb8aa3b, v6
	v_add_f32_e32 v11, 1.0, v13
	v_mul_f32_e32 v13, 0xbfb8aa3b, v7
	v_exp_f32_e32 v12, v12
	v_exp_f32_e32 v13, v13
	v_rcp_f32_e32 v10, v10
	v_rcp_f32_e32 v11, v11
	v_add_f32_e32 v12, 1.0, v12
	v_add_f32_e32 v13, 1.0, v13
	v_rcp_f32_e32 v12, v12
	v_rcp_f32_e32 v13, v13
	v_pk_mul_f32 v[4:5], v[4:5], v[10:11]
	s_nop 0
	v_pk_mul_f32 v[0:1], v[4:5], v[0:1]
	s_nop 0
	v_cvt_pk_bf16_f32 v10, v0, v1
	v_pk_mul_f32 v[0:1], v[6:7], v[12:13]
	s_nop 0
	v_pk_mul_f32 v[0:1], v[0:1], v[2:3]
	s_nop 0
	v_cvt_pk_bf16_f32 v11, v0, v1
	v_lshl_add_u64 v[0:1], v[164:165], 0, v[154:155]
	global_store_dwordx4 v[0:1], v[8:11], off nt
	s_cbranch_vccnz .LBB0_1249
	s_andn2_b64 vcc, exec, s[4:5]
	s_cbranch_vccnz .LBB0_1248
	s_barrier
	s_branch .LBB0_1248

.LBB0_1276:
	s_mov_b32 s86, s16
	s_mov_b32 s87, s24
	global_load_dwordx4 v[210:213], v3, s[86:87]
	global_load_dwordx4 v[214:217], v3, s[86:87] offset:16
	global_load_dwordx4 v[218:221], v3, s[86:87] offset:32
	global_load_dwordx4 v[222:225], v3, s[86:87] offset:48
	global_load_dwordx4 v[226:229], v3, s[86:87] offset:64
	global_load_dwordx4 v[230:233], v3, s[86:87] offset:80
	global_load_dwordx4 v[234:237], v3, s[86:87] offset:96
	global_load_dwordx4 v[238:241], v3, s[86:87] offset:112
	global_load_dword v168, v[4:5], off offset:-2048
	global_load_dword v169, v[4:5], off offset:-1536
	global_load_dword v170, v[4:5], off offset:-1024
	global_load_dword v171, v[4:5], off offset:-512
	global_load_dword v172, v[4:5], off
	global_load_dword v173, v[4:5], off offset:512
	global_load_dword v174, v[4:5], off offset:1024
	global_load_dword v175, v[4:5], off offset:1536
	v_lshl_add_u64 v[4:5], v[4:5], 0, s[20:21]
	global_load_dword v176, v[4:5], off offset:-2048
	global_load_dword v177, v[4:5], off offset:-1536
	global_load_dword v178, v[4:5], off offset:-1024
	global_load_dword v179, v[4:5], off offset:-512
	global_load_dword v180, v[4:5], off
	global_load_dword v181, v[4:5], off offset:512
	global_load_dword v182, v[4:5], off offset:1024
	global_load_dword v183, v[4:5], off offset:1536
	v_lshl_add_u64 v[4:5], v[4:5], 0, s[20:21]
	global_load_dword v184, v[4:5], off offset:-2048
	global_load_dword v185, v[4:5], off offset:-1536
	global_load_dword v186, v[4:5], off offset:-1024
	global_load_dword v187, v[4:5], off offset:-512
	global_load_dword v188, v[4:5], off
	global_load_dword v189, v[4:5], off offset:512
	global_load_dword v190, v[4:5], off offset:1024
	global_load_dword v191, v[4:5], off offset:1536
	v_lshl_add_u64 v[4:5], v[4:5], 0, s[20:21]
	global_load_dword v192, v[4:5], off offset:-2048
	global_load_dword v193, v[4:5], off offset:-1536
	global_load_dword v194, v[4:5], off offset:-1024
	global_load_dword v195, v[4:5], off offset:-512
	global_load_dword v196, v[4:5], off
	global_load_dword v197, v[4:5], off offset:512
	global_load_dword v198, v[4:5], off offset:1024
	global_load_dword v199, v[4:5], off offset:1536
	v_lshl_add_u64 v[4:5], v[4:5], 0, s[20:21]
	s_waitcnt vmcnt(31)
	v_fmac_f32_e32 v2, v210, v168
	s_waitcnt vmcnt(30)
	v_fmac_f32_e32 v2, v211, v169
	s_waitcnt vmcnt(29)
	v_fmac_f32_e32 v2, v212, v170
	s_waitcnt vmcnt(28)
	v_fmac_f32_e32 v2, v213, v171
	s_waitcnt vmcnt(27)
	v_fmac_f32_e32 v2, v214, v172
	s_waitcnt vmcnt(26)
	v_fmac_f32_e32 v2, v215, v173
	s_waitcnt vmcnt(25)
	v_fmac_f32_e32 v2, v216, v174
	s_waitcnt vmcnt(24)
	v_fmac_f32_e32 v2, v217, v175
	s_waitcnt vmcnt(23)
	v_fmac_f32_e32 v2, v218, v176
	s_waitcnt vmcnt(22)
	v_fmac_f32_e32 v2, v219, v177
	s_waitcnt vmcnt(21)
	v_fmac_f32_e32 v2, v220, v178
	s_waitcnt vmcnt(20)
	v_fmac_f32_e32 v2, v221, v179
	s_waitcnt vmcnt(19)
	v_fmac_f32_e32 v2, v222, v180
	s_waitcnt vmcnt(18)
	v_fmac_f32_e32 v2, v223, v181
	s_waitcnt vmcnt(17)
	v_fmac_f32_e32 v2, v224, v182
	s_waitcnt vmcnt(16)
	v_fmac_f32_e32 v2, v225, v183
	s_waitcnt vmcnt(15)
	v_fmac_f32_e32 v2, v226, v184
	s_waitcnt vmcnt(14)
	v_fmac_f32_e32 v2, v227, v185
	s_waitcnt vmcnt(13)
	v_fmac_f32_e32 v2, v228, v186
	s_waitcnt vmcnt(12)
	v_fmac_f32_e32 v2, v229, v187
	s_waitcnt vmcnt(11)
	v_fmac_f32_e32 v2, v230, v188
	s_waitcnt vmcnt(10)
	v_fmac_f32_e32 v2, v231, v189
	s_waitcnt vmcnt(9)
	v_fmac_f32_e32 v2, v232, v190
	s_waitcnt vmcnt(8)
	v_fmac_f32_e32 v2, v233, v191
	s_waitcnt vmcnt(7)
	v_fmac_f32_e32 v2, v234, v192
	s_waitcnt vmcnt(6)
	v_fmac_f32_e32 v2, v235, v193
	s_waitcnt vmcnt(5)
	v_fmac_f32_e32 v2, v236, v194
	s_waitcnt vmcnt(4)
	v_fmac_f32_e32 v2, v237, v195
	s_waitcnt vmcnt(3)
	v_fmac_f32_e32 v2, v238, v196
	s_waitcnt vmcnt(2)
	v_fmac_f32_e32 v2, v239, v197
	s_waitcnt vmcnt(1)
	v_fmac_f32_e32 v2, v240, v198
	s_waitcnt vmcnt(0)
	v_fmac_f32_e32 v2, v241, v199
	global_load_dwordx4 v[210:213], v3, s[86:87] offset:128
	global_load_dwordx4 v[214:217], v3, s[86:87] offset:144
	global_load_dwordx4 v[218:221], v3, s[86:87] offset:160
	global_load_dwordx4 v[222:225], v3, s[86:87] offset:176
	global_load_dwordx4 v[226:229], v3, s[86:87] offset:192
	global_load_dwordx4 v[230:233], v3, s[86:87] offset:208
	global_load_dwordx4 v[234:237], v3, s[86:87] offset:224
	global_load_dwordx4 v[238:241], v3, s[86:87] offset:240
	global_load_dword v168, v[4:5], off offset:-2048
	global_load_dword v169, v[4:5], off offset:-1536
	global_load_dword v170, v[4:5], off offset:-1024
	global_load_dword v171, v[4:5], off offset:-512
	global_load_dword v172, v[4:5], off
	global_load_dword v173, v[4:5], off offset:512
	global_load_dword v174, v[4:5], off offset:1024
	global_load_dword v175, v[4:5], off offset:1536
	v_lshl_add_u64 v[4:5], v[4:5], 0, s[20:21]
	global_load_dword v176, v[4:5], off offset:-2048
	global_load_dword v177, v[4:5], off offset:-1536
	global_load_dword v178, v[4:5], off offset:-1024
	global_load_dword v179, v[4:5], off offset:-512
	global_load_dword v180, v[4:5], off
	global_load_dword v181, v[4:5], off offset:512
	global_load_dword v182, v[4:5], off offset:1024
	global_load_dword v183, v[4:5], off offset:1536
	v_lshl_add_u64 v[4:5], v[4:5], 0, s[20:21]
	global_load_dword v184, v[4:5], off offset:-2048
	global_load_dword v185, v[4:5], off offset:-1536
	global_load_dword v186, v[4:5], off offset:-1024
	global_load_dword v187, v[4:5], off offset:-512
	global_load_dword v188, v[4:5], off
	global_load_dword v189, v[4:5], off offset:512
	global_load_dword v190, v[4:5], off offset:1024
	global_load_dword v191, v[4:5], off offset:1536
	v_lshl_add_u64 v[4:5], v[4:5], 0, s[20:21]
	global_load_dword v192, v[4:5], off offset:-2048
	global_load_dword v193, v[4:5], off offset:-1536
	global_load_dword v194, v[4:5], off offset:-1024
	global_load_dword v195, v[4:5], off offset:-512
	global_load_dword v196, v[4:5], off
	global_load_dword v197, v[4:5], off offset:512
	global_load_dword v198, v[4:5], off offset:1024
	global_load_dword v199, v[4:5], off offset:1536
	v_lshl_add_u64 v[4:5], v[4:5], 0, s[20:21]
	s_waitcnt vmcnt(31)
	v_fmac_f32_e32 v2, v210, v168
	s_waitcnt vmcnt(30)
	v_fmac_f32_e32 v2, v211, v169
	s_waitcnt vmcnt(29)
	v_fmac_f32_e32 v2, v212, v170
	s_waitcnt vmcnt(28)
	v_fmac_f32_e32 v2, v213, v171
	s_waitcnt vmcnt(27)
	v_fmac_f32_e32 v2, v214, v172
	s_waitcnt vmcnt(26)
	v_fmac_f32_e32 v2, v215, v173
	s_waitcnt vmcnt(25)
	v_fmac_f32_e32 v2, v216, v174
	s_waitcnt vmcnt(24)
	v_fmac_f32_e32 v2, v217, v175
	s_waitcnt vmcnt(23)
	v_fmac_f32_e32 v2, v218, v176
	s_waitcnt vmcnt(22)
	v_fmac_f32_e32 v2, v219, v177
	s_waitcnt vmcnt(21)
	v_fmac_f32_e32 v2, v220, v178
	s_waitcnt vmcnt(20)
	v_fmac_f32_e32 v2, v221, v179
	s_waitcnt vmcnt(19)
	v_fmac_f32_e32 v2, v222, v180
	s_waitcnt vmcnt(18)
	v_fmac_f32_e32 v2, v223, v181
	s_waitcnt vmcnt(17)
	v_fmac_f32_e32 v2, v224, v182
	s_waitcnt vmcnt(16)
	v_fmac_f32_e32 v2, v225, v183
	s_waitcnt vmcnt(15)
	v_fmac_f32_e32 v2, v226, v184
	s_waitcnt vmcnt(14)
	v_fmac_f32_e32 v2, v227, v185
	s_waitcnt vmcnt(13)
	v_fmac_f32_e32 v2, v228, v186
	s_waitcnt vmcnt(12)
	v_fmac_f32_e32 v2, v229, v187
	s_waitcnt vmcnt(11)
	v_fmac_f32_e32 v2, v230, v188
	s_waitcnt vmcnt(10)
	v_fmac_f32_e32 v2, v231, v189
	s_waitcnt vmcnt(9)
	v_fmac_f32_e32 v2, v232, v190
	s_waitcnt vmcnt(8)
	v_fmac_f32_e32 v2, v233, v191
	s_waitcnt vmcnt(7)
	v_fmac_f32_e32 v2, v234, v192
	s_waitcnt vmcnt(6)
	v_fmac_f32_e32 v2, v235, v193
	s_waitcnt vmcnt(5)
	v_fmac_f32_e32 v2, v236, v194
	s_waitcnt vmcnt(4)
	v_fmac_f32_e32 v2, v237, v195
	s_waitcnt vmcnt(3)
	v_fmac_f32_e32 v2, v238, v196
	s_waitcnt vmcnt(2)
	v_fmac_f32_e32 v2, v239, v197
	s_waitcnt vmcnt(1)
	v_fmac_f32_e32 v2, v240, v198
	s_waitcnt vmcnt(0)
	v_fmac_f32_e32 v2, v241, v199
	global_load_dwordx4 v[210:213], v3, s[86:87] offset:256
	global_load_dwordx4 v[214:217], v3, s[86:87] offset:272
	global_load_dwordx4 v[218:221], v3, s[86:87] offset:288
	global_load_dwordx4 v[222:225], v3, s[86:87] offset:304
	global_load_dwordx4 v[226:229], v3, s[86:87] offset:320
	global_load_dwordx4 v[230:233], v3, s[86:87] offset:336
	global_load_dwordx4 v[234:237], v3, s[86:87] offset:352
	global_load_dwordx4 v[238:241], v3, s[86:87] offset:368
	global_load_dword v168, v[4:5], off offset:-2048
	global_load_dword v169, v[4:5], off offset:-1536
	global_load_dword v170, v[4:5], off offset:-1024
	global_load_dword v171, v[4:5], off offset:-512
	global_load_dword v172, v[4:5], off
	global_load_dword v173, v[4:5], off offset:512
	global_load_dword v174, v[4:5], off offset:1024
	global_load_dword v175, v[4:5], off offset:1536
	v_lshl_add_u64 v[4:5], v[4:5], 0, s[20:21]
	global_load_dword v176, v[4:5], off offset:-2048
	global_load_dword v177, v[4:5], off offset:-1536
	global_load_dword v178, v[4:5], off offset:-1024
	global_load_dword v179, v[4:5], off offset:-512
	global_load_dword v180, v[4:5], off
	global_load_dword v181, v[4:5], off offset:512
	global_load_dword v182, v[4:5], off offset:1024
	global_load_dword v183, v[4:5], off offset:1536
	v_lshl_add_u64 v[4:5], v[4:5], 0, s[20:21]
	global_load_dword v184, v[4:5], off offset:-2048
	global_load_dword v185, v[4:5], off offset:-1536
	global_load_dword v186, v[4:5], off offset:-1024
	global_load_dword v187, v[4:5], off offset:-512
	global_load_dword v188, v[4:5], off
	global_load_dword v189, v[4:5], off offset:512
	global_load_dword v190, v[4:5], off offset:1024
	global_load_dword v191, v[4:5], off offset:1536
	v_lshl_add_u64 v[4:5], v[4:5], 0, s[20:21]
	global_load_dword v192, v[4:5], off offset:-2048
	global_load_dword v193, v[4:5], off offset:-1536
	global_load_dword v194, v[4:5], off offset:-1024
	global_load_dword v195, v[4:5], off offset:-512
	global_load_dword v196, v[4:5], off
	global_load_dword v197, v[4:5], off offset:512
	global_load_dword v198, v[4:5], off offset:1024
	global_load_dword v199, v[4:5], off offset:1536
	v_lshl_add_u64 v[4:5], v[4:5], 0, s[20:21]
	s_waitcnt vmcnt(31)
	v_fmac_f32_e32 v2, v210, v168
	s_waitcnt vmcnt(30)
	v_fmac_f32_e32 v2, v211, v169
	s_waitcnt vmcnt(29)
	v_fmac_f32_e32 v2, v212, v170
	s_waitcnt vmcnt(28)
	v_fmac_f32_e32 v2, v213, v171
	s_waitcnt vmcnt(27)
	v_fmac_f32_e32 v2, v214, v172
	s_waitcnt vmcnt(26)
	v_fmac_f32_e32 v2, v215, v173
	s_waitcnt vmcnt(25)
	v_fmac_f32_e32 v2, v216, v174
	s_waitcnt vmcnt(24)
	v_fmac_f32_e32 v2, v217, v175
	s_waitcnt vmcnt(23)
	v_fmac_f32_e32 v2, v218, v176
	s_waitcnt vmcnt(22)
	v_fmac_f32_e32 v2, v219, v177
	s_waitcnt vmcnt(21)
	v_fmac_f32_e32 v2, v220, v178
	s_waitcnt vmcnt(20)
	v_fmac_f32_e32 v2, v221, v179
	s_waitcnt vmcnt(19)
	v_fmac_f32_e32 v2, v222, v180
	s_waitcnt vmcnt(18)
	v_fmac_f32_e32 v2, v223, v181
	s_waitcnt vmcnt(17)
	v_fmac_f32_e32 v2, v224, v182
	s_waitcnt vmcnt(16)
	v_fmac_f32_e32 v2, v225, v183
	s_waitcnt vmcnt(15)
	v_fmac_f32_e32 v2, v226, v184
	s_waitcnt vmcnt(14)
	v_fmac_f32_e32 v2, v227, v185
	s_waitcnt vmcnt(13)
	v_fmac_f32_e32 v2, v228, v186
	s_waitcnt vmcnt(12)
	v_fmac_f32_e32 v2, v229, v187
	s_waitcnt vmcnt(11)
	v_fmac_f32_e32 v2, v230, v188
	s_waitcnt vmcnt(10)
	v_fmac_f32_e32 v2, v231, v189
	s_waitcnt vmcnt(9)
	v_fmac_f32_e32 v2, v232, v190
	s_waitcnt vmcnt(8)
	v_fmac_f32_e32 v2, v233, v191
	s_waitcnt vmcnt(7)
	v_fmac_f32_e32 v2, v234, v192
	s_waitcnt vmcnt(6)
	v_fmac_f32_e32 v2, v235, v193
	s_waitcnt vmcnt(5)
	v_fmac_f32_e32 v2, v236, v194
	s_waitcnt vmcnt(4)
	v_fmac_f32_e32 v2, v237, v195
	s_waitcnt vmcnt(3)
	v_fmac_f32_e32 v2, v238, v196
	s_waitcnt vmcnt(2)
	v_fmac_f32_e32 v2, v239, v197
	s_waitcnt vmcnt(1)
	v_fmac_f32_e32 v2, v240, v198
	s_waitcnt vmcnt(0)
	v_fmac_f32_e32 v2, v241, v199
	global_load_dwordx4 v[210:213], v3, s[86:87] offset:384
	global_load_dwordx4 v[214:217], v3, s[86:87] offset:400
	global_load_dwordx4 v[218:221], v3, s[86:87] offset:416
	global_load_dwordx4 v[222:225], v3, s[86:87] offset:432
	global_load_dwordx4 v[226:229], v3, s[86:87] offset:448
	global_load_dwordx4 v[230:233], v3, s[86:87] offset:464
	global_load_dwordx4 v[234:237], v3, s[86:87] offset:480
	global_load_dwordx4 v[238:241], v3, s[86:87] offset:496
	global_load_dword v168, v[4:5], off offset:-2048
	global_load_dword v169, v[4:5], off offset:-1536
	global_load_dword v170, v[4:5], off offset:-1024
	global_load_dword v171, v[4:5], off offset:-512
	global_load_dword v172, v[4:5], off
	global_load_dword v173, v[4:5], off offset:512
	global_load_dword v174, v[4:5], off offset:1024
	global_load_dword v175, v[4:5], off offset:1536
	v_lshl_add_u64 v[4:5], v[4:5], 0, s[20:21]
	global_load_dword v176, v[4:5], off offset:-2048
	global_load_dword v177, v[4:5], off offset:-1536
	global_load_dword v178, v[4:5], off offset:-1024
	global_load_dword v179, v[4:5], off offset:-512
	global_load_dword v180, v[4:5], off
	global_load_dword v181, v[4:5], off offset:512
	global_load_dword v182, v[4:5], off offset:1024
	global_load_dword v183, v[4:5], off offset:1536
	v_lshl_add_u64 v[4:5], v[4:5], 0, s[20:21]
	global_load_dword v184, v[4:5], off offset:-2048
	global_load_dword v185, v[4:5], off offset:-1536
	global_load_dword v186, v[4:5], off offset:-1024
	global_load_dword v187, v[4:5], off offset:-512
	global_load_dword v188, v[4:5], off
	global_load_dword v189, v[4:5], off offset:512
	global_load_dword v190, v[4:5], off offset:1024
	global_load_dword v191, v[4:5], off offset:1536
	v_lshl_add_u64 v[4:5], v[4:5], 0, s[20:21]
	global_load_dword v192, v[4:5], off offset:-2048
	global_load_dword v193, v[4:5], off offset:-1536
	global_load_dword v194, v[4:5], off offset:-1024
	global_load_dword v195, v[4:5], off offset:-512
	global_load_dword v196, v[4:5], off
	global_load_dword v197, v[4:5], off offset:512
	global_load_dword v198, v[4:5], off offset:1024
	global_load_dword v199, v[4:5], off offset:1536
	v_lshl_add_u64 v[4:5], v[4:5], 0, s[20:21]
	s_waitcnt vmcnt(31)
	v_fmac_f32_e32 v2, v210, v168
	s_waitcnt vmcnt(30)
	v_fmac_f32_e32 v2, v211, v169
	s_waitcnt vmcnt(29)
	v_fmac_f32_e32 v2, v212, v170
	s_waitcnt vmcnt(28)
	v_fmac_f32_e32 v2, v213, v171
	s_waitcnt vmcnt(27)
	v_fmac_f32_e32 v2, v214, v172
	s_waitcnt vmcnt(26)
	v_fmac_f32_e32 v2, v215, v173
	s_waitcnt vmcnt(25)
	v_fmac_f32_e32 v2, v216, v174
	s_waitcnt vmcnt(24)
	v_fmac_f32_e32 v2, v217, v175
	s_waitcnt vmcnt(23)
	v_fmac_f32_e32 v2, v218, v176
	s_waitcnt vmcnt(22)
	v_fmac_f32_e32 v2, v219, v177
	s_waitcnt vmcnt(21)
	v_fmac_f32_e32 v2, v220, v178
	s_waitcnt vmcnt(20)
	v_fmac_f32_e32 v2, v221, v179
	s_waitcnt vmcnt(19)
	v_fmac_f32_e32 v2, v222, v180
	s_waitcnt vmcnt(18)
	v_fmac_f32_e32 v2, v223, v181
	s_waitcnt vmcnt(17)
	v_fmac_f32_e32 v2, v224, v182
	s_waitcnt vmcnt(16)
	v_fmac_f32_e32 v2, v225, v183
	s_waitcnt vmcnt(15)
	v_fmac_f32_e32 v2, v226, v184
	s_waitcnt vmcnt(14)
	v_fmac_f32_e32 v2, v227, v185
	s_waitcnt vmcnt(13)
	v_fmac_f32_e32 v2, v228, v186
	s_waitcnt vmcnt(12)
	v_fmac_f32_e32 v2, v229, v187
	s_waitcnt vmcnt(11)
	v_fmac_f32_e32 v2, v230, v188
	s_waitcnt vmcnt(10)
	v_fmac_f32_e32 v2, v231, v189
	s_waitcnt vmcnt(9)
	v_fmac_f32_e32 v2, v232, v190
	s_waitcnt vmcnt(8)
	v_fmac_f32_e32 v2, v233, v191
	s_waitcnt vmcnt(7)
	v_fmac_f32_e32 v2, v234, v192
	s_waitcnt vmcnt(6)
	v_fmac_f32_e32 v2, v235, v193
	s_waitcnt vmcnt(5)
	v_fmac_f32_e32 v2, v236, v194
	s_waitcnt vmcnt(4)
	v_fmac_f32_e32 v2, v237, v195
	s_waitcnt vmcnt(3)
	v_fmac_f32_e32 v2, v238, v196
	s_waitcnt vmcnt(2)
	v_fmac_f32_e32 v2, v239, v197
	s_waitcnt vmcnt(1)
	v_fmac_f32_e32 v2, v240, v198
	s_waitcnt vmcnt(0)
	v_fmac_f32_e32 v2, v241, v199
	s_mov_b64 s[22:23], 0x200
	s_add_i32 s16, s26, 0xffffccf0
	s_lshl_b32 s22, s16, 6
	s_lshl_b32 s23, s26, 7
	s_and_b32 s22, s22, 0xfffff800
	s_lshl_b32 s16, s16, 2
	s_and_b32 s23, s23, 0x780
	s_and_b32 s16, s16, 64
	s_or_b32 s22, s22, s23
	s_or_b32 s16, s22, s16
	s_addk_i32 s16, 0x1000
	v_add_u32_e32 v4, s16, v166
	v_ashrrev_i32_e32 v5, 31, v4
	v_lshl_add_u64 v[4:5], v[4:5], 2, s[4:5]
	s_mov_b64 s[22:23], 0
	global_store_dword v[4:5], v2, off nt
.LBB0_1278:
	s_and_b64 vcc, exec, s[22:23]
	s_cbranch_vccz .LBB0_1288
	s_add_i32 s85, s26, 0xffffcdf0
	s_lshr_b32 s16, s85, 7
	s_add_i32 s16, s16, 2
	s_lshl_b64 s[22:23], s[16:17], 20
	s_waitcnt lgkmcnt(0)
	s_add_u32 s24, s0, s22
	s_addc_u32 s25, s1, s23
	s_lshl_b64 s[0:1], s[16:17], 19
	s_add_u32 s0, s33, s0
	s_addc_u32 s1, s34, s1
	s_lshl_b32 s16, s85, 4
	s_and_b32 s22, s16, 0x7c0
	s_lshl_b32 s16, s26, 5
	v_add_u32_e32 v4, s22, v21
	s_and_b32 s16, s16, 0x60
	v_ashrrev_i32_e32 v5, 31, v4
	v_or_b32_e32 v2, s16, v1
	v_lshlrev_b64 v[4:5], 9, v[4:5]
	v_lshl_add_u64 v[4:5], s[24:25], 0, v[4:5]
	v_lshlrev_b32_e32 v2, 2, v2
	v_lshl_add_u64 v[4:5], v[4:5], 0, v[2:3]
	s_movk_i32 s23, 0x1000
	v_add_co_u32_e32 v6, vcc, s23, v4
	s_movk_i32 s23, 0x3000
	s_nop 0
	v_addc_co_u32_e32 v7, vcc, 0, v5, vcc
	v_add_co_u32_e32 v8, vcc, s44, v4
	global_load_dword v2, v[4:5], off
	global_load_dword v10, v[4:5], off offset:1024
	global_load_dword v11, v[4:5], off offset:2048
	global_load_dword v12, v[4:5], off offset:3072
	v_addc_co_u32_e32 v9, vcc, 0, v5, vcc
	global_load_dword v13, v[8:9], off offset:-4096
	global_load_dword v14, v[6:7], off offset:1024
	global_load_dword v15, v[6:7], off offset:2048
	global_load_dword v16, v[6:7], off offset:3072
	global_load_dword v17, v[8:9], off
	global_load_dword v18, v[8:9], off offset:1024
	global_load_dword v19, v[8:9], off offset:2048
	global_load_dword v20, v[8:9], off offset:3072
	v_add_co_u32_e32 v6, vcc, s23, v4
	s_movk_i32 s23, 0x5000
	s_nop 0
	v_addc_co_u32_e32 v7, vcc, 0, v5, vcc
	v_add_co_u32_e32 v8, vcc, s45, v4
	s_nop 1
	v_addc_co_u32_e32 v9, vcc, 0, v5, vcc
	global_load_dword v22, v[8:9], off offset:-4096
	global_load_dword v23, v[6:7], off offset:1024
	global_load_dword v24, v[6:7], off offset:2048
	global_load_dword v25, v[6:7], off offset:3072
	global_load_dword v26, v[8:9], off
	global_load_dword v27, v[8:9], off offset:1024
	global_load_dword v28, v[8:9], off offset:2048
	global_load_dword v29, v[8:9], off offset:3072
	v_add_co_u32_e32 v6, vcc, s23, v4
	s_movk_i32 s23, 0x7000
	s_nop 0
	v_addc_co_u32_e32 v7, vcc, 0, v5, vcc
	v_add_co_u32_e32 v8, vcc, s46, v4
	s_nop 1
	v_addc_co_u32_e32 v9, vcc, 0, v5, vcc
	v_add_co_u32_e32 v4, vcc, s23, v4
	global_load_dword v30, v[8:9], off offset:-4096
	global_load_dword v31, v[6:7], off offset:1024
	global_load_dword v49, v[6:7], off offset:2048
	s_nop 0
	global_load_dword v6, v[6:7], off offset:3072
	s_nop 0
	global_load_dword v7, v[8:9], off
	global_load_dword v50, v[8:9], off offset:1024
	global_load_dword v51, v[8:9], off offset:2048
	s_nop 0
	global_load_dword v8, v[8:9], off offset:3072
	v_addc_co_u32_e32 v5, vcc, 0, v5, vcc
	global_load_dword v9, v[4:5], off
	global_load_dword v52, v[4:5], off offset:1024
	global_load_dword v53, v[4:5], off offset:2048
	s_nop 0
	global_load_dword v4, v[4:5], off offset:3072
	s_waitcnt vmcnt(30)
	ds_write2_b32 v41, v2, v10 offset1:66
	s_waitcnt vmcnt(28)
	ds_write2_b32 v41, v11, v12 offset0:132 offset1:198
	s_waitcnt vmcnt(26)
	ds_write2_b32 v42, v13, v14 offset0:8 offset1:74
	s_waitcnt vmcnt(24)
	ds_write2_b32 v42, v15, v16 offset0:140 offset1:206
	s_waitcnt vmcnt(22)
	ds_write2_b32 v43, v17, v18 offset0:16 offset1:82
	s_waitcnt vmcnt(20)
	ds_write2_b32 v43, v19, v20 offset0:148 offset1:214
	s_waitcnt vmcnt(18)
	ds_write2_b32 v44, v22, v23 offset0:24 offset1:90
	s_waitcnt vmcnt(16)
	ds_write2_b32 v44, v24, v25 offset0:156 offset1:222
	s_waitcnt vmcnt(14)
	ds_write2_b32 v45, v26, v27 offset0:32 offset1:98
	s_waitcnt vmcnt(12)
	ds_write2_b32 v45, v28, v29 offset0:164 offset1:230
	s_waitcnt vmcnt(10)
	ds_write2_b32 v46, v30, v31 offset0:40 offset1:106
	s_waitcnt vmcnt(8)
	ds_write2_b32 v46, v49, v6 offset0:172 offset1:238
	s_waitcnt vmcnt(6)
	ds_write2_b32 v47, v7, v50 offset0:48 offset1:114
	s_waitcnt vmcnt(4)
	ds_write2_b32 v47, v51, v8 offset0:180 offset1:246
	s_waitcnt vmcnt(2)
	ds_write2_b32 v48, v9, v52 offset0:56 offset1:122
	s_waitcnt vmcnt(0)
	ds_write2_b32 v48, v53, v4 offset0:188 offset1:254
	s_waitcnt lgkmcnt(0)
	v_or_b32_e32 v2, s22, v0
	v_add_u32_e32 v4, s16, v32
	v_cmp_gt_i32_e32 vcc, s47, v4
	v_lshlrev_b32_e32 v2, 1, v2
	s_and_saveexec_b64 s[22:23], vcc
	s_cbranch_execz .LBB0_1281
	v_add_u32_e32 v5, 0x8000, v33
	ds_read2_b32 v[6:7], v5 offset1:33
	ds_read2_b32 v[8:9], v5 offset0:66 offset1:99
	ds_read2_b32 v[10:11], v5 offset0:132 offset1:165
	ds_read2_b32 v[12:13], v5 offset0:198 offset1:231
	v_ashrrev_i32_e32 v5, 31, v4
	v_lshlrev_b64 v[4:5], 12, v[4:5]
	v_lshl_add_u64 v[4:5], s[0:1], 0, v[4:5]
	s_waitcnt lgkmcnt(3)
	v_cvt_pk_bf16_f32 v6, v6, v7
	s_waitcnt lgkmcnt(2)
	v_cvt_pk_bf16_f32 v7, v8, v9
	s_waitcnt lgkmcnt(1)
	v_cvt_pk_bf16_f32 v8, v10, v11
	s_waitcnt lgkmcnt(0)
	v_cvt_pk_bf16_f32 v9, v12, v13
	v_lshl_add_u64 v[4:5], v[4:5], 0, v[2:3]
	global_store_dwordx4 v[4:5], v[6:9], off nt
.LBB0_1281:
	s_or_b64 exec, exec, s[22:23]
	v_add_u32_e32 v4, s16, v34
	v_cmp_gt_i32_e32 vcc, s47, v4
	s_and_saveexec_b64 s[22:23], vcc
	s_cbranch_execz .LBB0_1283
	v_add_u32_e32 v5, 0x8000, v33
	ds_read2_b32 v[6:7], v5 offset0:8 offset1:41
	ds_read2_b32 v[8:9], v5 offset0:74 offset1:107
	ds_read2_b32 v[10:11], v5 offset0:140 offset1:173
	ds_read2_b32 v[12:13], v5 offset0:206 offset1:239
	v_ashrrev_i32_e32 v5, 31, v4
	v_lshlrev_b64 v[4:5], 12, v[4:5]
	v_lshl_add_u64 v[4:5], s[0:1], 0, v[4:5]
	s_waitcnt lgkmcnt(3)
	v_cvt_pk_bf16_f32 v6, v6, v7
	s_waitcnt lgkmcnt(2)
	v_cvt_pk_bf16_f32 v7, v8, v9
	s_waitcnt lgkmcnt(1)
	v_cvt_pk_bf16_f32 v8, v10, v11
	s_waitcnt lgkmcnt(0)
	v_cvt_pk_bf16_f32 v9, v12, v13
	v_lshl_add_u64 v[4:5], v[4:5], 0, v[2:3]
	global_store_dwordx4 v[4:5], v[6:9], off nt
.LBB0_1283:
	s_or_b64 exec, exec, s[22:23]
	v_add_u32_e32 v4, s16, v35
	v_cmp_gt_i32_e32 vcc, s47, v4
	s_and_saveexec_b64 s[22:23], vcc
	s_cbranch_execz .LBB0_1285
	v_add_u32_e32 v5, 0x8000, v33
	ds_read2_b32 v[6:7], v5 offset0:16 offset1:49
	ds_read2_b32 v[8:9], v5 offset0:82 offset1:115
	ds_read2_b32 v[10:11], v5 offset0:148 offset1:181
	ds_read2_b32 v[12:13], v5 offset0:214 offset1:247
	v_ashrrev_i32_e32 v5, 31, v4
	v_lshlrev_b64 v[4:5], 12, v[4:5]
	v_lshl_add_u64 v[4:5], s[0:1], 0, v[4:5]
	s_waitcnt lgkmcnt(3)
	v_cvt_pk_bf16_f32 v6, v6, v7
	s_waitcnt lgkmcnt(2)
	v_cvt_pk_bf16_f32 v7, v8, v9
	s_waitcnt lgkmcnt(1)
	v_cvt_pk_bf16_f32 v8, v10, v11
	s_waitcnt lgkmcnt(0)
	v_cvt_pk_bf16_f32 v9, v12, v13
	v_lshl_add_u64 v[4:5], v[4:5], 0, v[2:3]
	global_store_dwordx4 v[4:5], v[6:9], off nt
.LBB0_1285:
	s_or_b64 exec, exec, s[22:23]
	v_add_u32_e32 v4, s16, v36
	v_cmp_gt_i32_e32 vcc, s47, v4
	s_and_saveexec_b64 s[22:23], vcc
	s_cbranch_execz .LBB0_1287
	v_add_u32_e32 v5, 0x8000, v33
	ds_read2_b32 v[6:7], v5 offset0:24 offset1:57
	ds_read2_b32 v[8:9], v5 offset0:90 offset1:123
	ds_read2_b32 v[10:11], v5 offset0:156 offset1:189
	ds_read2_b32 v[12:13], v5 offset0:222 offset1:255
	v_ashrrev_i32_e32 v5, 31, v4
	v_lshlrev_b64 v[4:5], 12, v[4:5]
	v_lshl_add_u64 v[4:5], s[0:1], 0, v[4:5]
	s_waitcnt lgkmcnt(3)
	v_cvt_pk_bf16_f32 v6, v6, v7
	s_waitcnt lgkmcnt(2)
	v_cvt_pk_bf16_f32 v7, v8, v9
	s_waitcnt lgkmcnt(1)
	v_cvt_pk_bf16_f32 v8, v10, v11
	s_waitcnt lgkmcnt(0)
	v_cvt_pk_bf16_f32 v9, v12, v13
	v_lshl_add_u64 v[4:5], v[4:5], 0, v[2:3]
	global_store_dwordx4 v[4:5], v[6:9], off nt

.LBB0_1289:
	s_andn2_b64 vcc, exec, s[0:1]
	s_cbranch_vccnz .LBB0_1299
	s_load_dwordx2 s[0:1], s[2:3], 0x88
	s_add_i32 s22, s26, 0xcff0
	s_bfe_u32 s16, s22, 0xb0005
	s_lshl_b32 s22, s22, 5
	v_lshl_add_u32 v4, s16, 6, v21
	s_and_b32 s22, s22, 0x3e0
	v_ashrrev_i32_e32 v5, 31, v4
	v_or_b32_e32 v2, s22, v1
	v_lshlrev_b64 v[4:5], 12, v[4:5]
	s_waitcnt lgkmcnt(0)
	v_lshl_add_u64 v[4:5], s[0:1], 0, v[4:5]
	v_lshlrev_b32_e32 v2, 2, v2
	v_lshl_add_u64 v[4:5], v[4:5], 0, v[2:3]
	v_add_co_u32_e32 v6, vcc, 0x400000, v4
	s_nop 1
	v_addc_co_u32_e32 v7, vcc, 0, v5, vcc
	v_add_co_u32_e32 v8, vcc, 0x402000, v4
	s_nop 1
	v_addc_co_u32_e32 v9, vcc, 0, v5, vcc
	v_add_co_u32_e32 v10, vcc, 0x404000, v4
	s_nop 1
	v_addc_co_u32_e32 v11, vcc, 0, v5, vcc
	v_add_co_u32_e32 v12, vcc, 0x406000, v4
	s_nop 1
	v_addc_co_u32_e32 v13, vcc, 0, v5, vcc
	v_add_co_u32_e32 v14, vcc, 0x408000, v4
	s_nop 1
	v_addc_co_u32_e32 v15, vcc, 0, v5, vcc
	v_add_co_u32_e32 v16, vcc, 0x40a000, v4
	s_nop 1
	v_addc_co_u32_e32 v17, vcc, 0, v5, vcc
	v_add_co_u32_e32 v18, vcc, 0x40c000, v4
	s_nop 1
	v_addc_co_u32_e32 v19, vcc, 0, v5, vcc
	v_add_co_u32_e32 v22, vcc, 0x40e000, v4
	s_nop 1
	v_addc_co_u32_e32 v23, vcc, 0, v5, vcc
	global_load_dword v2, v[6:7], off
	global_load_dword v20, v[8:9], off
	global_load_dword v24, v[10:11], off
	global_load_dword v25, v[12:13], off
	global_load_dword v26, v[14:15], off
	global_load_dword v27, v[16:17], off
	global_load_dword v28, v[18:19], off
	global_load_dword v29, v[22:23], off
	v_add_co_u32_e32 v6, vcc, 0x410000, v4
	s_nop 1
	v_addc_co_u32_e32 v7, vcc, 0, v5, vcc
	v_add_co_u32_e32 v8, vcc, 0x412000, v4
	s_nop 1
	v_addc_co_u32_e32 v9, vcc, 0, v5, vcc
	v_add_co_u32_e32 v10, vcc, 0x414000, v4
	s_nop 1
	v_addc_co_u32_e32 v11, vcc, 0, v5, vcc
	v_add_co_u32_e32 v12, vcc, 0x416000, v4
	s_nop 1
	v_addc_co_u32_e32 v13, vcc, 0, v5, vcc
	v_add_co_u32_e32 v14, vcc, 0x418000, v4
	s_nop 1
	v_addc_co_u32_e32 v15, vcc, 0, v5, vcc
	v_add_co_u32_e32 v16, vcc, 0x41a000, v4
	s_nop 1
	v_addc_co_u32_e32 v17, vcc, 0, v5, vcc
	v_add_co_u32_e32 v18, vcc, 0x41c000, v4
	s_nop 1
	v_addc_co_u32_e32 v19, vcc, 0, v5, vcc
	v_add_co_u32_e32 v22, vcc, 0x41e000, v4
	s_nop 1
	v_addc_co_u32_e32 v23, vcc, 0, v5, vcc
	global_load_dword v30, v[6:7], off
	global_load_dword v31, v[8:9], off
	global_load_dword v49, v[10:11], off
	global_load_dword v50, v[12:13], off
	global_load_dword v51, v[14:15], off
	global_load_dword v52, v[16:17], off
	global_load_dword v53, v[18:19], off
	global_load_dword v54, v[22:23], off
	v_add_co_u32_e32 v6, vcc, 0x420000, v4
	s_nop 1
	v_addc_co_u32_e32 v7, vcc, 0, v5, vcc
	v_add_co_u32_e32 v8, vcc, 0x422000, v4
	s_nop 1
	v_addc_co_u32_e32 v9, vcc, 0, v5, vcc
	v_add_co_u32_e32 v10, vcc, 0x424000, v4
	s_nop 1
	v_addc_co_u32_e32 v11, vcc, 0, v5, vcc
	v_add_co_u32_e32 v12, vcc, 0x426000, v4
	s_nop 1
	v_addc_co_u32_e32 v13, vcc, 0, v5, vcc
	v_add_co_u32_e32 v14, vcc, 0x428000, v4
	s_nop 1
	v_addc_co_u32_e32 v15, vcc, 0, v5, vcc
	v_add_co_u32_e32 v16, vcc, 0x42a000, v4
	s_nop 1
	v_addc_co_u32_e32 v17, vcc, 0, v5, vcc
	v_add_co_u32_e32 v18, vcc, 0x42c000, v4
	s_nop 1
	v_addc_co_u32_e32 v19, vcc, 0, v5, vcc
	v_add_co_u32_e32 v22, vcc, 0x42e000, v4
	s_nop 1
	v_addc_co_u32_e32 v23, vcc, 0, v5, vcc
	global_load_dword v55, v[6:7], off
	global_load_dword v56, v[8:9], off
	global_load_dword v57, v[10:11], off
	global_load_dword v58, v[12:13], off
	global_load_dword v59, v[14:15], off
	global_load_dword v60, v[16:17], off
	global_load_dword v61, v[18:19], off
	s_nop 0
	global_load_dword v22, v[22:23], off
	v_add_co_u32_e32 v6, vcc, 0x430000, v4
	s_nop 1
	v_addc_co_u32_e32 v7, vcc, 0, v5, vcc
	v_add_co_u32_e32 v8, vcc, 0x432000, v4
	s_nop 1
	v_addc_co_u32_e32 v9, vcc, 0, v5, vcc
	v_add_co_u32_e32 v10, vcc, 0x434000, v4
	s_nop 1
	v_addc_co_u32_e32 v11, vcc, 0, v5, vcc
	v_add_co_u32_e32 v12, vcc, 0x436000, v4
	s_nop 1
	v_addc_co_u32_e32 v13, vcc, 0, v5, vcc
	v_add_co_u32_e32 v14, vcc, 0x438000, v4
	s_nop 1
	v_addc_co_u32_e32 v15, vcc, 0, v5, vcc
	v_add_co_u32_e32 v16, vcc, 0x43a000, v4
	s_nop 1
	v_addc_co_u32_e32 v17, vcc, 0, v5, vcc
	v_add_co_u32_e32 v18, vcc, 0x43c000, v4
	s_nop 1
	v_addc_co_u32_e32 v19, vcc, 0, v5, vcc
	v_add_co_u32_e32 v4, vcc, 0x43e000, v4
	s_nop 1
	v_addc_co_u32_e32 v5, vcc, 0, v5, vcc
	global_load_dword v6, v[6:7], off
	s_nop 0
	global_load_dword v7, v[8:9], off
	s_nop 0
	global_load_dword v8, v[10:11], off
	global_load_dword v9, v[12:13], off
	s_nop 0
	global_load_dword v10, v[14:15], off
	global_load_dword v11, v[16:17], off
	global_load_dword v12, v[18:19], off
	s_nop 0
	global_load_dword v4, v[4:5], off
	s_waitcnt vmcnt(30)
	ds_write2_b32 v41, v2, v20 offset1:66
	s_waitcnt vmcnt(28)
	ds_write2_b32 v41, v24, v25 offset0:132 offset1:198
	s_waitcnt vmcnt(26)
	ds_write2_b32 v42, v26, v27 offset0:8 offset1:74
	s_waitcnt vmcnt(24)
	ds_write2_b32 v42, v28, v29 offset0:140 offset1:206
	s_waitcnt vmcnt(22)
	ds_write2_b32 v43, v30, v31 offset0:16 offset1:82
	s_waitcnt vmcnt(20)
	ds_write2_b32 v43, v49, v50 offset0:148 offset1:214
	s_waitcnt vmcnt(18)
	ds_write2_b32 v44, v51, v52 offset0:24 offset1:90
	s_waitcnt vmcnt(16)
	ds_write2_b32 v44, v53, v54 offset0:156 offset1:222
	s_waitcnt vmcnt(14)
	ds_write2_b32 v45, v55, v56 offset0:32 offset1:98
	s_waitcnt vmcnt(12)
	ds_write2_b32 v45, v57, v58 offset0:164 offset1:230
	s_waitcnt vmcnt(10)
	ds_write2_b32 v46, v59, v60 offset0:40 offset1:106
	s_waitcnt vmcnt(8)
	ds_write2_b32 v46, v61, v22 offset0:172 offset1:238
	s_waitcnt vmcnt(6)
	ds_write2_b32 v47, v6, v7 offset0:48 offset1:114
	s_waitcnt vmcnt(4)
	ds_write2_b32 v47, v8, v9 offset0:180 offset1:246
	s_waitcnt vmcnt(2)
	ds_write2_b32 v48, v10, v11 offset0:56 offset1:122
	s_waitcnt vmcnt(0)
	ds_write2_b32 v48, v12, v4 offset0:188 offset1:254
	s_waitcnt lgkmcnt(0)
	v_add_u32_e32 v2, s22, v32
	v_cmp_gt_i32_e32 vcc, s48, v2
	s_and_saveexec_b64 s[0:1], vcc
	s_cbranch_execz .LBB0_1292
	v_add_u32_e32 v10, 0x8000, v33
	ds_read2_b32 v[4:5], v10 offset1:33
	ds_read2_b32 v[6:7], v10 offset0:66 offset1:99
	ds_read2_b32 v[8:9], v10 offset0:132 offset1:165
	ds_read2_b32 v[10:11], v10 offset0:198 offset1:231
	s_waitcnt lgkmcnt(3)
	v_cvt_pk_bf16_f32 v4, v4, v5
	s_waitcnt lgkmcnt(2)
	v_cvt_pk_bf16_f32 v5, v6, v7
	s_waitcnt lgkmcnt(1)
	v_cvt_pk_bf16_f32 v6, v8, v9
	v_ashrrev_i32_e32 v8, 4, v2
	v_and_b32_e32 v8, -16, v8
	v_add_u32_e32 v8, s16, v8
	v_ashrrev_i32_e32 v9, 31, v8
	v_lshlrev_b64 v[8:9], 15, v[8:9]
	v_lshlrev_b32_e32 v2, 7, v2
	v_lshl_add_u64 v[8:9], s[6:7], 0, v[8:9]
	v_and_b32_e32 v2, 0x7f80, v2
	v_lshl_add_u64 v[8:9], v[8:9], 0, v[2:3]
	v_lshlrev_b32_e32 v2, 1, v0
	s_waitcnt lgkmcnt(0)
	v_cvt_pk_bf16_f32 v7, v10, v11
	v_lshl_add_u64 v[8:9], v[8:9], 0, v[2:3]
	global_store_dwordx4 v[8:9], v[4:7], off nt
.LBB0_1292:
	s_or_b64 exec, exec, s[0:1]
	v_add_u32_e32 v2, s22, v34
	v_cmp_gt_i32_e32 vcc, s48, v2
	s_and_saveexec_b64 s[0:1], vcc
	s_cbranch_execz .LBB0_1294
	v_add_u32_e32 v10, 0x8000, v33
	ds_read2_b32 v[4:5], v10 offset0:8 offset1:41
	ds_read2_b32 v[6:7], v10 offset0:74 offset1:107
	ds_read2_b32 v[8:9], v10 offset0:140 offset1:173
	ds_read2_b32 v[10:11], v10 offset0:206 offset1:239
	s_waitcnt lgkmcnt(3)
	v_cvt_pk_bf16_f32 v4, v4, v5
	s_waitcnt lgkmcnt(2)
	v_cvt_pk_bf16_f32 v5, v6, v7
	s_waitcnt lgkmcnt(1)
	v_cvt_pk_bf16_f32 v6, v8, v9
	v_ashrrev_i32_e32 v8, 4, v2
	v_and_b32_e32 v8, -16, v8
	v_add_u32_e32 v8, s16, v8
	v_ashrrev_i32_e32 v9, 31, v8
	v_lshlrev_b64 v[8:9], 15, v[8:9]
	v_lshlrev_b32_e32 v2, 7, v2
	v_lshl_add_u64 v[8:9], s[6:7], 0, v[8:9]
	v_and_b32_e32 v2, 0x7f80, v2
	v_lshl_add_u64 v[8:9], v[8:9], 0, v[2:3]
	v_lshlrev_b32_e32 v2, 1, v0
	s_waitcnt lgkmcnt(0)
	v_cvt_pk_bf16_f32 v7, v10, v11
	v_lshl_add_u64 v[8:9], v[8:9], 0, v[2:3]
	global_store_dwordx4 v[8:9], v[4:7], off nt
.LBB0_1294:
	s_or_b64 exec, exec, s[0:1]
	v_add_u32_e32 v2, s22, v35
	v_cmp_gt_i32_e32 vcc, s48, v2
	s_and_saveexec_b64 s[0:1], vcc
	s_cbranch_execz .LBB0_1296
	v_add_u32_e32 v10, 0x8000, v33
	ds_read2_b32 v[4:5], v10 offset0:16 offset1:49
	ds_read2_b32 v[6:7], v10 offset0:82 offset1:115
	ds_read2_b32 v[8:9], v10 offset0:148 offset1:181
	ds_read2_b32 v[10:11], v10 offset0:214 offset1:247
	s_waitcnt lgkmcnt(3)
	v_cvt_pk_bf16_f32 v4, v4, v5
	s_waitcnt lgkmcnt(2)
	v_cvt_pk_bf16_f32 v5, v6, v7
	s_waitcnt lgkmcnt(1)
	v_cvt_pk_bf16_f32 v6, v8, v9
	v_ashrrev_i32_e32 v8, 4, v2
	v_and_b32_e32 v8, -16, v8
	v_add_u32_e32 v8, s16, v8
	v_ashrrev_i32_e32 v9, 31, v8
	v_lshlrev_b64 v[8:9], 15, v[8:9]
	v_lshlrev_b32_e32 v2, 7, v2
	v_lshl_add_u64 v[8:9], s[6:7], 0, v[8:9]
	v_and_b32_e32 v2, 0x7f80, v2
	v_lshl_add_u64 v[8:9], v[8:9], 0, v[2:3]
	v_lshlrev_b32_e32 v2, 1, v0
	s_waitcnt lgkmcnt(0)
	v_cvt_pk_bf16_f32 v7, v10, v11
	v_lshl_add_u64 v[8:9], v[8:9], 0, v[2:3]
	global_store_dwordx4 v[8:9], v[4:7], off nt
.LBB0_1296:
	s_or_b64 exec, exec, s[0:1]
	v_add_u32_e32 v2, s22, v36
	v_cmp_gt_i32_e32 vcc, s48, v2
	s_and_saveexec_b64 s[0:1], vcc
	s_cbranch_execz .LBB0_1298
	v_add_u32_e32 v10, 0x8000, v33
	ds_read2_b32 v[4:5], v10 offset0:24 offset1:57
	ds_read2_b32 v[6:7], v10 offset0:90 offset1:123
	ds_read2_b32 v[8:9], v10 offset0:156 offset1:189
	ds_read2_b32 v[10:11], v10 offset0:222 offset1:255
	s_waitcnt lgkmcnt(3)
	v_cvt_pk_bf16_f32 v4, v4, v5
	s_waitcnt lgkmcnt(2)
	v_cvt_pk_bf16_f32 v5, v6, v7
	s_waitcnt lgkmcnt(1)
	v_cvt_pk_bf16_f32 v6, v8, v9
	v_ashrrev_i32_e32 v8, 4, v2
	v_and_b32_e32 v8, -16, v8
	v_add_u32_e32 v8, s16, v8
	v_ashrrev_i32_e32 v9, 31, v8
	v_lshlrev_b64 v[8:9], 15, v[8:9]
	v_lshlrev_b32_e32 v2, 7, v2
	v_lshl_add_u64 v[8:9], s[6:7], 0, v[8:9]
	v_and_b32_e32 v2, 0x7f80, v2
	v_lshl_add_u64 v[8:9], v[8:9], 0, v[2:3]
	v_lshlrev_b32_e32 v2, 1, v0
	s_waitcnt lgkmcnt(0)
	v_cvt_pk_bf16_f32 v7, v10, v11
	v_lshl_add_u64 v[8:9], v[8:9], 0, v[2:3]
	global_store_dwordx4 v[8:9], v[4:7], off nt

.LBB0_1300:
	s_andn2_b64 vcc, exec, s[0:1]
	s_cbranch_vccnz .LBB0_1310
	s_load_dwordx2 s[0:1], s[2:3], 0x80
	s_add_i32 s22, s26, 0xd0f0
	s_bfe_u32 s16, s22, 0xb0005
	s_lshl_b32 s22, s22, 5
	v_lshl_add_u32 v4, s16, 6, v21
	s_and_b32 s22, s22, 0x3e0
	v_ashrrev_i32_e32 v5, 31, v4
	v_or_b32_e32 v2, s22, v1
	v_lshlrev_b64 v[4:5], 12, v[4:5]
	s_waitcnt lgkmcnt(0)
	v_lshl_add_u64 v[4:5], s[0:1], 0, v[4:5]
	v_lshlrev_b32_e32 v2, 2, v2
	v_lshl_add_u64 v[4:5], v[4:5], 0, v[2:3]
	v_add_co_u32_e32 v6, vcc, 0x200000, v4
	s_nop 1
	v_addc_co_u32_e32 v7, vcc, 0, v5, vcc
	v_add_co_u32_e32 v8, vcc, 0x202000, v4
	s_nop 1
	v_addc_co_u32_e32 v9, vcc, 0, v5, vcc
	v_add_co_u32_e32 v10, vcc, 0x204000, v4
	s_nop 1
	v_addc_co_u32_e32 v11, vcc, 0, v5, vcc
	v_add_co_u32_e32 v12, vcc, 0x206000, v4
	s_nop 1
	v_addc_co_u32_e32 v13, vcc, 0, v5, vcc
	v_add_co_u32_e32 v14, vcc, 0x208000, v4
	s_nop 1
	v_addc_co_u32_e32 v15, vcc, 0, v5, vcc
	v_add_co_u32_e32 v16, vcc, 0x20a000, v4
	s_nop 1
	v_addc_co_u32_e32 v17, vcc, 0, v5, vcc
	v_add_co_u32_e32 v18, vcc, 0x20c000, v4
	s_nop 1
	v_addc_co_u32_e32 v19, vcc, 0, v5, vcc
	v_add_co_u32_e32 v22, vcc, 0x20e000, v4
	s_nop 1
	v_addc_co_u32_e32 v23, vcc, 0, v5, vcc
	global_load_dword v2, v[6:7], off
	global_load_dword v20, v[8:9], off
	global_load_dword v24, v[10:11], off
	global_load_dword v25, v[12:13], off
	global_load_dword v26, v[14:15], off
	global_load_dword v27, v[16:17], off
	global_load_dword v28, v[18:19], off
	global_load_dword v29, v[22:23], off
	v_add_co_u32_e32 v6, vcc, 0x210000, v4
	s_nop 1
	v_addc_co_u32_e32 v7, vcc, 0, v5, vcc
	v_add_co_u32_e32 v8, vcc, 0x212000, v4
	s_nop 1
	v_addc_co_u32_e32 v9, vcc, 0, v5, vcc
	v_add_co_u32_e32 v10, vcc, 0x214000, v4
	s_nop 1
	v_addc_co_u32_e32 v11, vcc, 0, v5, vcc
	v_add_co_u32_e32 v12, vcc, 0x216000, v4
	s_nop 1
	v_addc_co_u32_e32 v13, vcc, 0, v5, vcc
	v_add_co_u32_e32 v14, vcc, 0x218000, v4
	s_nop 1
	v_addc_co_u32_e32 v15, vcc, 0, v5, vcc
	v_add_co_u32_e32 v16, vcc, 0x21a000, v4
	s_nop 1
	v_addc_co_u32_e32 v17, vcc, 0, v5, vcc
	v_add_co_u32_e32 v18, vcc, 0x21c000, v4
	s_nop 1
	v_addc_co_u32_e32 v19, vcc, 0, v5, vcc
	v_add_co_u32_e32 v22, vcc, 0x21e000, v4
	s_nop 1
	v_addc_co_u32_e32 v23, vcc, 0, v5, vcc
	global_load_dword v30, v[6:7], off
	global_load_dword v31, v[8:9], off
	global_load_dword v49, v[10:11], off
	global_load_dword v50, v[12:13], off
	global_load_dword v51, v[14:15], off
	global_load_dword v52, v[16:17], off
	global_load_dword v53, v[18:19], off
	global_load_dword v54, v[22:23], off
	v_add_co_u32_e32 v6, vcc, 0x220000, v4
	s_nop 1
	v_addc_co_u32_e32 v7, vcc, 0, v5, vcc
	v_add_co_u32_e32 v8, vcc, 0x222000, v4
	s_nop 1
	v_addc_co_u32_e32 v9, vcc, 0, v5, vcc
	v_add_co_u32_e32 v10, vcc, 0x224000, v4
	s_nop 1
	v_addc_co_u32_e32 v11, vcc, 0, v5, vcc
	v_add_co_u32_e32 v12, vcc, 0x226000, v4
	s_nop 1
	v_addc_co_u32_e32 v13, vcc, 0, v5, vcc
	v_add_co_u32_e32 v14, vcc, 0x228000, v4
	s_nop 1
	v_addc_co_u32_e32 v15, vcc, 0, v5, vcc
	v_add_co_u32_e32 v16, vcc, 0x22a000, v4
	s_nop 1
	v_addc_co_u32_e32 v17, vcc, 0, v5, vcc
	v_add_co_u32_e32 v18, vcc, 0x22c000, v4
	s_nop 1
	v_addc_co_u32_e32 v19, vcc, 0, v5, vcc
	v_add_co_u32_e32 v22, vcc, 0x22e000, v4
	s_nop 1
	v_addc_co_u32_e32 v23, vcc, 0, v5, vcc
	global_load_dword v55, v[6:7], off
	global_load_dword v56, v[8:9], off
	global_load_dword v57, v[10:11], off
	global_load_dword v58, v[12:13], off
	global_load_dword v59, v[14:15], off
	global_load_dword v60, v[16:17], off
	global_load_dword v61, v[18:19], off
	s_nop 0
	global_load_dword v22, v[22:23], off
	v_add_co_u32_e32 v6, vcc, 0x230000, v4
	s_nop 1
	v_addc_co_u32_e32 v7, vcc, 0, v5, vcc
	v_add_co_u32_e32 v8, vcc, 0x232000, v4
	s_nop 1
	v_addc_co_u32_e32 v9, vcc, 0, v5, vcc
	v_add_co_u32_e32 v10, vcc, 0x234000, v4
	s_nop 1
	v_addc_co_u32_e32 v11, vcc, 0, v5, vcc
	v_add_co_u32_e32 v12, vcc, 0x236000, v4
	s_nop 1
	v_addc_co_u32_e32 v13, vcc, 0, v5, vcc
	v_add_co_u32_e32 v14, vcc, 0x238000, v4
	s_nop 1
	v_addc_co_u32_e32 v15, vcc, 0, v5, vcc
	v_add_co_u32_e32 v16, vcc, 0x23a000, v4
	s_nop 1
	v_addc_co_u32_e32 v17, vcc, 0, v5, vcc
	v_add_co_u32_e32 v18, vcc, 0x23c000, v4
	s_nop 1
	v_addc_co_u32_e32 v19, vcc, 0, v5, vcc
	v_add_co_u32_e32 v4, vcc, 0x23e000, v4
	s_nop 1
	v_addc_co_u32_e32 v5, vcc, 0, v5, vcc
	global_load_dword v6, v[6:7], off
	s_nop 0
	global_load_dword v7, v[8:9], off
	s_nop 0
	global_load_dword v8, v[10:11], off
	global_load_dword v9, v[12:13], off
	s_nop 0
	global_load_dword v10, v[14:15], off
	global_load_dword v11, v[16:17], off
	global_load_dword v12, v[18:19], off
	s_nop 0
	global_load_dword v4, v[4:5], off
	s_waitcnt vmcnt(30)
	ds_write2_b32 v41, v2, v20 offset1:66
	s_waitcnt vmcnt(28)
	ds_write2_b32 v41, v24, v25 offset0:132 offset1:198
	s_waitcnt vmcnt(26)
	ds_write2_b32 v42, v26, v27 offset0:8 offset1:74
	s_waitcnt vmcnt(24)
	ds_write2_b32 v42, v28, v29 offset0:140 offset1:206
	s_waitcnt vmcnt(22)
	ds_write2_b32 v43, v30, v31 offset0:16 offset1:82
	s_waitcnt vmcnt(20)
	ds_write2_b32 v43, v49, v50 offset0:148 offset1:214
	s_waitcnt vmcnt(18)
	ds_write2_b32 v44, v51, v52 offset0:24 offset1:90
	s_waitcnt vmcnt(16)
	ds_write2_b32 v44, v53, v54 offset0:156 offset1:222
	s_waitcnt vmcnt(14)
	ds_write2_b32 v45, v55, v56 offset0:32 offset1:98
	s_waitcnt vmcnt(12)
	ds_write2_b32 v45, v57, v58 offset0:164 offset1:230
	s_waitcnt vmcnt(10)
	ds_write2_b32 v46, v59, v60 offset0:40 offset1:106
	s_waitcnt vmcnt(8)
	ds_write2_b32 v46, v61, v22 offset0:172 offset1:238
	s_waitcnt vmcnt(6)
	ds_write2_b32 v47, v6, v7 offset0:48 offset1:114
	s_waitcnt vmcnt(4)
	ds_write2_b32 v47, v8, v9 offset0:180 offset1:246
	s_waitcnt vmcnt(2)
	ds_write2_b32 v48, v10, v11 offset0:56 offset1:122
	s_waitcnt vmcnt(0)
	ds_write2_b32 v48, v12, v4 offset0:188 offset1:254
	s_waitcnt lgkmcnt(0)
	v_add_u32_e32 v2, s22, v32
	v_cmp_gt_i32_e32 vcc, s48, v2
	s_and_saveexec_b64 s[0:1], vcc
	s_cbranch_execz .LBB0_1303
	v_add_u32_e32 v10, 0x8000, v33
	ds_read2_b32 v[4:5], v10 offset1:33
	ds_read2_b32 v[6:7], v10 offset0:66 offset1:99
	ds_read2_b32 v[8:9], v10 offset0:132 offset1:165
	ds_read2_b32 v[10:11], v10 offset0:198 offset1:231
	s_waitcnt lgkmcnt(3)
	v_cvt_pk_bf16_f32 v4, v4, v5
	s_waitcnt lgkmcnt(2)
	v_cvt_pk_bf16_f32 v5, v6, v7
	s_waitcnt lgkmcnt(1)
	v_cvt_pk_bf16_f32 v6, v8, v9
	v_ashrrev_i32_e32 v8, 5, v2
	v_and_or_b32 v8, v8, -8, s16
	v_ashrrev_i32_e32 v9, 31, v8
	v_lshlrev_b64 v[8:9], 15, v[8:9]
	v_lshlrev_b32_e32 v2, 7, v2
	v_lshl_add_u64 v[8:9], s[8:9], 0, v[8:9]
	v_and_b32_e32 v2, 0x7f80, v2
	v_lshl_add_u64 v[8:9], v[8:9], 0, v[2:3]
	v_lshlrev_b32_e32 v2, 1, v0
	s_waitcnt lgkmcnt(0)
	v_cvt_pk_bf16_f32 v7, v10, v11
	v_lshl_add_u64 v[8:9], v[8:9], 0, v[2:3]
	global_store_dwordx4 v[8:9], v[4:7], off nt
.LBB0_1303:
	s_or_b64 exec, exec, s[0:1]
	v_add_u32_e32 v2, s22, v34
	v_cmp_gt_i32_e32 vcc, s48, v2
	s_and_saveexec_b64 s[0:1], vcc
	s_cbranch_execz .LBB0_1305
	v_add_u32_e32 v10, 0x8000, v33
	ds_read2_b32 v[4:5], v10 offset0:8 offset1:41
	ds_read2_b32 v[6:7], v10 offset0:74 offset1:107
	ds_read2_b32 v[8:9], v10 offset0:140 offset1:173
	ds_read2_b32 v[10:11], v10 offset0:206 offset1:239
	s_waitcnt lgkmcnt(3)
	v_cvt_pk_bf16_f32 v4, v4, v5
	s_waitcnt lgkmcnt(2)
	v_cvt_pk_bf16_f32 v5, v6, v7
	s_waitcnt lgkmcnt(1)
	v_cvt_pk_bf16_f32 v6, v8, v9
	v_ashrrev_i32_e32 v8, 5, v2
	v_and_or_b32 v8, v8, -8, s16
	v_ashrrev_i32_e32 v9, 31, v8
	v_lshlrev_b64 v[8:9], 15, v[8:9]
	v_lshlrev_b32_e32 v2, 7, v2
	v_lshl_add_u64 v[8:9], s[8:9], 0, v[8:9]
	v_and_b32_e32 v2, 0x7f80, v2
	v_lshl_add_u64 v[8:9], v[8:9], 0, v[2:3]
	v_lshlrev_b32_e32 v2, 1, v0
	s_waitcnt lgkmcnt(0)
	v_cvt_pk_bf16_f32 v7, v10, v11
	v_lshl_add_u64 v[8:9], v[8:9], 0, v[2:3]
	global_store_dwordx4 v[8:9], v[4:7], off nt
.LBB0_1305:
	s_or_b64 exec, exec, s[0:1]
	v_add_u32_e32 v2, s22, v35
	v_cmp_gt_i32_e32 vcc, s48, v2
	s_and_saveexec_b64 s[0:1], vcc
	s_cbranch_execz .LBB0_1307
	v_add_u32_e32 v10, 0x8000, v33
	ds_read2_b32 v[4:5], v10 offset0:16 offset1:49
	ds_read2_b32 v[6:7], v10 offset0:82 offset1:115
	ds_read2_b32 v[8:9], v10 offset0:148 offset1:181
	ds_read2_b32 v[10:11], v10 offset0:214 offset1:247
	s_waitcnt lgkmcnt(3)
	v_cvt_pk_bf16_f32 v4, v4, v5
	s_waitcnt lgkmcnt(2)
	v_cvt_pk_bf16_f32 v5, v6, v7
	s_waitcnt lgkmcnt(1)
	v_cvt_pk_bf16_f32 v6, v8, v9
	v_ashrrev_i32_e32 v8, 5, v2
	v_and_or_b32 v8, v8, -8, s16
	v_ashrrev_i32_e32 v9, 31, v8
	v_lshlrev_b64 v[8:9], 15, v[8:9]
	v_lshlrev_b32_e32 v2, 7, v2
	v_lshl_add_u64 v[8:9], s[8:9], 0, v[8:9]
	v_and_b32_e32 v2, 0x7f80, v2
	v_lshl_add_u64 v[8:9], v[8:9], 0, v[2:3]
	v_lshlrev_b32_e32 v2, 1, v0
	s_waitcnt lgkmcnt(0)
	v_cvt_pk_bf16_f32 v7, v10, v11
	v_lshl_add_u64 v[8:9], v[8:9], 0, v[2:3]
	global_store_dwordx4 v[8:9], v[4:7], off nt
.LBB0_1307:
	s_or_b64 exec, exec, s[0:1]
	v_add_u32_e32 v2, s22, v36
	v_cmp_gt_i32_e32 vcc, s48, v2
	s_and_saveexec_b64 s[0:1], vcc
	s_cbranch_execz .LBB0_1309
	v_add_u32_e32 v10, 0x8000, v33
	ds_read2_b32 v[4:5], v10 offset0:24 offset1:57
	ds_read2_b32 v[6:7], v10 offset0:90 offset1:123
	ds_read2_b32 v[8:9], v10 offset0:156 offset1:189
	ds_read2_b32 v[10:11], v10 offset0:222 offset1:255
	s_waitcnt lgkmcnt(3)
	v_cvt_pk_bf16_f32 v4, v4, v5
	s_waitcnt lgkmcnt(2)
	v_cvt_pk_bf16_f32 v5, v6, v7
	s_waitcnt lgkmcnt(1)
	v_cvt_pk_bf16_f32 v6, v8, v9
	v_ashrrev_i32_e32 v8, 5, v2
	v_and_or_b32 v8, v8, -8, s16
	v_ashrrev_i32_e32 v9, 31, v8
	v_lshlrev_b64 v[8:9], 15, v[8:9]
	v_lshlrev_b32_e32 v2, 7, v2
	v_lshl_add_u64 v[8:9], s[8:9], 0, v[8:9]
	v_and_b32_e32 v2, 0x7f80, v2
	v_lshl_add_u64 v[8:9], v[8:9], 0, v[2:3]
	v_lshlrev_b32_e32 v2, 1, v0
	s_waitcnt lgkmcnt(0)
	v_cvt_pk_bf16_f32 v7, v10, v11
	v_lshl_add_u64 v[8:9], v[8:9], 0, v[2:3]
	global_store_dwordx4 v[8:9], v[4:7], off nt

.LBB0_1311:
	s_andn2_b64 vcc, exec, s[0:1]
	s_cbranch_vccnz .LBB0_1321
	s_load_dwordx2 s[0:1], s[2:3], 0x78
	s_add_i32 s22, s26, 0xd1f0
	s_bfe_u32 s16, s22, 0xb0005
	s_lshl_b32 s22, s22, 5
	v_lshl_add_u32 v4, s16, 6, v21
	s_and_b32 s22, s22, 0x3e0
	v_ashrrev_i32_e32 v5, 31, v4
	v_or_b32_e32 v2, s22, v1
	v_lshlrev_b64 v[4:5], 12, v[4:5]
	s_waitcnt lgkmcnt(0)
	v_lshl_add_u64 v[4:5], s[0:1], 0, v[4:5]
	v_lshlrev_b32_e32 v2, 2, v2
	v_lshl_add_u64 v[4:5], v[4:5], 0, v[2:3]
	v_add_co_u32_e32 v6, vcc, 0x200000, v4
	s_nop 1
	v_addc_co_u32_e32 v7, vcc, 0, v5, vcc
	v_add_co_u32_e32 v8, vcc, 0x202000, v4
	s_nop 1
	v_addc_co_u32_e32 v9, vcc, 0, v5, vcc
	v_add_co_u32_e32 v10, vcc, 0x204000, v4
	s_nop 1
	v_addc_co_u32_e32 v11, vcc, 0, v5, vcc
	v_add_co_u32_e32 v12, vcc, 0x206000, v4
	s_nop 1
	v_addc_co_u32_e32 v13, vcc, 0, v5, vcc
	v_add_co_u32_e32 v14, vcc, 0x208000, v4
	s_nop 1
	v_addc_co_u32_e32 v15, vcc, 0, v5, vcc
	v_add_co_u32_e32 v16, vcc, 0x20a000, v4
	s_nop 1
	v_addc_co_u32_e32 v17, vcc, 0, v5, vcc
	v_add_co_u32_e32 v18, vcc, 0x20c000, v4
	s_nop 1
	v_addc_co_u32_e32 v19, vcc, 0, v5, vcc
	v_add_co_u32_e32 v22, vcc, 0x20e000, v4
	s_nop 1
	v_addc_co_u32_e32 v23, vcc, 0, v5, vcc
	global_load_dword v2, v[6:7], off
	global_load_dword v20, v[8:9], off
	global_load_dword v24, v[10:11], off
	global_load_dword v25, v[12:13], off
	global_load_dword v26, v[14:15], off
	global_load_dword v27, v[16:17], off
	global_load_dword v28, v[18:19], off
	global_load_dword v29, v[22:23], off
	v_add_co_u32_e32 v6, vcc, 0x210000, v4
	s_nop 1
	v_addc_co_u32_e32 v7, vcc, 0, v5, vcc
	v_add_co_u32_e32 v8, vcc, 0x212000, v4
	s_nop 1
	v_addc_co_u32_e32 v9, vcc, 0, v5, vcc
	v_add_co_u32_e32 v10, vcc, 0x214000, v4
	s_nop 1
	v_addc_co_u32_e32 v11, vcc, 0, v5, vcc
	v_add_co_u32_e32 v12, vcc, 0x216000, v4
	s_nop 1
	v_addc_co_u32_e32 v13, vcc, 0, v5, vcc
	v_add_co_u32_e32 v14, vcc, 0x218000, v4
	s_nop 1
	v_addc_co_u32_e32 v15, vcc, 0, v5, vcc
	v_add_co_u32_e32 v16, vcc, 0x21a000, v4
	s_nop 1
	v_addc_co_u32_e32 v17, vcc, 0, v5, vcc
	v_add_co_u32_e32 v18, vcc, 0x21c000, v4
	s_nop 1
	v_addc_co_u32_e32 v19, vcc, 0, v5, vcc
	v_add_co_u32_e32 v22, vcc, 0x21e000, v4
	s_nop 1
	v_addc_co_u32_e32 v23, vcc, 0, v5, vcc
	global_load_dword v30, v[6:7], off
	global_load_dword v31, v[8:9], off
	global_load_dword v49, v[10:11], off
	global_load_dword v50, v[12:13], off
	global_load_dword v51, v[14:15], off
	global_load_dword v52, v[16:17], off
	global_load_dword v53, v[18:19], off
	global_load_dword v54, v[22:23], off
	v_add_co_u32_e32 v6, vcc, 0x220000, v4
	s_nop 1
	v_addc_co_u32_e32 v7, vcc, 0, v5, vcc
	v_add_co_u32_e32 v8, vcc, 0x222000, v4
	s_nop 1
	v_addc_co_u32_e32 v9, vcc, 0, v5, vcc
	v_add_co_u32_e32 v10, vcc, 0x224000, v4
	s_nop 1
	v_addc_co_u32_e32 v11, vcc, 0, v5, vcc
	v_add_co_u32_e32 v12, vcc, 0x226000, v4
	s_nop 1
	v_addc_co_u32_e32 v13, vcc, 0, v5, vcc
	v_add_co_u32_e32 v14, vcc, 0x228000, v4
	s_nop 1
	v_addc_co_u32_e32 v15, vcc, 0, v5, vcc
	v_add_co_u32_e32 v16, vcc, 0x22a000, v4
	s_nop 1
	v_addc_co_u32_e32 v17, vcc, 0, v5, vcc
	v_add_co_u32_e32 v18, vcc, 0x22c000, v4
	s_nop 1
	v_addc_co_u32_e32 v19, vcc, 0, v5, vcc
	v_add_co_u32_e32 v22, vcc, 0x22e000, v4
	s_nop 1
	v_addc_co_u32_e32 v23, vcc, 0, v5, vcc
	global_load_dword v55, v[6:7], off
	global_load_dword v56, v[8:9], off
	global_load_dword v57, v[10:11], off
	global_load_dword v58, v[12:13], off
	global_load_dword v59, v[14:15], off
	global_load_dword v60, v[16:17], off
	global_load_dword v61, v[18:19], off
	s_nop 0
	global_load_dword v22, v[22:23], off
	v_add_co_u32_e32 v6, vcc, 0x230000, v4
	s_nop 1
	v_addc_co_u32_e32 v7, vcc, 0, v5, vcc
	v_add_co_u32_e32 v8, vcc, 0x232000, v4
	s_nop 1
	v_addc_co_u32_e32 v9, vcc, 0, v5, vcc
	v_add_co_u32_e32 v10, vcc, 0x234000, v4
	s_nop 1
	v_addc_co_u32_e32 v11, vcc, 0, v5, vcc
	v_add_co_u32_e32 v12, vcc, 0x236000, v4
	s_nop 1
	v_addc_co_u32_e32 v13, vcc, 0, v5, vcc
	v_add_co_u32_e32 v14, vcc, 0x238000, v4
	s_nop 1
	v_addc_co_u32_e32 v15, vcc, 0, v5, vcc
	v_add_co_u32_e32 v16, vcc, 0x23a000, v4
	s_nop 1
	v_addc_co_u32_e32 v17, vcc, 0, v5, vcc
	v_add_co_u32_e32 v18, vcc, 0x23c000, v4
	s_nop 1
	v_addc_co_u32_e32 v19, vcc, 0, v5, vcc
	v_add_co_u32_e32 v4, vcc, 0x23e000, v4
	s_nop 1
	v_addc_co_u32_e32 v5, vcc, 0, v5, vcc
	global_load_dword v6, v[6:7], off
	s_nop 0
	global_load_dword v7, v[8:9], off
	s_nop 0
	global_load_dword v8, v[10:11], off
	global_load_dword v9, v[12:13], off
	s_nop 0
	global_load_dword v10, v[14:15], off
	global_load_dword v11, v[16:17], off
	global_load_dword v12, v[18:19], off
	s_nop 0
	global_load_dword v4, v[4:5], off
	s_waitcnt vmcnt(30)
	ds_write2_b32 v41, v2, v20 offset1:66
	s_waitcnt vmcnt(28)
	ds_write2_b32 v41, v24, v25 offset0:132 offset1:198
	s_waitcnt vmcnt(26)
	ds_write2_b32 v42, v26, v27 offset0:8 offset1:74
	s_waitcnt vmcnt(24)
	ds_write2_b32 v42, v28, v29 offset0:140 offset1:206
	s_waitcnt vmcnt(22)
	ds_write2_b32 v43, v30, v31 offset0:16 offset1:82
	s_waitcnt vmcnt(20)
	ds_write2_b32 v43, v49, v50 offset0:148 offset1:214
	s_waitcnt vmcnt(18)
	ds_write2_b32 v44, v51, v52 offset0:24 offset1:90
	s_waitcnt vmcnt(16)
	ds_write2_b32 v44, v53, v54 offset0:156 offset1:222
	s_waitcnt vmcnt(14)
	ds_write2_b32 v45, v55, v56 offset0:32 offset1:98
	s_waitcnt vmcnt(12)
	ds_write2_b32 v45, v57, v58 offset0:164 offset1:230
	s_waitcnt vmcnt(10)
	ds_write2_b32 v46, v59, v60 offset0:40 offset1:106
	s_waitcnt vmcnt(8)
	ds_write2_b32 v46, v61, v22 offset0:172 offset1:238
	s_waitcnt vmcnt(6)
	ds_write2_b32 v47, v6, v7 offset0:48 offset1:114
	s_waitcnt vmcnt(4)
	ds_write2_b32 v47, v8, v9 offset0:180 offset1:246
	s_waitcnt vmcnt(2)
	ds_write2_b32 v48, v10, v11 offset0:56 offset1:122
	s_waitcnt vmcnt(0)
	ds_write2_b32 v48, v12, v4 offset0:188 offset1:254
	s_waitcnt lgkmcnt(0)
	v_add_u32_e32 v2, s22, v32
	v_cmp_gt_i32_e32 vcc, s48, v2
	s_and_saveexec_b64 s[0:1], vcc
	s_cbranch_execz .LBB0_1314
	v_add_u32_e32 v10, 0x8000, v33
	ds_read2_b32 v[4:5], v10 offset1:33
	ds_read2_b32 v[6:7], v10 offset0:66 offset1:99
	ds_read2_b32 v[8:9], v10 offset0:132 offset1:165
	ds_read2_b32 v[10:11], v10 offset0:198 offset1:231
	s_waitcnt lgkmcnt(3)
	v_cvt_pk_bf16_f32 v4, v4, v5
	s_waitcnt lgkmcnt(2)
	v_cvt_pk_bf16_f32 v5, v6, v7
	s_waitcnt lgkmcnt(1)
	v_cvt_pk_bf16_f32 v6, v8, v9
	v_ashrrev_i32_e32 v8, 5, v2
	v_and_or_b32 v8, v8, -8, s16
	v_ashrrev_i32_e32 v9, 31, v8
	v_lshlrev_b64 v[8:9], 15, v[8:9]
	v_lshlrev_b32_e32 v2, 7, v2
	v_lshl_add_u64 v[8:9], s[10:11], 0, v[8:9]
	v_and_b32_e32 v2, 0x7f80, v2
	v_lshl_add_u64 v[8:9], v[8:9], 0, v[2:3]
	v_lshlrev_b32_e32 v2, 1, v0
	s_waitcnt lgkmcnt(0)
	v_cvt_pk_bf16_f32 v7, v10, v11
	v_lshl_add_u64 v[8:9], v[8:9], 0, v[2:3]
	global_store_dwordx4 v[8:9], v[4:7], off nt
.LBB0_1314:
	s_or_b64 exec, exec, s[0:1]
	v_add_u32_e32 v2, s22, v34
	v_cmp_gt_i32_e32 vcc, s48, v2
	s_and_saveexec_b64 s[0:1], vcc
	s_cbranch_execz .LBB0_1316
	v_add_u32_e32 v10, 0x8000, v33
	ds_read2_b32 v[4:5], v10 offset0:8 offset1:41
	ds_read2_b32 v[6:7], v10 offset0:74 offset1:107
	ds_read2_b32 v[8:9], v10 offset0:140 offset1:173
	ds_read2_b32 v[10:11], v10 offset0:206 offset1:239
	s_waitcnt lgkmcnt(3)
	v_cvt_pk_bf16_f32 v4, v4, v5
	s_waitcnt lgkmcnt(2)
	v_cvt_pk_bf16_f32 v5, v6, v7
	s_waitcnt lgkmcnt(1)
	v_cvt_pk_bf16_f32 v6, v8, v9
	v_ashrrev_i32_e32 v8, 5, v2
	v_and_or_b32 v8, v8, -8, s16
	v_ashrrev_i32_e32 v9, 31, v8
	v_lshlrev_b64 v[8:9], 15, v[8:9]
	v_lshlrev_b32_e32 v2, 7, v2
	v_lshl_add_u64 v[8:9], s[10:11], 0, v[8:9]
	v_and_b32_e32 v2, 0x7f80, v2
	v_lshl_add_u64 v[8:9], v[8:9], 0, v[2:3]
	v_lshlrev_b32_e32 v2, 1, v0
	s_waitcnt lgkmcnt(0)
	v_cvt_pk_bf16_f32 v7, v10, v11
	v_lshl_add_u64 v[8:9], v[8:9], 0, v[2:3]
	global_store_dwordx4 v[8:9], v[4:7], off nt
.LBB0_1316:
	s_or_b64 exec, exec, s[0:1]
	v_add_u32_e32 v2, s22, v35
	v_cmp_gt_i32_e32 vcc, s48, v2
	s_and_saveexec_b64 s[0:1], vcc
	s_cbranch_execz .LBB0_1318
	v_add_u32_e32 v10, 0x8000, v33
	ds_read2_b32 v[4:5], v10 offset0:16 offset1:49
	ds_read2_b32 v[6:7], v10 offset0:82 offset1:115
	ds_read2_b32 v[8:9], v10 offset0:148 offset1:181
	ds_read2_b32 v[10:11], v10 offset0:214 offset1:247
	s_waitcnt lgkmcnt(3)
	v_cvt_pk_bf16_f32 v4, v4, v5
	s_waitcnt lgkmcnt(2)
	v_cvt_pk_bf16_f32 v5, v6, v7
	s_waitcnt lgkmcnt(1)
	v_cvt_pk_bf16_f32 v6, v8, v9
	v_ashrrev_i32_e32 v8, 5, v2
	v_and_or_b32 v8, v8, -8, s16
	v_ashrrev_i32_e32 v9, 31, v8
	v_lshlrev_b64 v[8:9], 15, v[8:9]
	v_lshlrev_b32_e32 v2, 7, v2
	v_lshl_add_u64 v[8:9], s[10:11], 0, v[8:9]
	v_and_b32_e32 v2, 0x7f80, v2
	v_lshl_add_u64 v[8:9], v[8:9], 0, v[2:3]
	v_lshlrev_b32_e32 v2, 1, v0
	s_waitcnt lgkmcnt(0)
	v_cvt_pk_bf16_f32 v7, v10, v11
	v_lshl_add_u64 v[8:9], v[8:9], 0, v[2:3]
	global_store_dwordx4 v[8:9], v[4:7], off nt
.LBB0_1318:
	s_or_b64 exec, exec, s[0:1]
	v_add_u32_e32 v2, s22, v36
	v_cmp_gt_i32_e32 vcc, s48, v2
	s_and_saveexec_b64 s[0:1], vcc
	s_cbranch_execz .LBB0_1320
	v_add_u32_e32 v10, 0x8000, v33
	ds_read2_b32 v[4:5], v10 offset0:24 offset1:57
	ds_read2_b32 v[6:7], v10 offset0:90 offset1:123
	ds_read2_b32 v[8:9], v10 offset0:156 offset1:189
	ds_read2_b32 v[10:11], v10 offset0:222 offset1:255
	s_waitcnt lgkmcnt(3)
	v_cvt_pk_bf16_f32 v4, v4, v5
	s_waitcnt lgkmcnt(2)
	v_cvt_pk_bf16_f32 v5, v6, v7
	s_waitcnt lgkmcnt(1)
	v_cvt_pk_bf16_f32 v6, v8, v9
	v_ashrrev_i32_e32 v8, 5, v2
	v_and_or_b32 v8, v8, -8, s16
	v_ashrrev_i32_e32 v9, 31, v8
	v_lshlrev_b64 v[8:9], 15, v[8:9]
	v_lshlrev_b32_e32 v2, 7, v2
	v_lshl_add_u64 v[8:9], s[10:11], 0, v[8:9]
	v_and_b32_e32 v2, 0x7f80, v2
	v_lshl_add_u64 v[8:9], v[8:9], 0, v[2:3]
	v_lshlrev_b32_e32 v2, 1, v0
	s_waitcnt lgkmcnt(0)
	v_cvt_pk_bf16_f32 v7, v10, v11
	v_lshl_add_u64 v[8:9], v[8:9], 0, v[2:3]
	global_store_dwordx4 v[8:9], v[4:7], off nt

.LBB0_1330:
	s_andn2_saveexec_b64 s[22:23], s[22:23]
	v_subrev_u32_e32 v2, 24, v12
	s_or_b64 exec, exec, s[22:23]
	s_waitcnt lgkmcnt(3)
	v_cvt_pk_bf16_f32 v4, v4, v5
	s_waitcnt lgkmcnt(2)
	v_cvt_pk_bf16_f32 v5, v6, v7
	s_waitcnt lgkmcnt(1)
	v_cvt_pk_bf16_f32 v6, v8, v9
	v_ashrrev_i32_e32 v8, 4, v2
	v_and_b32_e32 v8, -16, v8
	v_add_u32_e32 v8, s16, v8
	v_ashrrev_i32_e32 v9, 31, v8
	v_lshlrev_b64 v[8:9], 15, v[8:9]
	v_lshlrev_b32_e32 v2, 7, v2
	v_lshl_add_u64 v[8:9], s[12:13], 0, v[8:9]
	v_and_b32_e32 v2, 0x7f80, v2
	v_lshl_add_u64 v[8:9], v[8:9], 0, v[2:3]
	v_lshlrev_b32_e32 v2, 1, v0
	s_waitcnt lgkmcnt(0)
	v_cvt_pk_bf16_f32 v7, v10, v11
	v_lshl_add_u64 v[8:9], v[8:9], 0, v[2:3]
	global_store_dwordx4 v[8:9], v[4:7], off nt

.LBB0_1340:
	s_andn2_saveexec_b64 s[22:23], s[22:23]
	v_subrev_u32_e32 v2, 24, v13
	s_or_b64 exec, exec, s[22:23]
	s_waitcnt lgkmcnt(3)
	v_cvt_pk_bf16_f32 v4, v4, v5
	s_waitcnt lgkmcnt(2)
	v_cvt_pk_bf16_f32 v5, v6, v7
	s_waitcnt lgkmcnt(1)
	v_cvt_pk_bf16_f32 v6, v8, v9
	v_ashrrev_i32_e32 v8, 4, v2
	v_and_b32_e32 v8, -16, v8
	v_add_u32_e32 v8, s16, v8
	v_ashrrev_i32_e32 v9, 31, v8
	v_lshlrev_b64 v[8:9], 15, v[8:9]
	v_lshlrev_b32_e32 v2, 7, v2
	v_lshl_add_u64 v[8:9], s[12:13], 0, v[8:9]
	v_and_b32_e32 v2, 0x7f80, v2
	v_lshl_add_u64 v[8:9], v[8:9], 0, v[2:3]
	v_lshlrev_b32_e32 v2, 1, v0
	s_waitcnt lgkmcnt(0)
	v_cvt_pk_bf16_f32 v7, v10, v11
	v_lshl_add_u64 v[8:9], v[8:9], 0, v[2:3]
	global_store_dwordx4 v[8:9], v[4:7], off nt

.LBB0_1360:
	s_or_b64 exec, exec, s[22:23]
	v_ashrrev_i32_e32 v2, 4, v12
	v_and_b32_e32 v2, -16, v2
	s_waitcnt lgkmcnt(3)
	v_cvt_pk_bf16_f32 v4, v4, v5
	s_waitcnt lgkmcnt(2)
	v_cvt_pk_bf16_f32 v5, v6, v7
	s_waitcnt lgkmcnt(1)
	v_cvt_pk_bf16_f32 v6, v8, v9
	v_add_u32_e32 v8, s16, v2
	v_ashrrev_i32_e32 v9, 31, v8
	v_lshlrev_b64 v[8:9], 15, v[8:9]
	v_lshlrev_b32_e32 v2, 7, v12
	v_lshl_add_u64 v[8:9], s[12:13], 0, v[8:9]
	v_and_b32_e32 v2, 0x7f80, v2
	v_lshl_add_u64 v[8:9], v[8:9], 0, v[2:3]
	v_lshlrev_b32_e32 v2, 1, v0
	s_waitcnt lgkmcnt(0)
	v_cvt_pk_bf16_f32 v7, v10, v11
	v_lshl_add_u64 v[8:9], v[8:9], 0, v[2:3]
	global_store_dwordx4 v[8:9], v[4:7], off nt

.LBB0_1363:
	s_andn2_b64 vcc, exec, s[0:1]
	s_cbranch_vccnz .LBB0_1373
	s_add_i32 s16, s26, 0xffffe580
	s_cmpk_gt_u32 s16, 0x57f
	s_cselect_b64 s[0:1], -1, 0
	v_cndmask_b32_e64 v2, 0, 1, s[0:1]
	s_nop 0
	v_readfirstlane_b32 s0, v2
	s_or_b32 s24, s0, 2
	s_load_dwordx2 s[0:1], s[2:3], 0x30
	s_mul_i32 s22, s24, 0xb00000
	s_mul_i32 s24, s24, 0x580000
	s_waitcnt lgkmcnt(0)
	s_add_u32 s22, s0, s22
	s_addc_u32 s23, s1, 0
	s_add_u32 s0, s30, s24
	s_addc_u32 s1, s31, 0
	s_add_i32 s24, s26, 0xe000
	s_cmpk_lt_u32 s16, 0x580
	s_cselect_b32 s24, s16, s24
	s_bfe_u32 s16, s24, 0xb0005
	s_lshl_b32 s24, s24, 5
	v_lshl_add_u32 v4, s16, 6, v21
	s_and_b32 s24, s24, 0x3e0
	v_ashrrev_i32_e32 v5, 31, v4
	v_or_b32_e32 v2, s24, v1
	v_lshlrev_b64 v[4:5], 12, v[4:5]
	v_lshl_add_u64 v[4:5], s[22:23], 0, v[4:5]
	v_lshlrev_b32_e32 v2, 2, v2
	v_lshl_add_u64 v[4:5], v[4:5], 0, v[2:3]
	v_add_co_u32_e32 v6, vcc, s44, v4
	global_load_dword v2, v[4:5], off
	s_nop 0
	v_addc_co_u32_e32 v7, vcc, 0, v5, vcc
	global_load_dword v8, v[6:7], off
	v_add_co_u32_e32 v6, vcc, s45, v4
	s_mov_b32 s22, 0x8000
	s_nop 0
	v_addc_co_u32_e32 v7, vcc, 0, v5, vcc
	global_load_dword v9, v[6:7], off
	v_add_co_u32_e32 v6, vcc, s46, v4
	s_nop 1
	v_addc_co_u32_e32 v7, vcc, 0, v5, vcc
	global_load_dword v10, v[6:7], off
	v_add_co_u32_e32 v6, vcc, s22, v4
	s_mov_b32 s22, 0xa000
	s_nop 0
	v_addc_co_u32_e32 v7, vcc, 0, v5, vcc
	global_load_dword v11, v[6:7], off
	v_add_co_u32_e32 v6, vcc, s22, v4
	s_mov_b32 s22, 0xc000
	s_nop 0
	v_addc_co_u32_e32 v7, vcc, 0, v5, vcc
	global_load_dword v12, v[6:7], off
	v_add_co_u32_e32 v6, vcc, s22, v4
	s_mov_b32 s22, 0xe000
	s_nop 0
	v_addc_co_u32_e32 v7, vcc, 0, v5, vcc
	global_load_dword v13, v[6:7], off
	v_add_co_u32_e32 v6, vcc, s22, v4
	s_mov_b32 s22, 0x10000
	s_nop 0
	v_addc_co_u32_e32 v7, vcc, 0, v5, vcc
	global_load_dword v14, v[6:7], off
	v_add_co_u32_e32 v6, vcc, s22, v4
	s_mov_b32 s22, 0x12000
	s_nop 0
	v_addc_co_u32_e32 v7, vcc, 0, v5, vcc
	global_load_dword v15, v[6:7], off
	v_add_co_u32_e32 v6, vcc, s22, v4
	s_mov_b32 s22, 0x14000
	s_nop 0
	v_addc_co_u32_e32 v7, vcc, 0, v5, vcc
	global_load_dword v16, v[6:7], off
	v_add_co_u32_e32 v6, vcc, s22, v4
	s_mov_b32 s22, 0x18000
	s_nop 0
	v_addc_co_u32_e32 v7, vcc, 0, v5, vcc
	global_load_dword v17, v[6:7], off
	v_add_co_u32_e32 v6, vcc, s52, v4
	s_nop 1
	v_addc_co_u32_e32 v7, vcc, 0, v5, vcc
	global_load_dword v18, v[6:7], off
	v_add_co_u32_e32 v6, vcc, s22, v4
	s_mov_b32 s22, 0x1a000
	s_nop 0
	v_addc_co_u32_e32 v7, vcc, 0, v5, vcc
	global_load_dword v19, v[6:7], off
	v_add_co_u32_e32 v6, vcc, s22, v4
	s_mov_b32 s22, 0x1c000
	s_nop 0
	v_addc_co_u32_e32 v7, vcc, 0, v5, vcc
	global_load_dword v20, v[6:7], off
	v_add_co_u32_e32 v6, vcc, s22, v4
	s_mov_b32 s22, 0x1e000
	s_nop 0
	v_addc_co_u32_e32 v7, vcc, 0, v5, vcc
	global_load_dword v22, v[6:7], off
	v_add_co_u32_e32 v6, vcc, s22, v4
	s_mov_b32 s22, 0x20000
	s_nop 0
	v_addc_co_u32_e32 v7, vcc, 0, v5, vcc
	global_load_dword v23, v[6:7], off
	v_add_co_u32_e32 v6, vcc, s22, v4
	s_mov_b32 s22, 0x22000
	s_nop 0
	v_addc_co_u32_e32 v7, vcc, 0, v5, vcc
	global_load_dword v24, v[6:7], off
	v_add_co_u32_e32 v6, vcc, s22, v4
	s_mov_b32 s22, 0x24000
	s_nop 0
	v_addc_co_u32_e32 v7, vcc, 0, v5, vcc
	global_load_dword v25, v[6:7], off
	v_add_co_u32_e32 v6, vcc, s22, v4
	s_mov_b32 s22, 0x26000
	s_nop 0
	v_addc_co_u32_e32 v7, vcc, 0, v5, vcc
	global_load_dword v26, v[6:7], off
	v_add_co_u32_e32 v6, vcc, s22, v4
	s_mov_b32 s22, 0x28000
	s_nop 0
	v_addc_co_u32_e32 v7, vcc, 0, v5, vcc
	global_load_dword v27, v[6:7], off
	v_add_co_u32_e32 v6, vcc, s22, v4
	s_mov_b32 s22, 0x2a000
	s_nop 0
	v_addc_co_u32_e32 v7, vcc, 0, v5, vcc
	global_load_dword v28, v[6:7], off
	v_add_co_u32_e32 v6, vcc, s22, v4
	s_mov_b32 s22, 0x2e000
	s_nop 0
	v_addc_co_u32_e32 v7, vcc, 0, v5, vcc
	global_load_dword v29, v[6:7], off
	v_add_co_u32_e32 v6, vcc, s53, v4
	s_nop 1
	v_addc_co_u32_e32 v7, vcc, 0, v5, vcc
	global_load_dword v30, v[6:7], off
	v_add_co_u32_e32 v6, vcc, s22, v4
	s_mov_b32 s22, 0x30000
	s_nop 0
	v_addc_co_u32_e32 v7, vcc, 0, v5, vcc
	global_load_dword v31, v[6:7], off
	v_add_co_u32_e32 v6, vcc, s22, v4
	s_mov_b32 s22, 0x32000
	s_nop 0
	v_addc_co_u32_e32 v7, vcc, 0, v5, vcc
	global_load_dword v49, v[6:7], off
	v_add_co_u32_e32 v6, vcc, s22, v4
	s_mov_b32 s22, 0x34000
	s_nop 0
	v_addc_co_u32_e32 v7, vcc, 0, v5, vcc
	global_load_dword v50, v[6:7], off
	v_add_co_u32_e32 v6, vcc, s22, v4
	s_mov_b32 s22, 0x36000
	s_nop 0
	v_addc_co_u32_e32 v7, vcc, 0, v5, vcc
	global_load_dword v51, v[6:7], off
	v_add_co_u32_e32 v6, vcc, s22, v4
	s_mov_b32 s22, 0x38000
	s_nop 0
	v_addc_co_u32_e32 v7, vcc, 0, v5, vcc
	global_load_dword v52, v[6:7], off
	v_add_co_u32_e32 v6, vcc, s22, v4
	s_mov_b32 s22, 0x3a000
	s_nop 0
	v_addc_co_u32_e32 v7, vcc, 0, v5, vcc
	global_load_dword v53, v[6:7], off
	v_add_co_u32_e32 v6, vcc, s22, v4
	s_mov_b32 s22, 0x3c000
	s_nop 0
	v_addc_co_u32_e32 v7, vcc, 0, v5, vcc
	global_load_dword v54, v[6:7], off
	v_add_co_u32_e32 v6, vcc, s22, v4
	s_mov_b32 s22, 0x3e000
	s_nop 0
	v_addc_co_u32_e32 v7, vcc, 0, v5, vcc
	v_add_co_u32_e32 v4, vcc, s22, v4
	global_load_dword v6, v[6:7], off
	s_nop 0
	v_addc_co_u32_e32 v5, vcc, 0, v5, vcc
	global_load_dword v4, v[4:5], off
	s_waitcnt vmcnt(30)
	ds_write2_b32 v41, v2, v8 offset1:66
	s_waitcnt vmcnt(28)
	ds_write2_b32 v41, v9, v10 offset0:132 offset1:198
	s_waitcnt vmcnt(26)
	ds_write2_b32 v42, v11, v12 offset0:8 offset1:74
	s_waitcnt vmcnt(24)
	ds_write2_b32 v42, v13, v14 offset0:140 offset1:206
	s_waitcnt vmcnt(22)
	ds_write2_b32 v43, v15, v16 offset0:16 offset1:82
	s_waitcnt vmcnt(20)
	ds_write2_b32 v43, v17, v18 offset0:148 offset1:214
	s_waitcnt vmcnt(18)
	ds_write2_b32 v44, v19, v20 offset0:24 offset1:90
	s_waitcnt vmcnt(16)
	ds_write2_b32 v44, v22, v23 offset0:156 offset1:222
	s_waitcnt vmcnt(14)
	ds_write2_b32 v45, v24, v25 offset0:32 offset1:98
	s_waitcnt vmcnt(12)
	ds_write2_b32 v45, v26, v27 offset0:164 offset1:230
	s_waitcnt vmcnt(10)
	ds_write2_b32 v46, v28, v29 offset0:40 offset1:106
	s_waitcnt vmcnt(8)
	ds_write2_b32 v46, v30, v31 offset0:172 offset1:238
	s_waitcnt vmcnt(6)
	ds_write2_b32 v47, v49, v50 offset0:48 offset1:114
	s_waitcnt vmcnt(4)
	ds_write2_b32 v47, v51, v52 offset0:180 offset1:246
	s_waitcnt vmcnt(2)
	ds_write2_b32 v48, v53, v54 offset0:56 offset1:122
	s_waitcnt vmcnt(0)
	ds_write2_b32 v48, v6, v4 offset0:188 offset1:254
	s_waitcnt lgkmcnt(0)
	v_add_u32_e32 v2, s24, v32
	v_cmp_gt_i32_e32 vcc, s48, v2
	s_and_saveexec_b64 s[22:23], vcc
	s_cbranch_execz .LBB0_1366
	v_add_u32_e32 v10, 0x8000, v33
	ds_read2_b32 v[4:5], v10 offset1:33
	ds_read2_b32 v[6:7], v10 offset0:66 offset1:99
	ds_read2_b32 v[8:9], v10 offset0:132 offset1:165
	ds_read2_b32 v[10:11], v10 offset0:198 offset1:231
	s_waitcnt lgkmcnt(3)
	v_cvt_pk_bf16_f32 v4, v4, v5
	s_waitcnt lgkmcnt(2)
	v_cvt_pk_bf16_f32 v5, v6, v7
	s_waitcnt lgkmcnt(1)
	v_cvt_pk_bf16_f32 v6, v8, v9
	v_lshrrev_b32_e32 v8, 8, v2
	v_mad_i32_i24 v8, v8, 44, s16
	v_ashrrev_i32_e32 v9, 31, v8
	v_lshlrev_b64 v[8:9], 15, v[8:9]
	v_lshlrev_b32_e32 v2, 7, v2
	v_lshl_add_u64 v[8:9], s[0:1], 0, v[8:9]
	v_and_b32_e32 v2, 0x7f80, v2
	v_lshl_add_u64 v[8:9], v[8:9], 0, v[2:3]
	v_lshlrev_b32_e32 v2, 1, v0
	s_waitcnt lgkmcnt(0)
	v_cvt_pk_bf16_f32 v7, v10, v11
	v_lshl_add_u64 v[8:9], v[8:9], 0, v[2:3]
	global_store_dwordx4 v[8:9], v[4:7], off nt
.LBB0_1366:
	s_or_b64 exec, exec, s[22:23]
	v_add_u32_e32 v2, s24, v34
	v_cmp_gt_i32_e32 vcc, s48, v2
	s_and_saveexec_b64 s[22:23], vcc
	s_cbranch_execz .LBB0_1368
	v_add_u32_e32 v10, 0x8000, v33
	ds_read2_b32 v[4:5], v10 offset0:8 offset1:41
	ds_read2_b32 v[6:7], v10 offset0:74 offset1:107
	ds_read2_b32 v[8:9], v10 offset0:140 offset1:173
	ds_read2_b32 v[10:11], v10 offset0:206 offset1:239
	s_waitcnt lgkmcnt(3)
	v_cvt_pk_bf16_f32 v4, v4, v5
	s_waitcnt lgkmcnt(2)
	v_cvt_pk_bf16_f32 v5, v6, v7
	s_waitcnt lgkmcnt(1)
	v_cvt_pk_bf16_f32 v6, v8, v9
	v_lshrrev_b32_e32 v8, 8, v2
	v_mad_i32_i24 v8, v8, 44, s16
	v_ashrrev_i32_e32 v9, 31, v8
	v_lshlrev_b64 v[8:9], 15, v[8:9]
	v_lshlrev_b32_e32 v2, 7, v2
	v_lshl_add_u64 v[8:9], s[0:1], 0, v[8:9]
	v_and_b32_e32 v2, 0x7f80, v2
	v_lshl_add_u64 v[8:9], v[8:9], 0, v[2:3]
	v_lshlrev_b32_e32 v2, 1, v0
	s_waitcnt lgkmcnt(0)
	v_cvt_pk_bf16_f32 v7, v10, v11
	v_lshl_add_u64 v[8:9], v[8:9], 0, v[2:3]
	global_store_dwordx4 v[8:9], v[4:7], off nt
.LBB0_1368:
	s_or_b64 exec, exec, s[22:23]
	v_add_u32_e32 v2, s24, v35
	v_cmp_gt_i32_e32 vcc, s48, v2
	s_and_saveexec_b64 s[22:23], vcc
	s_cbranch_execz .LBB0_1370
	v_add_u32_e32 v10, 0x8000, v33
	ds_read2_b32 v[4:5], v10 offset0:16 offset1:49
	ds_read2_b32 v[6:7], v10 offset0:82 offset1:115
	ds_read2_b32 v[8:9], v10 offset0:148 offset1:181
	ds_read2_b32 v[10:11], v10 offset0:214 offset1:247
	s_waitcnt lgkmcnt(3)
	v_cvt_pk_bf16_f32 v4, v4, v5
	s_waitcnt lgkmcnt(2)
	v_cvt_pk_bf16_f32 v5, v6, v7
	s_waitcnt lgkmcnt(1)
	v_cvt_pk_bf16_f32 v6, v8, v9
	v_lshrrev_b32_e32 v8, 8, v2
	v_mad_i32_i24 v8, v8, 44, s16
	v_ashrrev_i32_e32 v9, 31, v8
	v_lshlrev_b64 v[8:9], 15, v[8:9]
	v_lshlrev_b32_e32 v2, 7, v2
	v_lshl_add_u64 v[8:9], s[0:1], 0, v[8:9]
	v_and_b32_e32 v2, 0x7f80, v2
	v_lshl_add_u64 v[8:9], v[8:9], 0, v[2:3]
	v_lshlrev_b32_e32 v2, 1, v0
	s_waitcnt lgkmcnt(0)
	v_cvt_pk_bf16_f32 v7, v10, v11
	v_lshl_add_u64 v[8:9], v[8:9], 0, v[2:3]
	global_store_dwordx4 v[8:9], v[4:7], off nt
.LBB0_1370:
	s_or_b64 exec, exec, s[22:23]
	v_add_u32_e32 v2, s24, v36
	v_cmp_gt_i32_e32 vcc, s48, v2
	s_and_saveexec_b64 s[22:23], vcc
	s_cbranch_execz .LBB0_1372
	v_add_u32_e32 v10, 0x8000, v33
	ds_read2_b32 v[4:5], v10 offset0:24 offset1:57
	ds_read2_b32 v[6:7], v10 offset0:90 offset1:123
	ds_read2_b32 v[8:9], v10 offset0:156 offset1:189
	ds_read2_b32 v[10:11], v10 offset0:222 offset1:255
	s_waitcnt lgkmcnt(3)
	v_cvt_pk_bf16_f32 v4, v4, v5
	s_waitcnt lgkmcnt(2)
	v_cvt_pk_bf16_f32 v5, v6, v7
	s_waitcnt lgkmcnt(1)
	v_cvt_pk_bf16_f32 v6, v8, v9
	v_lshrrev_b32_e32 v8, 8, v2
	v_mad_i32_i24 v8, v8, 44, s16
	v_ashrrev_i32_e32 v9, 31, v8
	v_lshlrev_b64 v[8:9], 15, v[8:9]
	v_lshlrev_b32_e32 v2, 7, v2
	v_lshl_add_u64 v[8:9], s[0:1], 0, v[8:9]
	v_and_b32_e32 v2, 0x7f80, v2
	v_lshl_add_u64 v[8:9], v[8:9], 0, v[2:3]
	v_lshlrev_b32_e32 v2, 1, v0
	s_waitcnt lgkmcnt(0)
	v_cvt_pk_bf16_f32 v7, v10, v11
	v_lshl_add_u64 v[8:9], v[8:9], 0, v[2:3]
	global_store_dwordx4 v[8:9], v[4:7], off nt

.LBB0_1374:
	s_andn2_b64 vcc, exec, s[0:1]
	s_cbranch_vccnz .LBB0_1400
	s_add_i32 s16, s26, 0xfffffb80
	s_cmpk_gt_u32 s16, 0xaff
	s_cselect_b64 s[0:1], -1, 0
	v_cndmask_b32_e64 v2, 0, 1, s[0:1]
	s_nop 0
	v_readfirstlane_b32 s0, v2
	s_or_b32 s24, s0, 2
	s_load_dwordx2 s[0:1], s[2:3], 0x28
	s_mul_i32 s22, s24, 0x1600000
	s_mul_i32 s24, s24, 0xb00000
	s_waitcnt lgkmcnt(0)
	s_add_u32 s22, s0, s22
	s_addc_u32 s23, s1, 0
	s_add_u32 s0, s28, s24
	s_addc_u32 s1, s29, 0
	s_add_i32 s24, s26, 0xf080
	s_cmpk_lt_u32 s16, 0xb00
	s_cselect_b32 s24, s16, s24
	s_and_b32 s16, s24, 0xffff
	s_mul_i32 s16, s16, 0xba2f
	s_lshr_b32 s16, s16, 23
	s_mul_i32 s25, s16, 0xb0
	s_sub_i32 s24, s24, s25
	s_lshl_b32 s24, s24, 5
	s_and_b32 s85, s24, 0xffe0
	v_or_b32_e32 v2, s85, v1
	v_lshl_add_u32 v6, s16, 6, v21
	v_mov_b64_e32 v[4:5], s[22:23]
	s_movk_i32 s22, 0x5800
	v_mad_i64_i32 v[4:5], s[22:23], v6, s22, v[4:5]
	v_lshlrev_b32_e32 v2, 2, v2
	v_lshl_add_u64 v[4:5], v[4:5], 0, v[2:3]
	s_mov_b32 s22, 0xb000
	v_add_co_u32_e32 v6, vcc, s22, v4
	global_load_dword v2, v[4:5], off
	s_nop 0
	v_addc_co_u32_e32 v7, vcc, 0, v5, vcc
	global_load_dword v8, v[6:7], off
	v_add_co_u32_e32 v6, vcc, s52, v4
	s_nop 1
	v_addc_co_u32_e32 v7, vcc, 0, v5, vcc
	global_load_dword v9, v[6:7], off
	v_add_co_u32_e32 v6, vcc, s55, v4
	s_nop 1
	v_addc_co_u32_e32 v7, vcc, 0, v5, vcc
	global_load_dword v10, v[6:7], off
	v_add_co_u32_e32 v6, vcc, s53, v4
	s_nop 1
	v_addc_co_u32_e32 v7, vcc, 0, v5, vcc
	global_load_dword v11, v[6:7], off
	v_add_co_u32_e32 v6, vcc, s56, v4
	s_nop 1
	v_addc_co_u32_e32 v7, vcc, 0, v5, vcc
	global_load_dword v12, v[6:7], off
	v_add_co_u32_e32 v6, vcc, s57, v4
	s_nop 1
	v_addc_co_u32_e32 v7, vcc, 0, v5, vcc
	global_load_dword v13, v[6:7], off
	v_add_co_u32_e32 v6, vcc, s58, v4
	s_nop 1
	v_addc_co_u32_e32 v7, vcc, 0, v5, vcc
	global_load_dword v14, v[6:7], off
	v_add_co_u32_e32 v6, vcc, s59, v4
	s_nop 1
	v_addc_co_u32_e32 v7, vcc, 0, v5, vcc
	global_load_dword v15, v[6:7], off
	v_add_co_u32_e32 v6, vcc, s60, v4
	s_nop 1
	v_addc_co_u32_e32 v7, vcc, 0, v5, vcc
	global_load_dword v16, v[6:7], off
	v_add_co_u32_e32 v6, vcc, s61, v4
	s_nop 1
	v_addc_co_u32_e32 v7, vcc, 0, v5, vcc
	global_load_dword v17, v[6:7], off
	v_add_co_u32_e32 v6, vcc, s62, v4
	s_nop 1
	v_addc_co_u32_e32 v7, vcc, 0, v5, vcc
	global_load_dword v18, v[6:7], off
	v_add_co_u32_e32 v6, vcc, s63, v4
	s_nop 1
	v_addc_co_u32_e32 v7, vcc, 0, v5, vcc
	global_load_dword v19, v[6:7], off
	v_add_co_u32_e32 v6, vcc, s64, v4
	s_nop 1
	v_addc_co_u32_e32 v7, vcc, 0, v5, vcc
	global_load_dword v20, v[6:7], off
	v_add_co_u32_e32 v6, vcc, s65, v4
	s_nop 1
	v_addc_co_u32_e32 v7, vcc, 0, v5, vcc
	global_load_dword v22, v[6:7], off
	v_add_co_u32_e32 v6, vcc, s66, v4
	s_nop 1
	v_addc_co_u32_e32 v7, vcc, 0, v5, vcc
	global_load_dword v23, v[6:7], off
	v_add_co_u32_e32 v6, vcc, s67, v4
	s_nop 1
	v_addc_co_u32_e32 v7, vcc, 0, v5, vcc
	global_load_dword v24, v[6:7], off
	v_add_co_u32_e32 v6, vcc, s68, v4
	s_nop 1
	v_addc_co_u32_e32 v7, vcc, 0, v5, vcc
	global_load_dword v25, v[6:7], off
	v_add_co_u32_e32 v6, vcc, s69, v4
	s_nop 1
	v_addc_co_u32_e32 v7, vcc, 0, v5, vcc
	global_load_dword v26, v[6:7], off
	v_add_co_u32_e32 v6, vcc, s70, v4
	s_nop 1
	v_addc_co_u32_e32 v7, vcc, 0, v5, vcc
	global_load_dword v27, v[6:7], off
	v_add_co_u32_e32 v6, vcc, s71, v4
	s_nop 1
	v_addc_co_u32_e32 v7, vcc, 0, v5, vcc
	global_load_dword v28, v[6:7], off
	v_add_co_u32_e32 v6, vcc, s72, v4
	s_nop 1
	v_addc_co_u32_e32 v7, vcc, 0, v5, vcc
	global_load_dword v29, v[6:7], off
	v_add_co_u32_e32 v6, vcc, s73, v4
	s_nop 1
	v_addc_co_u32_e32 v7, vcc, 0, v5, vcc
	global_load_dword v30, v[6:7], off
	v_add_co_u32_e32 v6, vcc, s74, v4
	s_nop 1
	v_addc_co_u32_e32 v7, vcc, 0, v5, vcc
	global_load_dword v31, v[6:7], off
	v_add_co_u32_e32 v6, vcc, s75, v4
	s_nop 1
	v_addc_co_u32_e32 v7, vcc, 0, v5, vcc
	global_load_dword v49, v[6:7], off
	v_add_co_u32_e32 v6, vcc, s76, v4
	s_nop 1
	v_addc_co_u32_e32 v7, vcc, 0, v5, vcc
	global_load_dword v50, v[6:7], off
	v_add_co_u32_e32 v6, vcc, s77, v4
	s_nop 1
	v_addc_co_u32_e32 v7, vcc, 0, v5, vcc
	global_load_dword v51, v[6:7], off
	v_add_co_u32_e32 v6, vcc, s78, v4
	s_nop 1
	v_addc_co_u32_e32 v7, vcc, 0, v5, vcc
	global_load_dword v52, v[6:7], off
	v_add_co_u32_e32 v6, vcc, s79, v4
	s_nop 1
	v_addc_co_u32_e32 v7, vcc, 0, v5, vcc
	global_load_dword v53, v[6:7], off
	v_add_co_u32_e32 v6, vcc, s80, v4
	s_nop 1
	v_addc_co_u32_e32 v7, vcc, 0, v5, vcc
	global_load_dword v54, v[6:7], off
	v_add_co_u32_e32 v6, vcc, s81, v4
	s_nop 1
	v_addc_co_u32_e32 v7, vcc, 0, v5, vcc
	v_add_co_u32_e32 v4, vcc, s82, v4
	global_load_dword v6, v[6:7], off
	s_nop 0
	v_addc_co_u32_e32 v5, vcc, 0, v5, vcc
	global_load_dword v4, v[4:5], off
	s_waitcnt vmcnt(30)
	ds_write2_b32 v41, v2, v8 offset1:66
	s_waitcnt vmcnt(28)
	ds_write2_b32 v41, v9, v10 offset0:132 offset1:198
	s_waitcnt vmcnt(26)
	ds_write2_b32 v42, v11, v12 offset0:8 offset1:74
	s_waitcnt vmcnt(24)
	ds_write2_b32 v42, v13, v14 offset0:140 offset1:206
	s_waitcnt vmcnt(22)
	ds_write2_b32 v43, v15, v16 offset0:16 offset1:82
	s_waitcnt vmcnt(20)
	ds_write2_b32 v43, v17, v18 offset0:148 offset1:214
	s_waitcnt vmcnt(18)
	ds_write2_b32 v44, v19, v20 offset0:24 offset1:90
	s_waitcnt vmcnt(16)
	ds_write2_b32 v44, v22, v23 offset0:156 offset1:222
	s_waitcnt vmcnt(14)
	ds_write2_b32 v45, v24, v25 offset0:32 offset1:98
	s_waitcnt vmcnt(12)
	ds_write2_b32 v45, v26, v27 offset0:164 offset1:230
	s_waitcnt vmcnt(10)
	ds_write2_b32 v46, v28, v29 offset0:40 offset1:106
	s_waitcnt vmcnt(8)
	ds_write2_b32 v46, v30, v31 offset0:172 offset1:238
	s_waitcnt vmcnt(6)
	ds_write2_b32 v47, v49, v50 offset0:48 offset1:114
	s_waitcnt vmcnt(4)
	ds_write2_b32 v47, v51, v52 offset0:180 offset1:246
	s_waitcnt vmcnt(2)
	ds_write2_b32 v48, v53, v54 offset0:56 offset1:122
	s_waitcnt vmcnt(0)
	ds_write2_b32 v48, v6, v4 offset0:188 offset1:254
	s_waitcnt lgkmcnt(0)
	v_add_u32_e32 v2, s85, v32
	v_cmp_gt_i32_e32 vcc, s83, v2
	v_add_u32_e32 v12, 0x8000, v33
	s_and_saveexec_b64 s[22:23], vcc
	s_cbranch_execz .LBB0_1381
	ds_read2_b32 v[4:5], v12 offset1:33
	ds_read2_b32 v[6:7], v12 offset0:66 offset1:99
	ds_read2_b32 v[8:9], v12 offset0:132 offset1:165
	ds_read2_b32 v[10:11], v12 offset0:198 offset1:231
	v_cmp_lt_i32_e32 vcc, s54, v2
	v_lshlrev_b32_e32 v13, 1, v2
	v_and_b32_e32 v14, 0x7f, v2
	s_and_saveexec_b64 s[24:25], vcc
	s_xor_b64 s[24:25], exec, s[24:25]
	v_add_u32_e32 v2, 0x7fffea00, v13
	v_and_b32_e32 v2, 0x7fffff00, v2
	v_or3_b32 v2, v14, v2, s47
	s_andn2_saveexec_b64 s[24:25], s[24:25]
	v_and_or_b32 v2, v13, s84, v14
	s_or_b64 exec, exec, s[24:25]
	s_waitcnt lgkmcnt(3)
	v_cvt_pk_bf16_f32 v4, v4, v5
	s_waitcnt lgkmcnt(2)
	v_cvt_pk_bf16_f32 v5, v6, v7
	s_waitcnt lgkmcnt(1)
	v_cvt_pk_bf16_f32 v6, v8, v9
	v_ashrrev_i32_e32 v8, 4, v2
	v_and_b32_e32 v8, -16, v8
	v_add_u32_e32 v8, s16, v8
	v_ashrrev_i32_e32 v9, 31, v8
	v_lshlrev_b64 v[8:9], 15, v[8:9]
	v_lshlrev_b32_e32 v2, 7, v2
	v_lshl_add_u64 v[8:9], s[0:1], 0, v[8:9]
	v_and_b32_e32 v2, 0x7f80, v2
	v_lshl_add_u64 v[8:9], v[8:9], 0, v[2:3]
	v_lshlrev_b32_e32 v2, 1, v0
	s_waitcnt lgkmcnt(0)
	v_cvt_pk_bf16_f32 v7, v10, v11
	v_lshl_add_u64 v[8:9], v[8:9], 0, v[2:3]
	global_store_dwordx4 v[8:9], v[4:7], off nt
.LBB0_1381:
	s_or_b64 exec, exec, s[22:23]
	v_add_u32_e32 v2, s85, v34
	v_cmp_gt_i32_e32 vcc, s83, v2
	s_and_saveexec_b64 s[22:23], vcc
	s_cbranch_execz .LBB0_1387
	ds_read2_b32 v[4:5], v12 offset0:8 offset1:41
	ds_read2_b32 v[6:7], v12 offset0:74 offset1:107
	ds_read2_b32 v[8:9], v12 offset0:140 offset1:173
	ds_read2_b32 v[10:11], v12 offset0:206 offset1:239
	v_cmp_lt_i32_e32 vcc, s54, v2
	v_lshlrev_b32_e32 v13, 1, v2
	v_and_b32_e32 v14, 0x7f, v2
	s_and_saveexec_b64 s[24:25], vcc
	s_xor_b64 s[24:25], exec, s[24:25]
	v_add_u32_e32 v2, 0x7fffea00, v13
	v_and_b32_e32 v2, 0x7fffff00, v2
	v_or3_b32 v2, v14, v2, s47
	s_andn2_saveexec_b64 s[24:25], s[24:25]
	v_and_or_b32 v2, v13, s84, v14
	s_or_b64 exec, exec, s[24:25]
	s_waitcnt lgkmcnt(3)
	v_cvt_pk_bf16_f32 v4, v4, v5
	s_waitcnt lgkmcnt(2)
	v_cvt_pk_bf16_f32 v5, v6, v7
	s_waitcnt lgkmcnt(1)
	v_cvt_pk_bf16_f32 v6, v8, v9
	v_ashrrev_i32_e32 v8, 4, v2
	v_and_b32_e32 v8, -16, v8
	v_add_u32_e32 v8, s16, v8
	v_ashrrev_i32_e32 v9, 31, v8
	v_lshlrev_b64 v[8:9], 15, v[8:9]
	v_lshlrev_b32_e32 v2, 7, v2
	v_lshl_add_u64 v[8:9], s[0:1], 0, v[8:9]
	v_and_b32_e32 v2, 0x7f80, v2
	v_lshl_add_u64 v[8:9], v[8:9], 0, v[2:3]
	v_lshlrev_b32_e32 v2, 1, v0
	s_waitcnt lgkmcnt(0)
	v_cvt_pk_bf16_f32 v7, v10, v11
	v_lshl_add_u64 v[8:9], v[8:9], 0, v[2:3]
	global_store_dwordx4 v[8:9], v[4:7], off nt
.LBB0_1387:
	s_or_b64 exec, exec, s[22:23]
	v_add_u32_e32 v2, s85, v35
	v_cmp_gt_i32_e32 vcc, s83, v2
	s_and_saveexec_b64 s[22:23], vcc
	s_cbranch_execz .LBB0_1393
	ds_read2_b32 v[4:5], v12 offset0:16 offset1:49
	ds_read2_b32 v[6:7], v12 offset0:82 offset1:115
	ds_read2_b32 v[8:9], v12 offset0:148 offset1:181
	ds_read2_b32 v[10:11], v12 offset0:214 offset1:247
	v_cmp_lt_i32_e32 vcc, s54, v2
	v_lshlrev_b32_e32 v13, 1, v2
	v_and_b32_e32 v14, 0x7f, v2
	s_and_saveexec_b64 s[24:25], vcc
	s_xor_b64 s[24:25], exec, s[24:25]
	v_add_u32_e32 v2, 0x7fffea00, v13
	v_and_b32_e32 v2, 0x7fffff00, v2
	v_or3_b32 v2, v14, v2, s47
	s_andn2_saveexec_b64 s[24:25], s[24:25]
	v_and_or_b32 v2, v13, s84, v14
	s_or_b64 exec, exec, s[24:25]
	s_waitcnt lgkmcnt(3)
	v_cvt_pk_bf16_f32 v4, v4, v5
	s_waitcnt lgkmcnt(2)
	v_cvt_pk_bf16_f32 v5, v6, v7
	s_waitcnt lgkmcnt(1)
	v_cvt_pk_bf16_f32 v6, v8, v9
	v_ashrrev_i32_e32 v8, 4, v2
	v_and_b32_e32 v8, -16, v8
	v_add_u32_e32 v8, s16, v8
	v_ashrrev_i32_e32 v9, 31, v8
	v_lshlrev_b64 v[8:9], 15, v[8:9]
	v_lshlrev_b32_e32 v2, 7, v2
	v_lshl_add_u64 v[8:9], s[0:1], 0, v[8:9]
	v_and_b32_e32 v2, 0x7f80, v2
	v_lshl_add_u64 v[8:9], v[8:9], 0, v[2:3]
	v_lshlrev_b32_e32 v2, 1, v0
	s_waitcnt lgkmcnt(0)
	v_cvt_pk_bf16_f32 v7, v10, v11
	v_lshl_add_u64 v[8:9], v[8:9], 0, v[2:3]
	global_store_dwordx4 v[8:9], v[4:7], off nt
.LBB0_1393:
	s_or_b64 exec, exec, s[22:23]
	v_add_u32_e32 v2, s85, v36
	v_cmp_gt_i32_e32 vcc, s83, v2
	s_and_saveexec_b64 s[22:23], vcc
	s_cbranch_execz .LBB0_1399
	ds_read2_b32 v[4:5], v12 offset0:24 offset1:57
	ds_read2_b32 v[6:7], v12 offset0:90 offset1:123
	ds_read2_b32 v[8:9], v12 offset0:156 offset1:189
	ds_read2_b32 v[10:11], v12 offset0:222 offset1:255
	v_cmp_lt_i32_e32 vcc, s54, v2
	v_lshlrev_b32_e32 v12, 1, v2
	v_and_b32_e32 v13, 0x7f, v2
	s_and_saveexec_b64 s[24:25], vcc
	s_xor_b64 s[24:25], exec, s[24:25]
	v_add_u32_e32 v2, 0x7fffea00, v12
	v_and_b32_e32 v2, 0x7fffff00, v2
	v_or3_b32 v2, v13, v2, s47
	s_andn2_saveexec_b64 s[24:25], s[24:25]
	v_and_or_b32 v2, v12, s84, v13
	s_or_b64 exec, exec, s[24:25]
	s_waitcnt lgkmcnt(3)
	v_cvt_pk_bf16_f32 v4, v4, v5
	s_waitcnt lgkmcnt(2)
	v_cvt_pk_bf16_f32 v5, v6, v7
	s_waitcnt lgkmcnt(1)
	v_cvt_pk_bf16_f32 v6, v8, v9
	v_ashrrev_i32_e32 v8, 4, v2
	v_and_b32_e32 v8, -16, v8
	v_add_u32_e32 v8, s16, v8
	v_ashrrev_i32_e32 v9, 31, v8
	v_lshlrev_b64 v[8:9], 15, v[8:9]
	v_lshlrev_b32_e32 v2, 7, v2
	v_lshl_add_u64 v[8:9], s[0:1], 0, v[8:9]
	v_and_b32_e32 v2, 0x7f80, v2
	v_lshl_add_u64 v[8:9], v[8:9], 0, v[2:3]
	v_lshlrev_b32_e32 v2, 1, v0
	s_waitcnt lgkmcnt(0)
	v_cvt_pk_bf16_f32 v7, v10, v11
	v_lshl_add_u64 v[8:9], v[8:9], 0, v[2:3]
	global_store_dwordx4 v[8:9], v[4:7], off nt

.LBB0_1403:
	v_lshl_add_u64 v[50:51], v[8:9], 0, s[0:1]
	v_add_co_u32_e32 v14, vcc, 0x2400000, v50
	v_mov_b32_e32 v49, s16
	s_nop 0
	v_addc_co_u32_e32 v15, vcc, 0, v51, vcc
	global_load_dword v24, v[14:15], off
	v_add_co_u32_e32 v14, vcc, 0x2409000, v50
	s_add_u32 s0, s0, 0x90000
	s_nop 0
	v_addc_co_u32_e32 v15, vcc, 0, v51, vcc
	global_load_dword v25, v[14:15], off
	v_add_co_u32_e32 v14, vcc, 0x2412000, v50
	s_addc_u32 s1, s1, 0
	s_nop 0
	v_addc_co_u32_e32 v15, vcc, 0, v51, vcc
	global_load_dword v26, v[14:15], off
	v_add_co_u32_e32 v14, vcc, 0x241b000, v50
	s_add_i32 s16, s16, 64
	s_nop 0
	v_addc_co_u32_e32 v15, vcc, 0, v51, vcc
	global_load_dword v27, v[14:15], off
	v_add_co_u32_e32 v14, vcc, 0x2424000, v50
	s_cmp_eq_u32 s0, 0x480000
	s_nop 0
	v_addc_co_u32_e32 v15, vcc, 0, v51, vcc
	global_load_dword v28, v[14:15], off
	v_add_co_u32_e32 v14, vcc, 0x242d000, v50
	s_waitcnt vmcnt(3)
	v_mov_b32_e32 v118, v25
	v_addc_co_u32_e32 v15, vcc, 0, v51, vcc
	global_load_dword v29, v[14:15], off
	v_add_co_u32_e32 v14, vcc, 0x2436000, v50
	v_mov_b32_e32 v144, v25
	s_nop 0
	v_addc_co_u32_e32 v15, vcc, 0, v51, vcc
	global_load_dword v30, v[14:15], off
	v_add_co_u32_e32 v14, vcc, 0x243f000, v50
	s_waitcnt vmcnt(1)
	v_mov_b32_e32 v119, v29
	v_addc_co_u32_e32 v15, vcc, 0, v51, vcc
	global_load_dword v31, v[14:15], off
	v_add_co_u32_e32 v14, vcc, 0x2448000, v50
	s_nop 1
	v_addc_co_u32_e32 v15, vcc, 0, v51, vcc
	global_load_dword v16, v[14:15], off
	v_add_co_u32_e32 v14, vcc, 0x2451000, v50
	s_nop 1
	v_addc_co_u32_e32 v15, vcc, 0, v51, vcc
	global_load_dword v17, v[14:15], off
	v_add_co_u32_e32 v14, vcc, 0x245a000, v50
	s_nop 1
	v_addc_co_u32_e32 v15, vcc, 0, v51, vcc
	v_add_co_u32_e32 v18, vcc, 0x2463000, v50
	global_load_dword v14, v[14:15], off
	s_nop 0
	v_addc_co_u32_e32 v19, vcc, 0, v51, vcc
	global_load_dword v15, v[18:19], off
	v_add_co_u32_e32 v18, vcc, 0x246c000, v50
	s_nop 1
	v_addc_co_u32_e32 v19, vcc, 0, v51, vcc
	global_load_dword v22, v[18:19], off
	v_add_co_u32_e32 v18, vcc, 0x2475000, v50
	s_nop 1
	v_addc_co_u32_e32 v19, vcc, 0, v51, vcc
	global_load_dword v20, v[18:19], off
	v_add_co_u32_e32 v18, vcc, 0x247e000, v50
	s_nop 1
	v_addc_co_u32_e32 v19, vcc, 0, v51, vcc
	v_add_co_u32_e32 v50, vcc, 0x2487000, v50
	global_load_dword v18, v[18:19], off
	s_nop 0
	v_addc_co_u32_e32 v51, vcc, 0, v51, vcc
	global_load_dword v2, v[50:51], off
	ds_read_b128 v[50:53], v49
	ds_read_b128 v[54:57], v49 offset:16
	ds_read_b128 v[58:61], v49 offset:32
	ds_read_b128 v[62:65], v49 offset:48
	ds_read_b128 v[66:69], v49 offset:4096
	ds_read_b128 v[70:73], v49 offset:8192
	ds_read_b128 v[74:77], v49 offset:12288
	ds_read_b128 v[78:81], v49 offset:16384
	ds_read_b128 v[82:85], v49 offset:20480
	ds_read_b128 v[86:89], v49 offset:24576
	s_waitcnt lgkmcnt(5)
	v_mov_b32_e32 v143, v66
	v_mov_b32_e32 v66, v51
	v_mov_b32_e32 v142, v50
	v_pk_mul_f32 v[50:51], v[144:145], v[66:67] op_sel_hi:[0,1]
	s_waitcnt lgkmcnt(0)
	v_mul_f32_e32 v90, v25, v87
	v_pk_fma_f32 v[86:87], v[24:25], v[86:87], v[90:91] op_sel_hi:[1,1,0]
	v_pk_fma_f32 v[50:51], v[24:25], v[142:143], v[50:51] op_sel_hi:[0,1,1]
	v_pk_fma_f32 v[86:87], v[26:27], v[88:89], v[86:87]
	v_mul_f32_e32 v88, v27, v89
	v_pk_add_f32 v[134:135], v[88:89], v[86:87] op_sel_hi:[0,1]
	ds_read_b128 v[86:89], v49 offset:28672
	ds_read_b128 v[90:93], v49 offset:4112
	ds_read_b128 v[94:97], v49 offset:8208
	ds_read_b128 v[98:101], v49 offset:12304
	ds_read_b128 v[102:105], v49 offset:16400
	ds_read_b128 v[106:109], v49 offset:20496
	ds_read_b128 v[110:113], v49 offset:24592
	s_waitcnt lgkmcnt(6)
	v_mov_b32_e32 v116, v86
	v_mov_b32_e32 v66, v52
	v_mov_b32_e32 v67, v68
	v_pk_fma_f32 v[50:51], v[26:27], v[66:67], v[50:51] op_sel_hi:[0,1,1]
	s_waitcnt lgkmcnt(0)
	v_mul_f32_e32 v114, v29, v111
	v_pk_fma_f32 v[110:111], v[28:29], v[110:111], v[114:115] op_sel_hi:[1,1,0]
	v_mov_b32_e32 v114, v24
	v_mov_b32_e32 v115, v28
	v_mov_b32_e32 v66, v27
	v_mov_b32_e32 v68, v53
	v_pk_fma_f32 v[50:51], v[66:67], v[68:69], v[50:51] op_sel_hi:[0,1,1]
	v_pk_add_f32 v[12:13], v[12:13], v[50:51]
	v_mov_b32_e32 v51, v90
	v_mov_b32_e32 v68, v29
	v_mov_b32_e32 v90, v55
	v_mov_b32_e32 v50, v54
	v_pk_mul_f32 v[52:53], v[68:69], v[90:91] op_sel_hi:[0,1]
	v_pk_fma_f32 v[50:51], v[28:29], v[50:51], v[52:53] op_sel_hi:[0,1,1]
	v_mov_b32_e32 v52, v56
	v_mov_b32_e32 v53, v92
	v_mov_b32_e32 v92, v57
	s_waitcnt vmcnt(8)
	v_pk_fma_f32 v[110:111], v[30:31], v[112:113], v[110:111]
	v_mul_f32_e32 v112, v31, v113
	v_pk_add_f32 v[136:137], v[112:113], v[110:111] op_sel_hi:[0,1]
	ds_read_b128 v[110:113], v49 offset:28688
	v_pk_fma_f32 v[50:51], v[30:31], v[52:53], v[50:51] op_sel_hi:[0,1,1]
	v_mov_b32_e32 v90, v31
	v_pk_fma_f32 v[50:51], v[90:91], v[92:93], v[50:51] op_sel_hi:[0,1,1]
	v_pk_add_f32 v[12:13], v[12:13], v[50:51]
	s_waitcnt lgkmcnt(0)
	v_mov_b32_e32 v117, v110
	v_mov_b32_e32 v110, v87
	v_pk_mul_f32 v[86:87], v[118:119], v[110:111]
	v_mov_b32_e32 v110, v26
	v_pk_fma_f32 v[86:87], v[114:115], v[116:117], v[86:87]
	v_mov_b32_e32 v111, v30
	v_mov_b32_e32 v114, v88
	v_mov_b32_e32 v115, v112
	v_pk_fma_f32 v[86:87], v[110:111], v[114:115], v[86:87]
	v_mov_b32_e32 v110, v27
	v_mov_b32_e32 v111, v31
	v_mov_b32_e32 v112, v89
	v_pk_fma_f32 v[138:139], v[110:111], v[112:113], v[86:87]
	ds_read_b128 v[86:89], v49 offset:4128
	ds_read_b128 v[110:113], v49 offset:8224
	ds_read_b128 v[114:117], v49 offset:12320
	ds_read_b128 v[118:121], v49 offset:16416
	ds_read_b128 v[122:125], v49 offset:20512
	ds_read_b128 v[126:129], v49 offset:24608
	v_mov_b32_e32 v50, v58
	s_waitcnt lgkmcnt(5)
	v_mov_b32_e32 v51, v86
	s_waitcnt vmcnt(6)
	v_mov_b32_e32 v58, v17
	v_mov_b32_e32 v86, v59
	s_waitcnt lgkmcnt(0)
	v_mul_f32_e32 v130, v17, v127
	v_pk_fma_f32 v[126:127], v[16:17], v[126:127], v[130:131] op_sel_hi:[1,1,0]
	v_pk_mul_f32 v[52:53], v[58:59], v[86:87] op_sel_hi:[0,1]
	s_waitcnt vmcnt(4)
	v_pk_fma_f32 v[126:127], v[14:15], v[128:129], v[126:127]
	v_mul_f32_e32 v128, v15, v129
	v_pk_add_f32 v[140:141], v[128:129], v[126:127] op_sel_hi:[0,1]
	ds_read_b128 v[126:129], v49 offset:28704
	ds_read_b128 v[130:133], v49 offset:4144
	v_pk_fma_f32 v[50:51], v[16:17], v[50:51], v[52:53] op_sel_hi:[0,1,1]
	v_mov_b32_e32 v52, v60
	v_mov_b32_e32 v53, v88
	v_pk_fma_f32 v[50:51], v[14:15], v[52:53], v[50:51] op_sel_hi:[0,1,1]
	v_mov_b32_e32 v60, v15
	v_mov_b32_e32 v88, v61
	v_pk_fma_f32 v[50:51], v[60:61], v[88:89], v[50:51] op_sel_hi:[0,1,1]
	v_pk_add_f32 v[12:13], v[12:13], v[50:51]
	s_waitcnt lgkmcnt(0)
	v_mov_b32_e32 v51, v130
	v_mov_b32_e32 v130, v63
	v_mov_b32_e32 v50, v62
	s_waitcnt vmcnt(2)
	v_pk_mul_f32 v[52:53], v[20:21], v[130:131] op_sel_hi:[0,1]
	v_mov_b32_e32 v63, v74
	v_mov_b32_e32 v74, v71
	v_pk_fma_f32 v[50:51], v[22:23], v[50:51], v[52:53] op_sel_hi:[0,1,1]
	v_mov_b32_e32 v52, v64
	v_mov_b32_e32 v53, v132
	v_mov_b32_e32 v132, v65
	v_mov_b32_e32 v62, v70
	v_pk_mul_f32 v[64:65], v[144:145], v[74:75] op_sel_hi:[0,1]
	v_pk_fma_f32 v[62:63], v[24:25], v[62:63], v[64:65] op_sel_hi:[0,1,1]
	v_mov_b32_e32 v64, v72
	v_mov_b32_e32 v65, v76
	v_pk_fma_f32 v[62:63], v[26:27], v[64:65], v[62:63] op_sel_hi:[0,1,1]
	v_mov_b32_e32 v76, v73
	v_pk_fma_f32 v[62:63], v[66:67], v[76:77], v[62:63] op_sel_hi:[0,1,1]
	v_pk_add_f32 v[10:11], v[10:11], v[62:63]
	v_mov_b32_e32 v63, v98
	v_mov_b32_e32 v98, v95
	v_mov_b32_e32 v62, v94
	v_pk_mul_f32 v[64:65], v[68:69], v[98:99] op_sel_hi:[0,1]
	v_pk_fma_f32 v[62:63], v[28:29], v[62:63], v[64:65] op_sel_hi:[0,1,1]
	v_mov_b32_e32 v64, v96
	v_mov_b32_e32 v65, v100
	s_waitcnt vmcnt(1)
	v_pk_fma_f32 v[50:51], v[18:19], v[52:53], v[50:51] op_sel_hi:[0,1,1]
	v_pk_fma_f32 v[62:63], v[30:31], v[64:65], v[62:63] op_sel_hi:[0,1,1]
	v_mov_b32_e32 v100, v97
	s_waitcnt vmcnt(0)
	v_pk_fma_f32 v[50:51], v[2:3], v[132:133], v[50:51] op_sel_hi:[0,1,1]
	v_pk_fma_f32 v[62:63], v[90:91], v[100:101], v[62:63] op_sel_hi:[0,1,1]
	v_pk_add_f32 v[12:13], v[12:13], v[50:51]
	ds_read_b128 v[50:53], v49 offset:8240
	ds_read_b128 v[54:57], v49 offset:12336
	v_pk_add_f32 v[10:11], v[10:11], v[62:63]
	v_mov_b32_e32 v63, v114
	v_mov_b32_e32 v114, v111
	v_mov_b32_e32 v62, v110
	v_pk_mul_f32 v[64:65], v[58:59], v[114:115] op_sel_hi:[0,1]
	v_pk_fma_f32 v[62:63], v[16:17], v[62:63], v[64:65] op_sel_hi:[0,1,1]
	v_mov_b32_e32 v64, v112
	v_mov_b32_e32 v65, v116
	v_pk_fma_f32 v[62:63], v[14:15], v[64:65], v[62:63] op_sel_hi:[0,1,1]
	v_mov_b32_e32 v116, v113
	v_pk_fma_f32 v[62:63], v[60:61], v[116:117], v[62:63] op_sel_hi:[0,1,1]
	v_pk_add_f32 v[10:11], v[10:11], v[62:63]
	s_waitcnt lgkmcnt(0)
	v_mov_b32_e32 v63, v54
	v_mov_b32_e32 v54, v51
	v_mov_b32_e32 v62, v50
	v_pk_mul_f32 v[50:51], v[20:21], v[54:55] op_sel_hi:[0,1]
	v_pk_fma_f32 v[50:51], v[22:23], v[62:63], v[50:51] op_sel_hi:[0,1,1]
	v_mov_b32_e32 v63, v82
	v_mov_b32_e32 v82, v79
	v_mov_b32_e32 v62, v78
	v_pk_mul_f32 v[64:65], v[144:145], v[82:83] op_sel_hi:[0,1]
	v_pk_fma_f32 v[24:25], v[24:25], v[62:63], v[64:65] op_sel_hi:[0,1,1]
	v_mov_b32_e32 v62, v80
	v_mov_b32_e32 v63, v84
	v_pk_fma_f32 v[24:25], v[26:27], v[62:63], v[24:25] op_sel_hi:[0,1,1]
	v_mov_b32_e32 v84, v81
	v_pk_fma_f32 v[24:25], v[66:67], v[84:85], v[24:25] op_sel_hi:[0,1,1]
	v_pk_add_f32 v[6:7], v[6:7], v[24:25]
	v_mov_b32_e32 v25, v106
	v_mov_b32_e32 v106, v103
	v_mov_b32_e32 v24, v102
	v_pk_mul_f32 v[26:27], v[68:69], v[106:107] op_sel_hi:[0,1]
	v_mov_b32_e32 v54, v52
	v_mov_b32_e32 v55, v56
	v_pk_fma_f32 v[24:25], v[28:29], v[24:25], v[26:27] op_sel_hi:[0,1,1]
	v_mov_b32_e32 v26, v104
	v_mov_b32_e32 v27, v108
	v_pk_fma_f32 v[50:51], v[18:19], v[54:55], v[50:51] op_sel_hi:[0,1,1]
	v_mov_b32_e32 v56, v53
	v_pk_fma_f32 v[24:25], v[30:31], v[26:27], v[24:25] op_sel_hi:[0,1,1]
	v_mov_b32_e32 v108, v105
	v_pk_fma_f32 v[50:51], v[2:3], v[56:57], v[50:51] op_sel_hi:[0,1,1]
	v_pk_fma_f32 v[24:25], v[90:91], v[108:109], v[24:25] op_sel_hi:[0,1,1]
	v_pk_add_f32 v[10:11], v[10:11], v[50:51]
	ds_read_b128 v[50:53], v49 offset:16432
	ds_read_b128 v[54:57], v49 offset:20528
	v_pk_add_f32 v[6:7], v[6:7], v[24:25]
	v_mov_b32_e32 v25, v122
	v_mov_b32_e32 v122, v119
	v_mov_b32_e32 v24, v118
	v_pk_mul_f32 v[26:27], v[58:59], v[122:123] op_sel_hi:[0,1]
	v_pk_fma_f32 v[24:25], v[16:17], v[24:25], v[26:27] op_sel_hi:[0,1,1]
	v_mov_b32_e32 v26, v120
	v_mov_b32_e32 v27, v124
	v_pk_fma_f32 v[24:25], v[14:15], v[26:27], v[24:25] op_sel_hi:[0,1,1]
	v_mov_b32_e32 v124, v121
	v_pk_fma_f32 v[24:25], v[60:61], v[124:125], v[24:25] op_sel_hi:[0,1,1]
	v_pk_add_f32 v[6:7], v[6:7], v[24:25]
	s_waitcnt lgkmcnt(0)
	v_mov_b32_e32 v25, v54
	v_mov_b32_e32 v54, v51
	v_mov_b32_e32 v24, v50
	v_pk_mul_f32 v[26:27], v[20:21], v[54:55] op_sel_hi:[0,1]
	v_pk_fma_f32 v[24:25], v[22:23], v[24:25], v[26:27] op_sel_hi:[0,1,1]
	v_mov_b32_e32 v26, v52
	v_mov_b32_e32 v27, v56
	v_pk_fma_f32 v[24:25], v[18:19], v[26:27], v[24:25] op_sel_hi:[0,1,1]
	v_mov_b32_e32 v56, v53
	v_pk_fma_f32 v[24:25], v[2:3], v[56:57], v[24:25] op_sel_hi:[0,1,1]
	v_pk_add_f32 v[6:7], v[6:7], v[24:25]
	ds_read_b128 v[24:27], v49 offset:24624
	v_mov_b32_e32 v23, v20
	v_mov_b32_e32 v19, v2
	v_mov_b32_e32 v30, v16
	v_mov_b32_e32 v16, v17
	s_waitcnt lgkmcnt(0)
	v_mul_f32_e32 v28, v20, v25
	v_pk_fma_f32 v[24:25], v[22:23], v[24:25], v[28:29] op_sel_hi:[1,1,0]
	v_mov_b32_e32 v17, v20
	v_pk_fma_f32 v[24:25], v[18:19], v[26:27], v[24:25]
	v_mul_f32_e32 v26, v2, v27
	v_pk_add_f32 v[28:29], v[26:27], v[24:25] op_sel_hi:[0,1]
	ds_read_b128 v[24:27], v49 offset:28720
	v_mov_b32_e32 v31, v22
	v_mov_b32_e32 v22, v126
	v_mov_b32_e32 v135, v138
	v_pk_add_f32 v[4:5], v[4:5], v[134:135]
	s_waitcnt lgkmcnt(0)
	v_mov_b32_e32 v23, v24
	v_mov_b32_e32 v24, v127
	v_pk_mul_f32 v[16:17], v[16:17], v[24:25]
	v_mov_b32_e32 v19, v26
	v_pk_fma_f32 v[16:17], v[30:31], v[22:23], v[16:17]
	v_mov_b32_e32 v22, v14
	v_mov_b32_e32 v23, v18
	v_mov_b32_e32 v18, v128
	v_pk_fma_f32 v[16:17], v[22:23], v[18:19], v[16:17]
	v_mov_b32_e32 v14, v15
	v_mov_b32_e32 v15, v2
	v_mov_b32_e32 v26, v129
	v_pk_fma_f32 v[14:15], v[14:15], v[26:27], v[16:17]
	v_mov_b32_e32 v137, v139
	v_pk_add_f32 v[4:5], v[4:5], v[136:137]
	v_mov_b32_e32 v141, v14
	v_pk_add_f32 v[4:5], v[4:5], v[140:141]
	v_mov_b32_e32 v29, v15
	v_pk_add_f32 v[4:5], v[4:5], v[28:29]
	s_cbranch_scc0 .LBB0_1403
	s_lshl_b32 s0, s26, 3
	s_andn2_b32 s0, s0, 63
	v_add_u32_e32 v8, s0, v166
	v_ashrrev_i32_e32 v9, 31, v8
	v_lshl_add_u64 v[8:9], v[8:9], 2, s[14:15]
	v_add_co_u32_e32 v14, vcc, 0x240000, v8
	s_nop 1
	v_addc_co_u32_e32 v15, vcc, 0, v9, vcc
	global_store_dword v[14:15], v12, off nt
	v_add_co_u32_e32 v14, vcc, 0x249000, v8
	s_nop 1
	v_addc_co_u32_e32 v15, vcc, 0, v9, vcc
	v_add_co_u32_e32 v12, vcc, 0x252000, v8
	global_store_dword v[14:15], v13, off nt
	s_nop 0
	v_addc_co_u32_e32 v13, vcc, 0, v9, vcc
	global_store_dword v[12:13], v10, off nt
	v_add_co_u32_e32 v12, vcc, 0x25b000, v8
	s_nop 1
	v_addc_co_u32_e32 v13, vcc, 0, v9, vcc
	v_add_co_u32_e32 v10, vcc, 0x264000, v8
	global_store_dword v[12:13], v11, off nt
	s_nop 0
	v_addc_co_u32_e32 v11, vcc, 0, v9, vcc
	global_store_dword v[10:11], v6, off nt
	v_add_co_u32_e32 v10, vcc, 0x26d000, v8
	s_nop 1
	v_addc_co_u32_e32 v11, vcc, 0, v9, vcc
	v_add_co_u32_e32 v6, vcc, 0x276000, v8
	global_store_dword v[10:11], v7, off nt
	s_nop 0
	v_addc_co_u32_e32 v7, vcc, 0, v9, vcc
	global_store_dword v[6:7], v4, off nt
	v_add_co_u32_e32 v6, vcc, 0x27f000, v8
	s_nop 1
	v_addc_co_u32_e32 v7, vcc, 0, v9, vcc
	global_store_dword v[6:7], v5, off nt
	s_branch .LBB0_1266

.LBB0_1566:
	v_mul_f32_e32 v162, 0xbfb8aa3b, v124
	v_exp_f32_e32 v168, v162
	v_mul_f32_e32 v162, 0xbfb8aa3b, v125
	v_exp_f32_e32 v169, v162
	v_mul_f32_e32 v170, 0xbfb8aa3b, v126
	v_mul_f32_e32 v171, 0xbfb8aa3b, v127
	v_exp_f32_e32 v170, v170
	v_exp_f32_e32 v171, v171
	v_add_f32_e32 v168, 1.0, v168
	v_add_f32_e32 v169, 1.0, v169
	v_rcp_f32_e32 v168, v168
	v_rcp_f32_e32 v169, v169
	v_add_f32_e32 v170, 1.0, v170
	v_add_f32_e32 v171, 1.0, v171
	v_rcp_f32_e32 v170, v170
	v_rcp_f32_e32 v171, v171
	v_pk_mul_f32 v[124:125], v[124:125], v[168:169]
	s_lshl_b32 s9, s18, 7
	v_pk_mul_f32 v[120:121], v[124:125], v[120:121]
	v_pk_mul_f32 v[124:125], v[126:127], v[170:171]
	v_cvt_pk_bf16_f32 v120, v120, v121
	v_mul_f32_e32 v121, 0xbfb8aa3b, v116
	v_pk_mul_f32 v[122:123], v[124:125], v[122:123]
	v_exp_f32_e32 v124, v121
	v_mul_f32_e32 v121, 0xbfb8aa3b, v117
	v_exp_f32_e32 v125, v121
	v_cvt_pk_bf16_f32 v121, v122, v123
	v_add_f32_e32 v122, 1.0, v124
	v_mul_f32_e32 v124, 0xbfb8aa3b, v118
	v_add_f32_e32 v123, 1.0, v125
	v_mul_f32_e32 v125, 0xbfb8aa3b, v119
	v_exp_f32_e32 v124, v124
	v_exp_f32_e32 v125, v125
	v_rcp_f32_e32 v122, v122
	v_rcp_f32_e32 v123, v123
	v_add_f32_e32 v124, 1.0, v124
	v_add_f32_e32 v125, 1.0, v125
	v_rcp_f32_e32 v124, v124
	v_rcp_f32_e32 v125, v125
	v_pk_mul_f32 v[116:117], v[116:117], v[122:123]
	s_or_b32 s9, s9, s39
	v_pk_mul_f32 v[112:113], v[116:117], v[112:113]
	s_mul_i32 s11, s16, 44
	s_ashr_i32 s9, s9, 6
	v_cvt_pk_bf16_f32 v122, v112, v113
	v_pk_mul_f32 v[112:113], v[118:119], v[124:125]
	s_add_i32 s20, s9, s11
	v_pk_mul_f32 v[112:113], v[112:113], v[114:115]
	v_mul_f32_e32 v114, 0xbfb8aa3b, v108
	v_mul_f32_e32 v115, 0xbfb8aa3b, v109
	s_ashr_i32 s21, s20, 31
	v_exp_f32_e32 v114, v114
	v_exp_f32_e32 v115, v115
	s_lshl_b64 s[20:21], s[20:21], 15
	s_cmp_eq_u32 s54, 2
	s_cselect_b32 s55, 0x4000, 0
	s_add_u32 s20, s20, s55
	s_addc_u32 s21, s21, 0
	v_lshl_add_u64 v[162:163], v[136:137], 0, s[20:21]
	v_cvt_pk_bf16_f32 v123, v112, v113
	v_lshl_add_u64 v[112:113], v[162:163], 0, v[138:139]
	global_store_dwordx4 v[112:113], v[120:123], off nt
	v_add_f32_e32 v112, 1.0, v114
	v_add_f32_e32 v113, 1.0, v115
	v_mul_f32_e32 v114, 0xbfb8aa3b, v110
	v_mul_f32_e32 v115, 0xbfb8aa3b, v111
	v_exp_f32_e32 v114, v114
	v_exp_f32_e32 v115, v115
	v_rcp_f32_e32 v112, v112
	v_rcp_f32_e32 v113, v113
	v_add_f32_e32 v114, 1.0, v114
	v_add_f32_e32 v115, 1.0, v115
	v_rcp_f32_e32 v114, v114
	v_rcp_f32_e32 v115, v115
	v_pk_mul_f32 v[108:109], v[108:109], v[112:113]
	s_andn2_b64 vcc, exec, s[0:1]
	v_pk_mul_f32 v[104:105], v[108:109], v[104:105]
	v_pk_mul_f32 v[108:109], v[110:111], v[114:115]
	v_cvt_pk_bf16_f32 v104, v104, v105
	v_mul_f32_e32 v105, 0xbfb8aa3b, v100
	v_pk_mul_f32 v[106:107], v[108:109], v[106:107]
	v_exp_f32_e32 v108, v105
	v_mul_f32_e32 v105, 0xbfb8aa3b, v101
	v_exp_f32_e32 v109, v105
	v_cvt_pk_bf16_f32 v105, v106, v107
	v_add_f32_e32 v106, 1.0, v108
	v_mul_f32_e32 v108, 0xbfb8aa3b, v102
	v_add_f32_e32 v107, 1.0, v109
	v_mul_f32_e32 v109, 0xbfb8aa3b, v103
	v_exp_f32_e32 v108, v108
	v_exp_f32_e32 v109, v109
	v_rcp_f32_e32 v106, v106
	v_rcp_f32_e32 v107, v107
	v_add_f32_e32 v108, 1.0, v108
	v_add_f32_e32 v109, 1.0, v109
	v_rcp_f32_e32 v108, v108
	v_rcp_f32_e32 v109, v109
	v_pk_mul_f32 v[100:101], v[100:101], v[106:107]
	s_mov_b64 s[0:1], -1
	v_pk_mul_f32 v[96:97], v[100:101], v[96:97]
	s_nop 0
	v_cvt_pk_bf16_f32 v106, v96, v97
	v_pk_mul_f32 v[96:97], v[102:103], v[108:109]
	s_nop 0
	v_pk_mul_f32 v[96:97], v[96:97], v[98:99]
	v_mul_f32_e32 v98, 0xbfb8aa3b, v92
	v_mul_f32_e32 v99, 0xbfb8aa3b, v93
	v_exp_f32_e32 v98, v98
	v_exp_f32_e32 v99, v99
	v_cvt_pk_bf16_f32 v107, v96, v97
	v_lshl_add_u64 v[96:97], v[162:163], 0, v[140:141]
	global_store_dwordx4 v[96:97], v[104:107], off nt
	v_add_f32_e32 v96, 1.0, v98
	v_add_f32_e32 v97, 1.0, v99
	v_mul_f32_e32 v98, 0xbfb8aa3b, v94
	v_mul_f32_e32 v99, 0xbfb8aa3b, v95
	v_exp_f32_e32 v98, v98
	v_exp_f32_e32 v99, v99
	v_rcp_f32_e32 v96, v96
	v_rcp_f32_e32 v97, v97
	v_add_f32_e32 v98, 1.0, v98
	v_add_f32_e32 v99, 1.0, v99
	v_rcp_f32_e32 v98, v98
	v_rcp_f32_e32 v99, v99
	v_pk_mul_f32 v[92:93], v[92:93], v[96:97]
	s_nop 0
	v_pk_mul_f32 v[88:89], v[92:93], v[88:89]
	v_pk_mul_f32 v[92:93], v[94:95], v[98:99]
	v_cvt_pk_bf16_f32 v88, v88, v89
	v_mul_f32_e32 v89, 0xbfb8aa3b, v84
	v_pk_mul_f32 v[90:91], v[92:93], v[90:91]
	v_exp_f32_e32 v92, v89
	v_mul_f32_e32 v89, 0xbfb8aa3b, v85
	v_exp_f32_e32 v93, v89
	v_cvt_pk_bf16_f32 v89, v90, v91
	v_add_f32_e32 v90, 1.0, v92
	v_mul_f32_e32 v92, 0xbfb8aa3b, v86
	v_add_f32_e32 v91, 1.0, v93
	v_mul_f32_e32 v93, 0xbfb8aa3b, v87
	v_exp_f32_e32 v92, v92
	v_exp_f32_e32 v93, v93
	v_rcp_f32_e32 v90, v90
	v_rcp_f32_e32 v91, v91
	v_add_f32_e32 v92, 1.0, v92
	v_add_f32_e32 v93, 1.0, v93
	v_rcp_f32_e32 v92, v92
	v_rcp_f32_e32 v93, v93
	v_pk_mul_f32 v[84:85], v[84:85], v[90:91]
	s_nop 0
	v_pk_mul_f32 v[80:81], v[84:85], v[80:81]
	s_nop 0
	v_cvt_pk_bf16_f32 v90, v80, v81
	v_pk_mul_f32 v[80:81], v[86:87], v[92:93]
	s_nop 0
	v_pk_mul_f32 v[80:81], v[80:81], v[82:83]
	v_mul_f32_e32 v82, 0xbfb8aa3b, v76
	v_mul_f32_e32 v83, 0xbfb8aa3b, v77
	v_exp_f32_e32 v82, v82
	v_exp_f32_e32 v83, v83
	v_cvt_pk_bf16_f32 v91, v80, v81
	v_lshl_add_u64 v[80:81], v[162:163], 0, v[142:143]
	global_store_dwordx4 v[80:81], v[88:91], off nt
	v_add_f32_e32 v80, 1.0, v82
	v_add_f32_e32 v81, 1.0, v83
	v_mul_f32_e32 v82, 0xbfb8aa3b, v78
	v_mul_f32_e32 v83, 0xbfb8aa3b, v79
	v_exp_f32_e32 v82, v82
	v_exp_f32_e32 v83, v83
	v_rcp_f32_e32 v80, v80
	v_rcp_f32_e32 v81, v81
	v_add_f32_e32 v82, 1.0, v82
	v_add_f32_e32 v83, 1.0, v83
	v_rcp_f32_e32 v82, v82
	v_rcp_f32_e32 v83, v83
	v_pk_mul_f32 v[76:77], v[76:77], v[80:81]
	s_nop 0
	v_pk_mul_f32 v[72:73], v[76:77], v[72:73]
	v_pk_mul_f32 v[76:77], v[78:79], v[82:83]
	v_cvt_pk_bf16_f32 v72, v72, v73
	v_mul_f32_e32 v73, 0xbfb8aa3b, v68
	v_pk_mul_f32 v[74:75], v[76:77], v[74:75]
	v_exp_f32_e32 v76, v73
	v_mul_f32_e32 v73, 0xbfb8aa3b, v69
	v_exp_f32_e32 v77, v73
	v_cvt_pk_bf16_f32 v73, v74, v75
	v_add_f32_e32 v74, 1.0, v76
	v_mul_f32_e32 v76, 0xbfb8aa3b, v70
	v_add_f32_e32 v75, 1.0, v77
	v_mul_f32_e32 v77, 0xbfb8aa3b, v71
	v_exp_f32_e32 v76, v76
	v_exp_f32_e32 v77, v77
	v_rcp_f32_e32 v74, v74
	v_rcp_f32_e32 v75, v75
	v_add_f32_e32 v76, 1.0, v76
	v_add_f32_e32 v77, 1.0, v77
	v_rcp_f32_e32 v76, v76
	v_rcp_f32_e32 v77, v77
	v_pk_mul_f32 v[68:69], v[68:69], v[74:75]
	s_nop 0
	v_pk_mul_f32 v[64:65], v[68:69], v[64:65]
	s_nop 0
	v_cvt_pk_bf16_f32 v74, v64, v65
	v_pk_mul_f32 v[64:65], v[70:71], v[76:77]
	s_nop 0
	v_pk_mul_f32 v[64:65], v[64:65], v[66:67]
	v_mul_f32_e32 v66, 0xbfb8aa3b, v60
	v_mul_f32_e32 v67, 0xbfb8aa3b, v61
	v_exp_f32_e32 v66, v66
	v_exp_f32_e32 v67, v67
	v_cvt_pk_bf16_f32 v75, v64, v65
	v_lshl_add_u64 v[64:65], v[162:163], 0, v[144:145]
	global_store_dwordx4 v[64:65], v[72:75], off nt
	s_cmp_lg_u32 s54, 0
	s_cbranch_scc1 .Lts0_epi_end
	v_add_f32_e32 v64, 1.0, v66
	v_add_f32_e32 v65, 1.0, v67
	v_mul_f32_e32 v66, 0xbfb8aa3b, v62
	v_mul_f32_e32 v67, 0xbfb8aa3b, v63
	v_exp_f32_e32 v66, v66
	v_exp_f32_e32 v67, v67
	v_rcp_f32_e32 v64, v64
	v_rcp_f32_e32 v65, v65
	v_add_f32_e32 v66, 1.0, v66
	v_add_f32_e32 v67, 1.0, v67
	v_rcp_f32_e32 v66, v66
	v_rcp_f32_e32 v67, v67
	v_pk_mul_f32 v[60:61], v[60:61], v[64:65]
	s_nop 0
	v_pk_mul_f32 v[56:57], v[60:61], v[56:57]
	v_pk_mul_f32 v[60:61], v[62:63], v[66:67]
	v_cvt_pk_bf16_f32 v56, v56, v57
	v_mul_f32_e32 v57, 0xbfb8aa3b, v52
	v_pk_mul_f32 v[58:59], v[60:61], v[58:59]
	v_exp_f32_e32 v60, v57
	v_mul_f32_e32 v57, 0xbfb8aa3b, v53
	v_exp_f32_e32 v61, v57
	v_cvt_pk_bf16_f32 v57, v58, v59
	v_add_f32_e32 v58, 1.0, v60
	v_mul_f32_e32 v60, 0xbfb8aa3b, v54
	v_add_f32_e32 v59, 1.0, v61
	v_mul_f32_e32 v61, 0xbfb8aa3b, v55
	v_exp_f32_e32 v60, v60
	v_exp_f32_e32 v61, v61
	v_rcp_f32_e32 v58, v58
	v_rcp_f32_e32 v59, v59
	v_add_f32_e32 v60, 1.0, v60
	v_add_f32_e32 v61, 1.0, v61
	v_rcp_f32_e32 v60, v60
	v_rcp_f32_e32 v61, v61
	v_pk_mul_f32 v[52:53], v[52:53], v[58:59]
	s_nop 0
	v_pk_mul_f32 v[48:49], v[52:53], v[48:49]
	s_nop 0
	v_cvt_pk_bf16_f32 v58, v48, v49
	v_pk_mul_f32 v[48:49], v[54:55], v[60:61]
	s_nop 0
	v_pk_mul_f32 v[48:49], v[48:49], v[50:51]
	v_mul_f32_e32 v50, 0xbfb8aa3b, v44
	v_mul_f32_e32 v51, 0xbfb8aa3b, v45
	v_exp_f32_e32 v50, v50
	v_exp_f32_e32 v51, v51
	v_cvt_pk_bf16_f32 v59, v48, v49
	v_lshl_add_u64 v[48:49], v[162:163], 0, v[146:147]
	global_store_dwordx4 v[48:49], v[56:59], off nt
	v_add_f32_e32 v48, 1.0, v50
	v_add_f32_e32 v49, 1.0, v51
	v_mul_f32_e32 v50, 0xbfb8aa3b, v46
	v_mul_f32_e32 v51, 0xbfb8aa3b, v47
	v_exp_f32_e32 v50, v50
	v_exp_f32_e32 v51, v51
	v_rcp_f32_e32 v48, v48
	v_rcp_f32_e32 v49, v49
	v_add_f32_e32 v50, 1.0, v50
	v_add_f32_e32 v51, 1.0, v51
	v_rcp_f32_e32 v50, v50
	v_rcp_f32_e32 v51, v51
	v_pk_mul_f32 v[44:45], v[44:45], v[48:49]
	s_nop 0
	v_pk_mul_f32 v[40:41], v[44:45], v[40:41]
	v_pk_mul_f32 v[44:45], v[46:47], v[50:51]
	v_cvt_pk_bf16_f32 v40, v40, v41
	v_mul_f32_e32 v41, 0xbfb8aa3b, v36
	v_pk_mul_f32 v[42:43], v[44:45], v[42:43]
	v_exp_f32_e32 v44, v41
	v_mul_f32_e32 v41, 0xbfb8aa3b, v37
	v_exp_f32_e32 v45, v41
	v_cvt_pk_bf16_f32 v41, v42, v43
	v_add_f32_e32 v42, 1.0, v44
	v_mul_f32_e32 v44, 0xbfb8aa3b, v38
	v_add_f32_e32 v43, 1.0, v45
	v_mul_f32_e32 v45, 0xbfb8aa3b, v39
	v_exp_f32_e32 v44, v44
	v_exp_f32_e32 v45, v45
	v_rcp_f32_e32 v42, v42
	v_rcp_f32_e32 v43, v43
	v_add_f32_e32 v44, 1.0, v44
	v_add_f32_e32 v45, 1.0, v45
	v_rcp_f32_e32 v44, v44
	v_rcp_f32_e32 v45, v45
	v_pk_mul_f32 v[36:37], v[36:37], v[42:43]
	s_nop 0
	v_pk_mul_f32 v[32:33], v[36:37], v[32:33]
	s_nop 0
	v_cvt_pk_bf16_f32 v42, v32, v33
	v_pk_mul_f32 v[32:33], v[38:39], v[44:45]
	s_nop 0
	v_pk_mul_f32 v[32:33], v[32:33], v[34:35]
	v_mul_f32_e32 v34, 0xbfb8aa3b, v28
	v_mul_f32_e32 v35, 0xbfb8aa3b, v29
	v_exp_f32_e32 v34, v34
	v_exp_f32_e32 v35, v35
	v_cvt_pk_bf16_f32 v43, v32, v33
	v_lshl_add_u64 v[32:33], v[162:163], 0, v[148:149]
	global_store_dwordx4 v[32:33], v[40:43], off nt
	v_add_f32_e32 v32, 1.0, v34
	v_add_f32_e32 v33, 1.0, v35
	v_mul_f32_e32 v34, 0xbfb8aa3b, v30
	v_mul_f32_e32 v35, 0xbfb8aa3b, v31
	v_exp_f32_e32 v34, v34
	v_exp_f32_e32 v35, v35
	v_rcp_f32_e32 v32, v32
	v_rcp_f32_e32 v33, v33
	v_add_f32_e32 v34, 1.0, v34
	v_add_f32_e32 v35, 1.0, v35
	v_rcp_f32_e32 v34, v34
	v_rcp_f32_e32 v35, v35
	v_pk_mul_f32 v[28:29], v[28:29], v[32:33]
	s_nop 0
	v_pk_mul_f32 v[24:25], v[28:29], v[24:25]
	v_pk_mul_f32 v[28:29], v[30:31], v[34:35]
	v_cvt_pk_bf16_f32 v24, v24, v25
	v_mul_f32_e32 v25, 0xbfb8aa3b, v20
	v_pk_mul_f32 v[26:27], v[28:29], v[26:27]
	v_exp_f32_e32 v28, v25
	v_mul_f32_e32 v25, 0xbfb8aa3b, v21
	v_exp_f32_e32 v29, v25
	v_cvt_pk_bf16_f32 v25, v26, v27
	v_add_f32_e32 v26, 1.0, v28
	v_mul_f32_e32 v28, 0xbfb8aa3b, v22
	v_add_f32_e32 v27, 1.0, v29
	v_mul_f32_e32 v29, 0xbfb8aa3b, v23
	v_exp_f32_e32 v28, v28
	v_exp_f32_e32 v29, v29
	v_rcp_f32_e32 v26, v26
	v_rcp_f32_e32 v27, v27
	v_add_f32_e32 v28, 1.0, v28
	v_add_f32_e32 v29, 1.0, v29
	v_rcp_f32_e32 v28, v28
	v_rcp_f32_e32 v29, v29
	v_pk_mul_f32 v[20:21], v[20:21], v[26:27]
	s_nop 0
	v_pk_mul_f32 v[16:17], v[20:21], v[16:17]
	s_nop 0
	v_cvt_pk_bf16_f32 v26, v16, v17
	v_pk_mul_f32 v[16:17], v[22:23], v[28:29]
	s_nop 0
	v_pk_mul_f32 v[16:17], v[16:17], v[18:19]
	v_mul_f32_e32 v18, 0xbfb8aa3b, v12
	v_mul_f32_e32 v19, 0xbfb8aa3b, v13
	v_exp_f32_e32 v18, v18
	v_exp_f32_e32 v19, v19
	v_cvt_pk_bf16_f32 v27, v16, v17
	v_lshl_add_u64 v[16:17], v[162:163], 0, v[150:151]
	global_store_dwordx4 v[16:17], v[24:27], off nt
	v_add_f32_e32 v16, 1.0, v18
	v_add_f32_e32 v17, 1.0, v19
	v_mul_f32_e32 v18, 0xbfb8aa3b, v14
	v_mul_f32_e32 v19, 0xbfb8aa3b, v15
	v_exp_f32_e32 v18, v18
	v_exp_f32_e32 v19, v19
	v_rcp_f32_e32 v16, v16
	v_rcp_f32_e32 v17, v17
	v_add_f32_e32 v18, 1.0, v18
	v_add_f32_e32 v19, 1.0, v19
	v_rcp_f32_e32 v18, v18
	v_rcp_f32_e32 v19, v19
	v_pk_mul_f32 v[12:13], v[12:13], v[16:17]
	s_nop 0
	v_pk_mul_f32 v[8:9], v[12:13], v[8:9]
	v_pk_mul_f32 v[12:13], v[14:15], v[18:19]
	v_cvt_pk_bf16_f32 v8, v8, v9
	v_mul_f32_e32 v9, 0xbfb8aa3b, v4
	v_pk_mul_f32 v[10:11], v[12:13], v[10:11]
	v_exp_f32_e32 v12, v9
	v_mul_f32_e32 v9, 0xbfb8aa3b, v5
	v_exp_f32_e32 v13, v9
	v_cvt_pk_bf16_f32 v9, v10, v11
	v_add_f32_e32 v10, 1.0, v12
	v_mul_f32_e32 v12, 0xbfb8aa3b, v6
	v_add_f32_e32 v11, 1.0, v13
	v_mul_f32_e32 v13, 0xbfb8aa3b, v7
	v_exp_f32_e32 v12, v12
	v_exp_f32_e32 v13, v13
	v_rcp_f32_e32 v10, v10
	v_rcp_f32_e32 v11, v11
	v_add_f32_e32 v12, 1.0, v12
	v_add_f32_e32 v13, 1.0, v13
	v_rcp_f32_e32 v12, v12
	v_rcp_f32_e32 v13, v13
	v_pk_mul_f32 v[4:5], v[4:5], v[10:11]
	s_nop 0
	v_pk_mul_f32 v[0:1], v[4:5], v[0:1]
	s_nop 0
	v_cvt_pk_bf16_f32 v10, v0, v1
	v_pk_mul_f32 v[0:1], v[6:7], v[12:13]
	s_nop 0
	v_pk_mul_f32 v[0:1], v[0:1], v[2:3]
	s_nop 0
	v_cvt_pk_bf16_f32 v11, v0, v1
	v_lshl_add_u64 v[0:1], v[162:163], 0, v[152:153]
	global_store_dwordx4 v[0:1], v[8:11], off nt
